# post-MFMA s_barrier of every 32-MFMA block moved up by 6 MFMAs (same order relative to all LDS ops and waits): partner wave starts its MFMAs while the tail drains
# baseline (speedup 1.0000x reference)
.LBB0_122:
	s_cmp_eq_u32 s89, 12
	s_cselect_b32 s42, s20, s65
	s_cselect_b32 s43, s16, s86
	s_cselect_b32 s45, s31, s88
	s_cselect_b32 s44, s59, s87
	s_add_u32 s38, s42, 0x80
	s_addc_u32 s39, s43, 0
	s_add_u32 s74, s44, 0x80
	s_addc_u32 s75, s45, 0
	s_add_i32 s35, 0, 0x10000
	s_mov_b64 s[18:19], s[68:69]
	v_add_u32_e32 v140, s35, v142
	s_add_i32 s49, 0, 0x14000
	ds_read_b128 v[136:139], v140
	ds_read_b128 v[144:147], v140 offset:1024
	ds_read_b128 v[148:151], v140 offset:2048
	ds_read_b128 v[152:155], v140 offset:3072
	v_add_u32_e32 v140, s49, v142
	ds_read_b128 v[156:159], v140
	ds_read_b128 v[160:163], v140 offset:1024
	ds_read_b128 v[164:167], v140 offset:2048
	ds_read_b128 v[168:171], v140 offset:3072
	s_add_u32 s18, s18, 0x40000
	s_addc_u32 s19, s19, 0
	v_lshl_add_u64 v[140:141], s[18:19], 0, v[130:131]
	s_add_i32 m0, s67, 0xc000
	ds_read_b128 v[172:175], v143
	ds_read_b128 v[176:179], v143 offset:1024
	ds_read_b128 v[180:183], v143 offset:2048
	ds_read_b128 v[184:187], v143 offset:3072
	ds_read_b128 v[188:191], v143 offset:4096
	ds_read_b128 v[192:195], v143 offset:5120
	ds_read_b128 v[196:199], v143 offset:6144
	ds_read_b128 v[200:203], v143 offset:7168
	global_load_lds_dwordx4 v[140:141], off
	v_lshl_add_u64 v[140:141], s[18:19], 0, v[132:133]
	s_add_i32 m0, s67, 0xe000
	s_nop 0
	global_load_lds_dwordx4 v[140:141], off
	s_waitcnt vmcnt(8)
	s_waitcnt lgkmcnt(0)
	s_barrier
	s_setprio 1
	s_waitcnt lgkmcnt(0)
	v_mfma_f32_16x16x32_bf16 v[126:129], v[136:139], v[172:175], v[126:129]
	v_mfma_f32_16x16x32_bf16 v[122:125], v[148:151], v[172:175], v[122:125]
	v_mfma_f32_16x16x32_bf16 v[110:113], v[136:139], v[180:183], v[110:113]
	v_mfma_f32_16x16x32_bf16 v[106:109], v[148:151], v[180:183], v[106:109]
	v_mfma_f32_16x16x32_bf16 v[92:95], v[136:139], v[188:191], v[92:95]
	v_mfma_f32_16x16x32_bf16 v[88:91], v[148:151], v[188:191], v[88:91]
	v_mfma_f32_16x16x32_bf16 v[76:79], v[136:139], v[196:199], v[76:79]
	v_mfma_f32_16x16x32_bf16 v[72:75], v[148:151], v[196:199], v[72:75]
	v_mfma_f32_16x16x32_bf16 v[126:129], v[144:147], v[176:179], v[126:129]
	v_mfma_f32_16x16x32_bf16 v[122:125], v[152:155], v[176:179], v[122:125]
	v_mfma_f32_16x16x32_bf16 v[110:113], v[144:147], v[184:187], v[110:113]
	v_mfma_f32_16x16x32_bf16 v[106:109], v[152:155], v[184:187], v[106:109]
	v_mfma_f32_16x16x32_bf16 v[92:95], v[144:147], v[192:195], v[92:95]
	v_mfma_f32_16x16x32_bf16 v[88:91], v[152:155], v[192:195], v[88:91]
	v_mfma_f32_16x16x32_bf16 v[76:79], v[144:147], v[200:203], v[76:79]
	v_mfma_f32_16x16x32_bf16 v[72:75], v[152:155], v[200:203], v[72:75]
	v_mfma_f32_16x16x32_bf16 v[118:121], v[156:159], v[172:175], v[118:121]
	v_mfma_f32_16x16x32_bf16 v[114:117], v[164:167], v[172:175], v[114:117]
	v_mfma_f32_16x16x32_bf16 v[102:105], v[156:159], v[180:183], v[102:105]
	v_mfma_f32_16x16x32_bf16 v[98:101], v[164:167], v[180:183], v[98:101]
	v_mfma_f32_16x16x32_bf16 v[84:87], v[156:159], v[188:191], v[84:87]
	v_mfma_f32_16x16x32_bf16 v[80:83], v[164:167], v[188:191], v[80:83]
	v_mfma_f32_16x16x32_bf16 v[68:71], v[156:159], v[196:199], v[68:71]
	v_mfma_f32_16x16x32_bf16 v[64:67], v[164:167], v[196:199], v[64:67]
	v_mfma_f32_16x16x32_bf16 v[118:121], v[160:163], v[176:179], v[118:121]
	v_mfma_f32_16x16x32_bf16 v[114:117], v[168:171], v[176:179], v[114:117]
	s_barrier
	v_mfma_f32_16x16x32_bf16 v[102:105], v[160:163], v[184:187], v[102:105]
	v_mfma_f32_16x16x32_bf16 v[98:101], v[168:171], v[184:187], v[98:101]
	v_mfma_f32_16x16x32_bf16 v[84:87], v[160:163], v[192:195], v[84:87]
	v_mfma_f32_16x16x32_bf16 v[80:83], v[168:171], v[192:195], v[80:83]
	v_mfma_f32_16x16x32_bf16 v[68:71], v[160:163], v[200:203], v[68:71]
	v_mfma_f32_16x16x32_bf16 v[64:67], v[168:171], v[200:203], v[64:67]
	s_setprio 0
	s_add_i32 s18, s35, s14
	v_lshl_add_u64 v[140:141], s[44:45], 0, v[96:97]
	s_mov_b32 m0, s18
	ds_read_b128 v[172:175], v143 offset:16384
	ds_read_b128 v[176:179], v143 offset:17408
	ds_read_b128 v[180:183], v143 offset:18432
	ds_read_b128 v[184:187], v143 offset:19456
	ds_read_b128 v[188:191], v143 offset:20480
	ds_read_b128 v[192:195], v143 offset:21504
	ds_read_b128 v[196:199], v143 offset:22528
	ds_read_b128 v[200:203], v143 offset:23552
	global_load_lds_dwordx4 v[140:141], off
	s_add_i32 m0, s18, 0x2000
	s_add_u32 s18, s44, 0x40000
	v_lshl_add_u64 v[140:141], s[44:45], 0, v[134:135]
	s_addc_u32 s19, s45, 0
	s_add_i32 s35, s49, s14
	global_load_lds_dwordx4 v[140:141], off
	v_lshl_add_u64 v[140:141], s[18:19], 0, v[96:97]
	s_mov_b32 m0, s35
	s_nop 0
	global_load_lds_dwordx4 v[140:141], off
	v_lshl_add_u64 v[140:141], s[18:19], 0, v[134:135]
	s_add_i32 m0, s35, 0x2000
	s_nop 0
	global_load_lds_dwordx4 v[140:141], off
	v_lshl_add_u64 v[140:141], s[42:43], 0, v[130:131]
	s_mov_b32 m0, s67
	s_nop 0
	global_load_lds_dwordx4 v[140:141], off
	v_lshl_add_u64 v[140:141], s[42:43], 0, v[132:133]
	s_mov_b32 m0, s73
	s_nop 0
	global_load_lds_dwordx4 v[140:141], off
	s_waitcnt vmcnt(8)
	s_waitcnt lgkmcnt(0)
	s_barrier
	s_setprio 1
	s_waitcnt lgkmcnt(0)
	v_mfma_f32_16x16x32_bf16 v[60:63], v[136:139], v[172:175], v[60:63]
	v_mfma_f32_16x16x32_bf16 v[56:59], v[148:151], v[172:175], v[56:59]
	v_mfma_f32_16x16x32_bf16 v[44:47], v[136:139], v[180:183], v[44:47]
	v_mfma_f32_16x16x32_bf16 v[40:43], v[148:151], v[180:183], v[40:43]
	v_mfma_f32_16x16x32_bf16 v[28:31], v[136:139], v[188:191], v[28:31]
	v_mfma_f32_16x16x32_bf16 v[24:27], v[148:151], v[188:191], v[24:27]
	v_mfma_f32_16x16x32_bf16 v[12:15], v[136:139], v[196:199], v[12:15]
	v_mfma_f32_16x16x32_bf16 v[8:11], v[148:151], v[196:199], v[8:11]
	v_mfma_f32_16x16x32_bf16 v[60:63], v[144:147], v[176:179], v[60:63]
	v_mfma_f32_16x16x32_bf16 v[56:59], v[152:155], v[176:179], v[56:59]
	v_mfma_f32_16x16x32_bf16 v[44:47], v[144:147], v[184:187], v[44:47]
	v_mfma_f32_16x16x32_bf16 v[40:43], v[152:155], v[184:187], v[40:43]
	v_mfma_f32_16x16x32_bf16 v[28:31], v[144:147], v[192:195], v[28:31]
	v_mfma_f32_16x16x32_bf16 v[24:27], v[152:155], v[192:195], v[24:27]
	v_mfma_f32_16x16x32_bf16 v[12:15], v[144:147], v[200:203], v[12:15]
	v_mfma_f32_16x16x32_bf16 v[8:11], v[152:155], v[200:203], v[8:11]
	v_mfma_f32_16x16x32_bf16 v[52:55], v[156:159], v[172:175], v[52:55]
	v_mfma_f32_16x16x32_bf16 v[48:51], v[164:167], v[172:175], v[48:51]
	v_mfma_f32_16x16x32_bf16 v[36:39], v[156:159], v[180:183], v[36:39]
	v_mfma_f32_16x16x32_bf16 v[32:35], v[164:167], v[180:183], v[32:35]
	v_mfma_f32_16x16x32_bf16 v[20:23], v[156:159], v[188:191], v[20:23]
	v_mfma_f32_16x16x32_bf16 v[16:19], v[164:167], v[188:191], v[16:19]
	v_mfma_f32_16x16x32_bf16 v[4:7], v[156:159], v[196:199], v[4:7]
	v_mfma_f32_16x16x32_bf16 v[0:3], v[164:167], v[196:199], v[0:3]
	v_mfma_f32_16x16x32_bf16 v[52:55], v[160:163], v[176:179], v[52:55]
	v_mfma_f32_16x16x32_bf16 v[48:51], v[168:171], v[176:179], v[48:51]
	s_barrier
	v_mfma_f32_16x16x32_bf16 v[36:39], v[160:163], v[184:187], v[36:39]
	v_mfma_f32_16x16x32_bf16 v[32:35], v[168:171], v[184:187], v[32:35]
	v_mfma_f32_16x16x32_bf16 v[20:23], v[160:163], v[192:195], v[20:23]
	v_mfma_f32_16x16x32_bf16 v[16:19], v[168:171], v[192:195], v[16:19]
	v_mfma_f32_16x16x32_bf16 v[4:7], v[160:163], v[200:203], v[4:7]
	v_mfma_f32_16x16x32_bf16 v[0:3], v[168:171], v[200:203], v[0:3]
	s_setprio 0
	s_add_i32 s35, 0, 0x18000
	v_add_u32_e32 v140, s35, v142
	s_add_i32 s44, 0, 0x1c000
	ds_read_b128 v[136:139], v140
	ds_read_b128 v[144:147], v140 offset:1024
	ds_read_b128 v[148:151], v140 offset:2048
	ds_read_b128 v[152:155], v140 offset:3072
	v_add_u32_e32 v140, s44, v142
	ds_read_b128 v[156:159], v140
	ds_read_b128 v[160:163], v140 offset:1024
	ds_read_b128 v[164:167], v140 offset:2048
	ds_read_b128 v[168:171], v140 offset:3072
	s_add_u32 s18, s42, 0x40000
	s_addc_u32 s19, s43, 0
	s_mov_b32 m0, s76
	v_lshl_add_u64 v[140:141], s[18:19], 0, v[130:131]
	ds_read_b128 v[172:175], v143 offset:32768
	ds_read_b128 v[176:179], v143 offset:33792
	ds_read_b128 v[180:183], v143 offset:34816
	ds_read_b128 v[184:187], v143 offset:35840
	ds_read_b128 v[188:191], v143 offset:36864
	ds_read_b128 v[192:195], v143 offset:37888
	ds_read_b128 v[196:199], v143 offset:38912
	ds_read_b128 v[200:203], v143 offset:39936
	global_load_lds_dwordx4 v[140:141], off
	v_lshl_add_u64 v[140:141], s[18:19], 0, v[132:133]
	s_mov_b32 m0, s77
	s_nop 0
	global_load_lds_dwordx4 v[140:141], off
	s_waitcnt vmcnt(8)
	s_waitcnt lgkmcnt(0)
	s_barrier
	s_setprio 1
	s_waitcnt lgkmcnt(0)
	v_mfma_f32_16x16x32_bf16 v[126:129], v[136:139], v[172:175], v[126:129]
	v_mfma_f32_16x16x32_bf16 v[122:125], v[148:151], v[172:175], v[122:125]
	v_mfma_f32_16x16x32_bf16 v[110:113], v[136:139], v[180:183], v[110:113]
	v_mfma_f32_16x16x32_bf16 v[106:109], v[148:151], v[180:183], v[106:109]
	v_mfma_f32_16x16x32_bf16 v[92:95], v[136:139], v[188:191], v[92:95]
	v_mfma_f32_16x16x32_bf16 v[88:91], v[148:151], v[188:191], v[88:91]
	v_mfma_f32_16x16x32_bf16 v[76:79], v[136:139], v[196:199], v[76:79]
	v_mfma_f32_16x16x32_bf16 v[72:75], v[148:151], v[196:199], v[72:75]
	v_mfma_f32_16x16x32_bf16 v[126:129], v[144:147], v[176:179], v[126:129]
	v_mfma_f32_16x16x32_bf16 v[122:125], v[152:155], v[176:179], v[122:125]
	v_mfma_f32_16x16x32_bf16 v[110:113], v[144:147], v[184:187], v[110:113]
	v_mfma_f32_16x16x32_bf16 v[106:109], v[152:155], v[184:187], v[106:109]
	v_mfma_f32_16x16x32_bf16 v[92:95], v[144:147], v[192:195], v[92:95]
	v_mfma_f32_16x16x32_bf16 v[88:91], v[152:155], v[192:195], v[88:91]
	v_mfma_f32_16x16x32_bf16 v[76:79], v[144:147], v[200:203], v[76:79]
	v_mfma_f32_16x16x32_bf16 v[72:75], v[152:155], v[200:203], v[72:75]
	v_mfma_f32_16x16x32_bf16 v[118:121], v[156:159], v[172:175], v[118:121]
	v_mfma_f32_16x16x32_bf16 v[114:117], v[164:167], v[172:175], v[114:117]
	v_mfma_f32_16x16x32_bf16 v[102:105], v[156:159], v[180:183], v[102:105]
	v_mfma_f32_16x16x32_bf16 v[98:101], v[164:167], v[180:183], v[98:101]
	v_mfma_f32_16x16x32_bf16 v[84:87], v[156:159], v[188:191], v[84:87]
	v_mfma_f32_16x16x32_bf16 v[80:83], v[164:167], v[188:191], v[80:83]
	v_mfma_f32_16x16x32_bf16 v[68:71], v[156:159], v[196:199], v[68:71]
	v_mfma_f32_16x16x32_bf16 v[64:67], v[164:167], v[196:199], v[64:67]
	v_mfma_f32_16x16x32_bf16 v[118:121], v[160:163], v[176:179], v[118:121]
	v_mfma_f32_16x16x32_bf16 v[114:117], v[168:171], v[176:179], v[114:117]
	s_barrier
	v_mfma_f32_16x16x32_bf16 v[102:105], v[160:163], v[184:187], v[102:105]
	v_mfma_f32_16x16x32_bf16 v[98:101], v[168:171], v[184:187], v[98:101]
	v_mfma_f32_16x16x32_bf16 v[84:87], v[160:163], v[192:195], v[84:87]
	v_mfma_f32_16x16x32_bf16 v[80:83], v[168:171], v[192:195], v[80:83]
	v_mfma_f32_16x16x32_bf16 v[68:71], v[160:163], v[200:203], v[68:71]
	v_mfma_f32_16x16x32_bf16 v[64:67], v[168:171], v[200:203], v[64:67]
	s_setprio 0
	s_add_i32 s18, s35, s14
	v_lshl_add_u64 v[140:141], s[74:75], 0, v[96:97]
	s_mov_b32 m0, s18
	ds_read_b128 v[172:175], v143 offset:49152
	ds_read_b128 v[176:179], v143 offset:50176
	ds_read_b128 v[180:183], v143 offset:51200
	ds_read_b128 v[184:187], v143 offset:52224
	ds_read_b128 v[188:191], v143 offset:53248
	ds_read_b128 v[192:195], v143 offset:54272
	ds_read_b128 v[196:199], v143 offset:55296
	ds_read_b128 v[200:203], v143 offset:56320
	global_load_lds_dwordx4 v[140:141], off
	s_add_i32 m0, s18, 0x2000
	s_add_u32 s18, s74, 0x40000
	v_lshl_add_u64 v[140:141], s[74:75], 0, v[134:135]
	s_addc_u32 s19, s75, 0
	s_add_i32 s35, s44, s14
	global_load_lds_dwordx4 v[140:141], off
	v_lshl_add_u64 v[140:141], s[18:19], 0, v[96:97]
	s_mov_b32 m0, s35
	s_nop 0
	global_load_lds_dwordx4 v[140:141], off
	v_lshl_add_u64 v[140:141], s[18:19], 0, v[134:135]
	s_add_i32 m0, s35, 0x2000
	s_nop 0
	global_load_lds_dwordx4 v[140:141], off
	v_lshl_add_u64 v[140:141], s[38:39], 0, v[130:131]
	s_mov_b32 m0, s81
	s_nop 0
	global_load_lds_dwordx4 v[140:141], off
	v_lshl_add_u64 v[140:141], s[38:39], 0, v[132:133]
	s_mov_b32 m0, s82
	s_nop 0
	global_load_lds_dwordx4 v[140:141], off
	s_waitcnt vmcnt(8)
	s_waitcnt lgkmcnt(0)
	s_barrier
	s_setprio 1
	s_waitcnt lgkmcnt(0)
	v_mfma_f32_16x16x32_bf16 v[60:63], v[136:139], v[172:175], v[60:63]
	v_mfma_f32_16x16x32_bf16 v[56:59], v[148:151], v[172:175], v[56:59]
	v_mfma_f32_16x16x32_bf16 v[44:47], v[136:139], v[180:183], v[44:47]
	v_mfma_f32_16x16x32_bf16 v[40:43], v[148:151], v[180:183], v[40:43]
	v_mfma_f32_16x16x32_bf16 v[28:31], v[136:139], v[188:191], v[28:31]
	v_mfma_f32_16x16x32_bf16 v[24:27], v[148:151], v[188:191], v[24:27]
	v_mfma_f32_16x16x32_bf16 v[12:15], v[136:139], v[196:199], v[12:15]
	v_mfma_f32_16x16x32_bf16 v[8:11], v[148:151], v[196:199], v[8:11]
	v_mfma_f32_16x16x32_bf16 v[60:63], v[144:147], v[176:179], v[60:63]
	v_mfma_f32_16x16x32_bf16 v[56:59], v[152:155], v[176:179], v[56:59]
	v_mfma_f32_16x16x32_bf16 v[44:47], v[144:147], v[184:187], v[44:47]
	v_mfma_f32_16x16x32_bf16 v[40:43], v[152:155], v[184:187], v[40:43]
	v_mfma_f32_16x16x32_bf16 v[28:31], v[144:147], v[192:195], v[28:31]
	v_mfma_f32_16x16x32_bf16 v[24:27], v[152:155], v[192:195], v[24:27]
	v_mfma_f32_16x16x32_bf16 v[12:15], v[144:147], v[200:203], v[12:15]
	v_mfma_f32_16x16x32_bf16 v[8:11], v[152:155], v[200:203], v[8:11]
	v_mfma_f32_16x16x32_bf16 v[52:55], v[156:159], v[172:175], v[52:55]
	v_mfma_f32_16x16x32_bf16 v[48:51], v[164:167], v[172:175], v[48:51]
	v_mfma_f32_16x16x32_bf16 v[36:39], v[156:159], v[180:183], v[36:39]
	v_mfma_f32_16x16x32_bf16 v[32:35], v[164:167], v[180:183], v[32:35]
	v_mfma_f32_16x16x32_bf16 v[20:23], v[156:159], v[188:191], v[20:23]
	v_mfma_f32_16x16x32_bf16 v[16:19], v[164:167], v[188:191], v[16:19]
	v_mfma_f32_16x16x32_bf16 v[4:7], v[156:159], v[196:199], v[4:7]
	v_mfma_f32_16x16x32_bf16 v[0:3], v[164:167], v[196:199], v[0:3]
	v_mfma_f32_16x16x32_bf16 v[52:55], v[160:163], v[176:179], v[52:55]
	v_mfma_f32_16x16x32_bf16 v[48:51], v[168:171], v[176:179], v[48:51]
	s_barrier
	v_mfma_f32_16x16x32_bf16 v[36:39], v[160:163], v[184:187], v[36:39]
	v_mfma_f32_16x16x32_bf16 v[32:35], v[168:171], v[184:187], v[32:35]
	v_mfma_f32_16x16x32_bf16 v[20:23], v[160:163], v[192:195], v[20:23]
	v_mfma_f32_16x16x32_bf16 v[16:19], v[168:171], v[192:195], v[16:19]
	v_mfma_f32_16x16x32_bf16 v[4:7], v[160:163], v[200:203], v[4:7]
	v_mfma_f32_16x16x32_bf16 v[0:3], v[168:171], v[200:203], v[0:3]
	s_setprio 0
	s_add_i32 s89, s89, 2
	s_add_u32 s65, s65, 0x100
	s_addc_u32 s86, s86, 0
	s_add_u32 s87, s87, 0x100
	s_addc_u32 s88, s88, 0
	s_add_u32 s68, s68, 0x100
	s_addc_u32 s69, s69, 0
	s_cmp_gt_u32 s89, 13
	s_cbranch_scc0 .LBB0_122
	s_and_b64 vcc, exec, s[28:29]
	s_cbranch_vccz .LBB0_125
	s_barrier

.LBB0_195:
	s_cmp_eq_u32 s72, s76
	s_cselect_b64 s[18:19], -1, 0
	s_add_i32 s76, s76, 2
	s_and_b64 s[42:43], s[18:19], exec
	s_cselect_b32 s44, s38, s73
	s_cselect_b32 s45, s39, s75
	s_cselect_b32 s47, s61, vcc_hi
	s_cselect_b32 s46, s60, vcc_lo
	s_add_u32 s58, s44, 0x80
	s_addc_u32 s59, s45, 0
	s_add_u32 s42, s46, 0x80
	s_addc_u32 s43, s47, 0
	s_add_i32 s35, 0, 0x10000
	s_and_b64 s[30:31], s[18:19], exec
	s_mov_b64 s[68:69], s[78:79]
	v_add_u32_e32 v144, s35, v170
	s_cselect_b32 s49, s29, s14
	s_add_i32 s70, 0, 0x14000
	ds_read_b128 v[132:135], v144
	ds_read_b128 v[136:139], v144 offset:1024
	ds_read_b128 v[140:143], v144 offset:2048
	ds_read_b128 v[150:153], v144 offset:3072
	v_add_u32_e32 v144, s70, v170
	ds_read_b128 v[154:157], v144
	ds_read_b128 v[158:161], v144 offset:1024
	ds_read_b128 v[162:165], v144 offset:2048
	ds_read_b128 v[172:175], v144 offset:3072
	s_and_b64 s[18:19], s[18:19], exec
	s_cselect_b32 s18, 0, s67
	s_cselect_b32 s19, s20, s66
	s_add_u32 s30, s68, s66
	s_addc_u32 s31, s69, s67
	v_lshl_add_u64 v[144:145], s[30:31], 0, v[96:97]
	s_add_i32 m0, s63, 0xc000
	ds_read_b128 v[176:179], v171
	ds_read_b128 v[180:183], v171 offset:1024
	ds_read_b128 v[184:187], v171 offset:2048
	ds_read_b128 v[188:191], v171 offset:3072
	ds_read_b128 v[192:195], v171 offset:4096
	ds_read_b128 v[196:199], v171 offset:5120
	ds_read_b128 v[200:203], v171 offset:6144
	ds_read_b128 v[204:207], v171 offset:7168
	global_load_lds_dwordx4 v[144:145], off
	v_lshl_add_u64 v[144:145], s[30:31], 0, v[130:131]
	s_add_i32 m0, s63, 0xe000
	s_nop 0
	global_load_lds_dwordx4 v[144:145], off
	s_waitcnt vmcnt(8)
	s_waitcnt lgkmcnt(0)
	s_barrier
	s_setprio 1
	s_waitcnt lgkmcnt(0)
	v_mfma_f32_16x16x32_bf16 v[126:129], v[132:135], v[176:179], v[126:129]
	v_mfma_f32_16x16x32_bf16 v[122:125], v[140:143], v[176:179], v[122:125]
	v_mfma_f32_16x16x32_bf16 v[110:113], v[132:135], v[184:187], v[110:113]
	v_mfma_f32_16x16x32_bf16 v[106:109], v[140:143], v[184:187], v[106:109]
	v_mfma_f32_16x16x32_bf16 v[92:95], v[132:135], v[192:195], v[92:95]
	v_mfma_f32_16x16x32_bf16 v[88:91], v[140:143], v[192:195], v[88:91]
	v_mfma_f32_16x16x32_bf16 v[76:79], v[132:135], v[200:203], v[76:79]
	v_mfma_f32_16x16x32_bf16 v[72:75], v[140:143], v[200:203], v[72:75]
	v_mfma_f32_16x16x32_bf16 v[126:129], v[136:139], v[180:183], v[126:129]
	v_mfma_f32_16x16x32_bf16 v[122:125], v[150:153], v[180:183], v[122:125]
	v_mfma_f32_16x16x32_bf16 v[110:113], v[136:139], v[188:191], v[110:113]
	v_mfma_f32_16x16x32_bf16 v[106:109], v[150:153], v[188:191], v[106:109]
	v_mfma_f32_16x16x32_bf16 v[92:95], v[136:139], v[196:199], v[92:95]
	v_mfma_f32_16x16x32_bf16 v[88:91], v[150:153], v[196:199], v[88:91]
	v_mfma_f32_16x16x32_bf16 v[76:79], v[136:139], v[204:207], v[76:79]
	v_mfma_f32_16x16x32_bf16 v[72:75], v[150:153], v[204:207], v[72:75]
	v_mfma_f32_16x16x32_bf16 v[118:121], v[154:157], v[176:179], v[118:121]
	v_mfma_f32_16x16x32_bf16 v[114:117], v[162:165], v[176:179], v[114:117]
	v_mfma_f32_16x16x32_bf16 v[102:105], v[154:157], v[184:187], v[102:105]
	v_mfma_f32_16x16x32_bf16 v[98:101], v[162:165], v[184:187], v[98:101]
	v_mfma_f32_16x16x32_bf16 v[84:87], v[154:157], v[192:195], v[84:87]
	v_mfma_f32_16x16x32_bf16 v[80:83], v[162:165], v[192:195], v[80:83]
	v_mfma_f32_16x16x32_bf16 v[68:71], v[154:157], v[200:203], v[68:71]
	v_mfma_f32_16x16x32_bf16 v[64:67], v[162:165], v[200:203], v[64:67]
	v_mfma_f32_16x16x32_bf16 v[118:121], v[158:161], v[180:183], v[118:121]
	v_mfma_f32_16x16x32_bf16 v[114:117], v[172:175], v[180:183], v[114:117]
	s_barrier
	v_mfma_f32_16x16x32_bf16 v[102:105], v[158:161], v[188:191], v[102:105]
	v_mfma_f32_16x16x32_bf16 v[98:101], v[172:175], v[188:191], v[98:101]
	v_mfma_f32_16x16x32_bf16 v[84:87], v[158:161], v[196:199], v[84:87]
	v_mfma_f32_16x16x32_bf16 v[80:83], v[172:175], v[196:199], v[80:83]
	v_mfma_f32_16x16x32_bf16 v[68:71], v[158:161], v[204:207], v[68:71]
	v_mfma_f32_16x16x32_bf16 v[64:67], v[172:175], v[204:207], v[64:67]
	s_setprio 0
	s_add_i32 s35, s35, s80
	v_mad_u64_u32 v[144:145], s[30:31], v168, s49, v[146:147]
	s_mov_b32 m0, s35
	ds_read_b128 v[176:179], v171 offset:16384
	ds_read_b128 v[180:183], v171 offset:17408
	ds_read_b128 v[184:187], v171 offset:18432
	ds_read_b128 v[188:191], v171 offset:19456
	ds_read_b128 v[192:195], v171 offset:20480
	ds_read_b128 v[196:199], v171 offset:21504
	ds_read_b128 v[200:203], v171 offset:22528
	ds_read_b128 v[204:207], v171 offset:23552
	global_load_lds_dwordx4 v144, s[46:47]
	v_mad_u64_u32 v[166:167], s[30:31], v169, s49, v[148:149]
	s_add_i32 m0, s35, 0x2000
	s_add_u32 s30, s46, s19
	s_addc_u32 s31, s47, s18
	s_add_i32 s35, s70, s80
	global_load_lds_dwordx4 v166, s[46:47]
	s_mov_b32 m0, s35
	s_nop 0
	global_load_lds_dwordx4 v144, s[30:31]
	s_add_i32 m0, s35, 0x2000
	s_nop 0
	global_load_lds_dwordx4 v166, s[30:31]
	v_mad_u64_u32 v[208:209], s[30:31], s49, v147, v[146:147]
	s_mov_b32 m0, s63
	v_mad_u64_u32 v[210:211], s[30:31], s49, v149, v[148:149]
	global_load_lds_dwordx4 v208, s[44:45]
	s_mov_b32 m0, s65
	s_nop 0
	global_load_lds_dwordx4 v210, s[44:45]
	s_waitcnt vmcnt(8)
	s_waitcnt lgkmcnt(0)
	s_barrier
	s_setprio 1
	s_waitcnt lgkmcnt(0)
	v_mfma_f32_16x16x32_bf16 v[60:63], v[132:135], v[176:179], v[60:63]
	v_mfma_f32_16x16x32_bf16 v[56:59], v[140:143], v[176:179], v[56:59]
	v_mfma_f32_16x16x32_bf16 v[44:47], v[132:135], v[184:187], v[44:47]
	v_mfma_f32_16x16x32_bf16 v[40:43], v[140:143], v[184:187], v[40:43]
	v_mfma_f32_16x16x32_bf16 v[28:31], v[132:135], v[192:195], v[28:31]
	v_mfma_f32_16x16x32_bf16 v[24:27], v[140:143], v[192:195], v[24:27]
	v_mfma_f32_16x16x32_bf16 v[12:15], v[132:135], v[200:203], v[12:15]
	v_mfma_f32_16x16x32_bf16 v[8:11], v[140:143], v[200:203], v[8:11]
	v_mfma_f32_16x16x32_bf16 v[60:63], v[136:139], v[180:183], v[60:63]
	v_mfma_f32_16x16x32_bf16 v[56:59], v[150:153], v[180:183], v[56:59]
	v_mfma_f32_16x16x32_bf16 v[44:47], v[136:139], v[188:191], v[44:47]
	v_mfma_f32_16x16x32_bf16 v[40:43], v[150:153], v[188:191], v[40:43]
	v_mfma_f32_16x16x32_bf16 v[28:31], v[136:139], v[196:199], v[28:31]
	v_mfma_f32_16x16x32_bf16 v[24:27], v[150:153], v[196:199], v[24:27]
	v_mfma_f32_16x16x32_bf16 v[12:15], v[136:139], v[204:207], v[12:15]
	v_mfma_f32_16x16x32_bf16 v[8:11], v[150:153], v[204:207], v[8:11]
	v_mfma_f32_16x16x32_bf16 v[52:55], v[154:157], v[176:179], v[52:55]
	v_mfma_f32_16x16x32_bf16 v[48:51], v[162:165], v[176:179], v[48:51]
	v_mfma_f32_16x16x32_bf16 v[36:39], v[154:157], v[184:187], v[36:39]
	v_mfma_f32_16x16x32_bf16 v[32:35], v[162:165], v[184:187], v[32:35]
	v_mfma_f32_16x16x32_bf16 v[20:23], v[154:157], v[192:195], v[20:23]
	v_mfma_f32_16x16x32_bf16 v[16:19], v[162:165], v[192:195], v[16:19]
	v_mfma_f32_16x16x32_bf16 v[4:7], v[154:157], v[200:203], v[4:7]
	v_mfma_f32_16x16x32_bf16 v[0:3], v[162:165], v[200:203], v[0:3]
	v_mfma_f32_16x16x32_bf16 v[52:55], v[158:161], v[180:183], v[52:55]
	v_mfma_f32_16x16x32_bf16 v[48:51], v[172:175], v[180:183], v[48:51]
	s_barrier
	v_mfma_f32_16x16x32_bf16 v[36:39], v[158:161], v[188:191], v[36:39]
	v_mfma_f32_16x16x32_bf16 v[32:35], v[172:175], v[188:191], v[32:35]
	v_mfma_f32_16x16x32_bf16 v[20:23], v[158:161], v[196:199], v[20:23]
	v_mfma_f32_16x16x32_bf16 v[16:19], v[172:175], v[196:199], v[16:19]
	v_mfma_f32_16x16x32_bf16 v[4:7], v[158:161], v[204:207], v[4:7]
	v_mfma_f32_16x16x32_bf16 v[0:3], v[172:175], v[204:207], v[0:3]
	s_setprio 0
	s_add_i32 s35, 0, 0x18000
	v_add_u32_e32 v145, s35, v170
	s_add_i32 s46, 0, 0x1c000
	ds_read_b128 v[132:135], v145
	ds_read_b128 v[136:139], v145 offset:1024
	ds_read_b128 v[140:143], v145 offset:2048
	ds_read_b128 v[150:153], v145 offset:3072
	v_add_u32_e32 v145, s46, v170
	ds_read_b128 v[154:157], v145
	ds_read_b128 v[158:161], v145 offset:1024
	ds_read_b128 v[162:165], v145 offset:2048
	ds_read_b128 v[172:175], v145 offset:3072
	s_add_u32 s30, s44, s19
	s_addc_u32 s31, s45, s18
	s_mov_b32 m0, s81
	ds_read_b128 v[176:179], v171 offset:32768
	ds_read_b128 v[180:183], v171 offset:33792
	ds_read_b128 v[184:187], v171 offset:34816
	ds_read_b128 v[188:191], v171 offset:35840
	ds_read_b128 v[192:195], v171 offset:36864
	ds_read_b128 v[196:199], v171 offset:37888
	ds_read_b128 v[200:203], v171 offset:38912
	ds_read_b128 v[204:207], v171 offset:39936
	global_load_lds_dwordx4 v208, s[30:31]
	s_mov_b32 m0, s90
	s_nop 0
	global_load_lds_dwordx4 v210, s[30:31]
	s_waitcnt vmcnt(8)
	s_waitcnt lgkmcnt(0)
	s_barrier
	s_setprio 1
	s_waitcnt lgkmcnt(0)
	v_mfma_f32_16x16x32_bf16 v[126:129], v[132:135], v[176:179], v[126:129]
	v_mfma_f32_16x16x32_bf16 v[122:125], v[140:143], v[176:179], v[122:125]
	v_mfma_f32_16x16x32_bf16 v[110:113], v[132:135], v[184:187], v[110:113]
	v_mfma_f32_16x16x32_bf16 v[106:109], v[140:143], v[184:187], v[106:109]
	v_mfma_f32_16x16x32_bf16 v[92:95], v[132:135], v[192:195], v[92:95]
	v_mfma_f32_16x16x32_bf16 v[88:91], v[140:143], v[192:195], v[88:91]
	v_mfma_f32_16x16x32_bf16 v[76:79], v[132:135], v[200:203], v[76:79]
	v_mfma_f32_16x16x32_bf16 v[72:75], v[140:143], v[200:203], v[72:75]
	v_mfma_f32_16x16x32_bf16 v[126:129], v[136:139], v[180:183], v[126:129]
	v_mfma_f32_16x16x32_bf16 v[122:125], v[150:153], v[180:183], v[122:125]
	v_mfma_f32_16x16x32_bf16 v[110:113], v[136:139], v[188:191], v[110:113]
	v_mfma_f32_16x16x32_bf16 v[106:109], v[150:153], v[188:191], v[106:109]
	v_mfma_f32_16x16x32_bf16 v[92:95], v[136:139], v[196:199], v[92:95]
	v_mfma_f32_16x16x32_bf16 v[88:91], v[150:153], v[196:199], v[88:91]
	v_mfma_f32_16x16x32_bf16 v[76:79], v[136:139], v[204:207], v[76:79]
	v_mfma_f32_16x16x32_bf16 v[72:75], v[150:153], v[204:207], v[72:75]
	v_mfma_f32_16x16x32_bf16 v[118:121], v[154:157], v[176:179], v[118:121]
	v_mfma_f32_16x16x32_bf16 v[114:117], v[162:165], v[176:179], v[114:117]
	v_mfma_f32_16x16x32_bf16 v[102:105], v[154:157], v[184:187], v[102:105]
	v_mfma_f32_16x16x32_bf16 v[98:101], v[162:165], v[184:187], v[98:101]
	v_mfma_f32_16x16x32_bf16 v[84:87], v[154:157], v[192:195], v[84:87]
	v_mfma_f32_16x16x32_bf16 v[80:83], v[162:165], v[192:195], v[80:83]
	v_mfma_f32_16x16x32_bf16 v[68:71], v[154:157], v[200:203], v[68:71]
	v_mfma_f32_16x16x32_bf16 v[64:67], v[162:165], v[200:203], v[64:67]
	v_mfma_f32_16x16x32_bf16 v[118:121], v[158:161], v[180:183], v[118:121]
	v_mfma_f32_16x16x32_bf16 v[114:117], v[172:175], v[180:183], v[114:117]
	s_barrier
	v_mfma_f32_16x16x32_bf16 v[102:105], v[158:161], v[188:191], v[102:105]
	v_mfma_f32_16x16x32_bf16 v[98:101], v[172:175], v[188:191], v[98:101]
	v_mfma_f32_16x16x32_bf16 v[84:87], v[158:161], v[196:199], v[84:87]
	v_mfma_f32_16x16x32_bf16 v[80:83], v[172:175], v[196:199], v[80:83]
	v_mfma_f32_16x16x32_bf16 v[68:71], v[158:161], v[204:207], v[68:71]
	v_mfma_f32_16x16x32_bf16 v[64:67], v[172:175], v[204:207], v[64:67]
	s_setprio 0
	s_add_i32 s30, s35, s80
	s_mov_b32 m0, s30
	ds_read_b128 v[176:179], v171 offset:49152
	ds_read_b128 v[180:183], v171 offset:50176
	ds_read_b128 v[184:187], v171 offset:51200
	ds_read_b128 v[188:191], v171 offset:52224
	ds_read_b128 v[192:195], v171 offset:53248
	ds_read_b128 v[196:199], v171 offset:54272
	ds_read_b128 v[200:203], v171 offset:55296
	ds_read_b128 v[204:207], v171 offset:56320
	global_load_lds_dwordx4 v144, s[42:43]
	s_add_i32 m0, s30, 0x2000
	s_add_u32 s30, s42, s19
	s_addc_u32 s31, s43, s18
	s_add_i32 s18, s46, s80
	global_load_lds_dwordx4 v166, s[42:43]
	s_mov_b32 m0, s18
	s_nop 0
	global_load_lds_dwordx4 v144, s[30:31]
	s_add_i32 m0, s18, 0x2000
	s_nop 0
	global_load_lds_dwordx4 v166, s[30:31]
	s_mov_b32 m0, s82
	s_nop 0
	global_load_lds_dwordx4 v208, s[58:59]
	s_mov_b32 m0, s83
	s_nop 0
	global_load_lds_dwordx4 v210, s[58:59]
	s_waitcnt vmcnt(8)
	s_waitcnt lgkmcnt(0)
	s_barrier
	s_setprio 1
	s_waitcnt lgkmcnt(0)
	v_mfma_f32_16x16x32_bf16 v[60:63], v[132:135], v[176:179], v[60:63]
	v_mfma_f32_16x16x32_bf16 v[56:59], v[140:143], v[176:179], v[56:59]
	v_mfma_f32_16x16x32_bf16 v[44:47], v[132:135], v[184:187], v[44:47]
	v_mfma_f32_16x16x32_bf16 v[40:43], v[140:143], v[184:187], v[40:43]
	v_mfma_f32_16x16x32_bf16 v[28:31], v[132:135], v[192:195], v[28:31]
	v_mfma_f32_16x16x32_bf16 v[24:27], v[140:143], v[192:195], v[24:27]
	v_mfma_f32_16x16x32_bf16 v[12:15], v[132:135], v[200:203], v[12:15]
	v_mfma_f32_16x16x32_bf16 v[8:11], v[140:143], v[200:203], v[8:11]
	v_mfma_f32_16x16x32_bf16 v[60:63], v[136:139], v[180:183], v[60:63]
	v_mfma_f32_16x16x32_bf16 v[56:59], v[150:153], v[180:183], v[56:59]
	v_mfma_f32_16x16x32_bf16 v[44:47], v[136:139], v[188:191], v[44:47]
	v_mfma_f32_16x16x32_bf16 v[40:43], v[150:153], v[188:191], v[40:43]
	v_mfma_f32_16x16x32_bf16 v[28:31], v[136:139], v[196:199], v[28:31]
	v_mfma_f32_16x16x32_bf16 v[24:27], v[150:153], v[196:199], v[24:27]
	v_mfma_f32_16x16x32_bf16 v[12:15], v[136:139], v[204:207], v[12:15]
	v_mfma_f32_16x16x32_bf16 v[8:11], v[150:153], v[204:207], v[8:11]
	v_mfma_f32_16x16x32_bf16 v[52:55], v[154:157], v[176:179], v[52:55]
	v_mfma_f32_16x16x32_bf16 v[48:51], v[162:165], v[176:179], v[48:51]
	v_mfma_f32_16x16x32_bf16 v[36:39], v[154:157], v[184:187], v[36:39]
	v_mfma_f32_16x16x32_bf16 v[32:35], v[162:165], v[184:187], v[32:35]
	v_mfma_f32_16x16x32_bf16 v[20:23], v[154:157], v[192:195], v[20:23]
	v_mfma_f32_16x16x32_bf16 v[16:19], v[162:165], v[192:195], v[16:19]
	v_mfma_f32_16x16x32_bf16 v[4:7], v[154:157], v[200:203], v[4:7]
	v_mfma_f32_16x16x32_bf16 v[0:3], v[162:165], v[200:203], v[0:3]
	v_mfma_f32_16x16x32_bf16 v[52:55], v[158:161], v[180:183], v[52:55]
	v_mfma_f32_16x16x32_bf16 v[48:51], v[172:175], v[180:183], v[48:51]
	s_barrier
	v_mfma_f32_16x16x32_bf16 v[36:39], v[158:161], v[188:191], v[36:39]
	v_mfma_f32_16x16x32_bf16 v[32:35], v[172:175], v[188:191], v[32:35]
	v_mfma_f32_16x16x32_bf16 v[20:23], v[158:161], v[196:199], v[20:23]
	v_mfma_f32_16x16x32_bf16 v[16:19], v[172:175], v[196:199], v[16:19]
	v_mfma_f32_16x16x32_bf16 v[4:7], v[158:161], v[204:207], v[4:7]
	v_mfma_f32_16x16x32_bf16 v[0:3], v[172:175], v[204:207], v[0:3]
	s_setprio 0
	s_add_u32 s73, s73, 0x100
	s_addc_u32 s75, s75, 0
	s_add_u32 vcc_lo, vcc_lo, 0x100
	s_addc_u32 vcc_hi, vcc_hi, 0
	s_add_u32 s78, s78, 0x100
	s_addc_u32 s79, s79, 0
	s_cmp_ge_u32 s76, s16
	s_cbranch_scc0 .LBB0_195
	s_and_b64 vcc, exec, s[96:97]
	s_cbranch_vccz .LBB0_198
	s_barrier

.LBB0_383:
	s_add_u32 s18, s78, 0x80
	s_addc_u32 s19, s79, 0
	s_add_u32 s42, s78, 0x100
	s_addc_u32 s43, s79, 0
	s_add_u32 s44, s76, 0x100
	s_addc_u32 s45, s77, 0
	s_add_u32 s80, s78, 0x180
	s_addc_u32 s81, s79, 0
	s_add_u32 s84, s76, 0x180
	s_addc_u32 s85, s77, 0
	s_add_i32 vcc_hi, 0, 0x10000
	s_add_i32 s22, 0, 0x14000
	s_mov_b64 s[82:83], s[80:81]
	v_add_u32_e32 v0, vcc_hi, v155
	v_add_u32_e32 v1, s22, v155
	ds_read_b128 v[2:5], v0
	ds_read_b128 v[6:9], v0 offset:1024
	ds_read_b128 v[10:13], v0 offset:2048
	ds_read_b128 v[14:17], v0 offset:3072
	ds_read_b128 v[18:21], v1
	ds_read_b128 v[22:25], v1 offset:1024
	ds_read_b128 v[26:29], v1 offset:2048
	ds_read_b128 v[30:33], v1 offset:3072
	s_add_u32 s18, s18, 0x18000
	s_addc_u32 s19, s19, 0
	s_add_i32 s88, s49, 0xc000
	v_lshl_add_u64 v[66:67], s[18:19], 0, v[136:137]
	s_mov_b32 m0, s88
	s_add_i32 vcc_lo, s49, 0xe000
	ds_read_b128 v[34:37], v157
	ds_read_b128 v[38:41], v157 offset:1024
	ds_read_b128 v[42:45], v157 offset:2048
	ds_read_b128 v[46:49], v157 offset:3072
	ds_read_b128 v[50:53], v157 offset:4096
	ds_read_b128 v[54:57], v157 offset:5120
	ds_read_b128 v[58:61], v157 offset:6144
	ds_read_b128 v[62:65], v157 offset:7168
	global_load_lds_dwordx4 v[66:67], off
	v_lshl_add_u64 v[66:67], s[18:19], 0, v[132:133]
	s_mov_b32 m0, vcc_lo
	s_nop 0
	global_load_lds_dwordx4 v[66:67], off
	s_waitcnt vmcnt(8)
	s_waitcnt lgkmcnt(0)
	s_barrier
	s_setprio 1
	s_waitcnt lgkmcnt(0)
	v_mfma_f32_16x16x32_bf16 v[66:69], v[2:5], v[34:37], 0
	v_mfma_f32_16x16x32_bf16 v[70:73], v[10:13], v[34:37], 0
	v_mfma_f32_16x16x32_bf16 v[74:77], v[2:5], v[42:45], 0
	v_mfma_f32_16x16x32_bf16 v[78:81], v[10:13], v[42:45], 0
	v_mfma_f32_16x16x32_bf16 v[82:85], v[2:5], v[50:53], 0
	v_mfma_f32_16x16x32_bf16 v[86:89], v[10:13], v[50:53], 0
	v_mfma_f32_16x16x32_bf16 v[90:93], v[2:5], v[58:61], 0
	v_mfma_f32_16x16x32_bf16 v[98:101], v[10:13], v[58:61], 0
	v_mfma_f32_16x16x32_bf16 v[66:69], v[6:9], v[38:41], v[66:69]
	v_mfma_f32_16x16x32_bf16 v[70:73], v[14:17], v[38:41], v[70:73]
	v_mfma_f32_16x16x32_bf16 v[74:77], v[6:9], v[46:49], v[74:77]
	v_mfma_f32_16x16x32_bf16 v[78:81], v[14:17], v[46:49], v[78:81]
	v_mfma_f32_16x16x32_bf16 v[82:85], v[6:9], v[54:57], v[82:85]
	v_mfma_f32_16x16x32_bf16 v[86:89], v[14:17], v[54:57], v[86:89]
	v_mfma_f32_16x16x32_bf16 v[90:93], v[6:9], v[62:65], v[90:93]
	v_mfma_f32_16x16x32_bf16 v[98:101], v[14:17], v[62:65], v[98:101]
	v_mfma_f32_16x16x32_bf16 v[102:105], v[18:21], v[34:37], 0
	v_mfma_f32_16x16x32_bf16 v[34:37], v[26:29], v[34:37], 0
	v_mfma_f32_16x16x32_bf16 v[102:105], v[22:25], v[38:41], v[102:105]
	v_mfma_f32_16x16x32_bf16 v[34:37], v[30:33], v[38:41], v[34:37]
	v_mfma_f32_16x16x32_bf16 v[38:41], v[18:21], v[42:45], 0
	v_mfma_f32_16x16x32_bf16 v[42:45], v[26:29], v[42:45], 0
	v_mfma_f32_16x16x32_bf16 v[38:41], v[22:25], v[46:49], v[38:41]
	v_mfma_f32_16x16x32_bf16 v[42:45], v[30:33], v[46:49], v[42:45]
	v_mfma_f32_16x16x32_bf16 v[46:49], v[18:21], v[50:53], 0
	v_mfma_f32_16x16x32_bf16 v[50:53], v[26:29], v[50:53], 0
	s_barrier
	v_mfma_f32_16x16x32_bf16 v[46:49], v[22:25], v[54:57], v[46:49]
	v_mfma_f32_16x16x32_bf16 v[50:53], v[30:33], v[54:57], v[50:53]
	v_mfma_f32_16x16x32_bf16 v[54:57], v[18:21], v[58:61], 0
	v_mfma_f32_16x16x32_bf16 v[58:61], v[26:29], v[58:61], 0
	v_mfma_f32_16x16x32_bf16 v[54:57], v[22:25], v[62:65], v[54:57]
	v_mfma_f32_16x16x32_bf16 v[58:61], v[30:33], v[62:65], v[58:61]
	s_setprio 0
	s_add_i32 vcc_hi, vcc_hi, s75
	s_add_i32 s70, vcc_hi, 0x2000
	v_lshl_add_u64 v[94:95], s[44:45], 0, v[134:135]
	s_mov_b32 m0, vcc_hi
	s_add_u32 s18, s44, 0x18000
	ds_read_b128 v[62:65], v157 offset:16384
	ds_read_b128 v[106:109], v157 offset:17408
	ds_read_b128 v[110:113], v157 offset:18432
	ds_read_b128 v[114:117], v157 offset:19456
	ds_read_b128 v[118:121], v157 offset:20480
	ds_read_b128 v[122:125], v157 offset:21504
	ds_read_b128 v[126:129], v157 offset:22528
	ds_read_b128 v[138:141], v157 offset:23552
	global_load_lds_dwordx4 v[94:95], off
	v_lshl_add_u64 v[94:95], s[44:45], 0, v[130:131]
	s_mov_b32 m0, s70
	s_addc_u32 s19, s45, 0
	s_add_i32 s22, s22, s75
	global_load_lds_dwordx4 v[94:95], off
	v_lshl_add_u64 v[94:95], s[18:19], 0, v[134:135]
	s_mov_b32 m0, s22
	s_add_i32 s23, s22, 0x2000
	global_load_lds_dwordx4 v[94:95], off
	v_lshl_add_u64 v[94:95], s[18:19], 0, v[130:131]
	s_mov_b32 m0, s23
	s_nop 0
	global_load_lds_dwordx4 v[94:95], off
	v_lshl_add_u64 v[94:95], s[42:43], 0, v[136:137]
	s_mov_b32 m0, s49
	s_nop 0
	global_load_lds_dwordx4 v[94:95], off
	v_lshl_add_u64 v[94:95], s[42:43], 0, v[132:133]
	s_mov_b32 m0, s89
	s_nop 0
	global_load_lds_dwordx4 v[94:95], off
	s_waitcnt vmcnt(8)
	s_waitcnt lgkmcnt(0)
	s_barrier
	s_setprio 1
	s_waitcnt lgkmcnt(0)
	v_mfma_f32_16x16x32_bf16 v[142:145], v[2:5], v[62:65], 0
	v_mfma_f32_16x16x32_bf16 v[150:153], v[2:5], v[110:113], 0
	v_mfma_f32_16x16x32_bf16 v[162:165], v[2:5], v[118:121], 0
	v_mfma_f32_16x16x32_bf16 v[2:5], v[2:5], v[126:129], 0
	v_mfma_f32_16x16x32_bf16 v[142:145], v[6:9], v[106:109], v[142:145]
	v_mfma_f32_16x16x32_bf16 v[146:149], v[10:13], v[62:65], 0
	v_mfma_f32_16x16x32_bf16 v[150:153], v[6:9], v[114:117], v[150:153]
	v_mfma_f32_16x16x32_bf16 v[158:161], v[10:13], v[110:113], 0
	v_mfma_f32_16x16x32_bf16 v[162:165], v[6:9], v[122:125], v[162:165]
	v_mfma_f32_16x16x32_bf16 v[166:169], v[10:13], v[118:121], 0
	v_mfma_f32_16x16x32_bf16 v[4:7], v[6:9], v[138:141], v[2:5]
	v_mfma_f32_16x16x32_bf16 v[8:11], v[10:13], v[126:129], 0
	v_mfma_f32_16x16x32_bf16 v[8:11], v[14:17], v[138:141], v[8:11]
	v_mfma_f32_16x16x32_bf16 v[146:149], v[14:17], v[106:109], v[146:149]
	v_mfma_f32_16x16x32_bf16 v[158:161], v[14:17], v[114:117], v[158:161]
	v_mfma_f32_16x16x32_bf16 v[166:169], v[14:17], v[122:125], v[166:169]
	v_mfma_f32_16x16x32_bf16 v[12:15], v[18:21], v[62:65], 0
	v_mfma_f32_16x16x32_bf16 v[62:65], v[26:29], v[62:65], 0
	v_mfma_f32_16x16x32_bf16 v[12:15], v[22:25], v[106:109], v[12:15]
	v_mfma_f32_16x16x32_bf16 v[62:65], v[30:33], v[106:109], v[62:65]
	v_mfma_f32_16x16x32_bf16 v[106:109], v[18:21], v[110:113], 0
	v_mfma_f32_16x16x32_bf16 v[110:113], v[26:29], v[110:113], 0
	v_mfma_f32_16x16x32_bf16 v[106:109], v[22:25], v[114:117], v[106:109]
	v_mfma_f32_16x16x32_bf16 v[110:113], v[30:33], v[114:117], v[110:113]
	v_mfma_f32_16x16x32_bf16 v[114:117], v[18:21], v[118:121], 0
	v_mfma_f32_16x16x32_bf16 v[16:19], v[18:21], v[126:129], 0
	s_barrier
	v_mfma_f32_16x16x32_bf16 v[114:117], v[22:25], v[122:125], v[114:117]
	v_mfma_f32_16x16x32_bf16 v[118:121], v[26:29], v[118:121], 0
	v_mfma_f32_16x16x32_bf16 v[16:19], v[22:25], v[138:141], v[16:19]
	v_mfma_f32_16x16x32_bf16 v[20:23], v[26:29], v[126:129], 0
	v_mfma_f32_16x16x32_bf16 v[118:121], v[30:33], v[122:125], v[118:121]
	v_mfma_f32_16x16x32_bf16 v[20:23], v[30:33], v[138:141], v[20:23]
	s_setprio 0
	s_add_i32 s35, 0, 0x18000
	s_add_i32 s44, 0, 0x1c000
	v_add_u32_e32 v2, s35, v155
	v_add_u32_e32 v3, s44, v155
	ds_read_b128 v[24:27], v2
	ds_read_b128 v[28:31], v2 offset:1024
	ds_read_b128 v[122:125], v2 offset:2048
	ds_read_b128 v[126:129], v2 offset:3072
	ds_read_b128 v[138:141], v3
	ds_read_b128 v[170:173], v3 offset:1024
	ds_read_b128 v[174:177], v3 offset:2048
	ds_read_b128 v[178:181], v3 offset:3072
	s_add_u32 s18, s42, 0x18000
	s_addc_u32 s19, s43, 0
	s_mov_b32 m0, s90
	v_lshl_add_u64 v[32:33], s[18:19], 0, v[136:137]
	ds_read_b128 v[182:185], v157 offset:32768
	ds_read_b128 v[190:193], v157 offset:33792
	ds_read_b128 v[194:197], v157 offset:34816
	ds_read_b128 v[198:201], v157 offset:35840
	ds_read_b128 v[202:205], v157 offset:36864
	ds_read_b128 v[206:209], v157 offset:37888
	ds_read_b128 v[210:213], v157 offset:38912
	ds_read_b128 v[220:223], v157 offset:39936
	global_load_lds_dwordx4 v[32:33], off
	v_lshl_add_u64 v[32:33], s[18:19], 0, v[132:133]
	s_mov_b32 m0, s91
	s_nop 0
	global_load_lds_dwordx4 v[32:33], off
	s_waitcnt vmcnt(8)
	s_waitcnt lgkmcnt(0)
	s_barrier
	s_setprio 1
	s_waitcnt lgkmcnt(0)
	v_mfma_f32_16x16x32_bf16 v[66:69], v[24:27], v[182:185], v[66:69]
	v_mfma_f32_16x16x32_bf16 v[70:73], v[122:125], v[182:185], v[70:73]
	v_mfma_f32_16x16x32_bf16 v[74:77], v[24:27], v[194:197], v[74:77]
	v_mfma_f32_16x16x32_bf16 v[78:81], v[122:125], v[194:197], v[78:81]
	v_mfma_f32_16x16x32_bf16 v[82:85], v[24:27], v[202:205], v[82:85]
	v_mfma_f32_16x16x32_bf16 v[86:89], v[122:125], v[202:205], v[86:89]
	v_mfma_f32_16x16x32_bf16 v[90:93], v[24:27], v[210:213], v[90:93]
	v_mfma_f32_16x16x32_bf16 v[98:101], v[122:125], v[210:213], v[98:101]
	v_mfma_f32_16x16x32_bf16 v[66:69], v[28:31], v[190:193], v[66:69]
	v_mfma_f32_16x16x32_bf16 v[70:73], v[126:129], v[190:193], v[70:73]
	v_mfma_f32_16x16x32_bf16 v[74:77], v[28:31], v[198:201], v[74:77]
	v_mfma_f32_16x16x32_bf16 v[78:81], v[126:129], v[198:201], v[78:81]
	v_mfma_f32_16x16x32_bf16 v[82:85], v[28:31], v[206:209], v[82:85]
	v_mfma_f32_16x16x32_bf16 v[86:89], v[126:129], v[206:209], v[86:89]
	v_mfma_f32_16x16x32_bf16 v[90:93], v[28:31], v[220:223], v[90:93]
	v_mfma_f32_16x16x32_bf16 v[98:101], v[126:129], v[220:223], v[98:101]
	v_mfma_f32_16x16x32_bf16 v[102:105], v[138:141], v[182:185], v[102:105]
	v_mfma_f32_16x16x32_bf16 v[32:35], v[174:177], v[182:185], v[34:37]
	v_mfma_f32_16x16x32_bf16 v[36:39], v[138:141], v[194:197], v[38:41]
	v_mfma_f32_16x16x32_bf16 v[40:43], v[174:177], v[194:197], v[42:45]
	v_mfma_f32_16x16x32_bf16 v[44:47], v[138:141], v[202:205], v[46:49]
	v_mfma_f32_16x16x32_bf16 v[48:51], v[174:177], v[202:205], v[50:53]
	v_mfma_f32_16x16x32_bf16 v[52:55], v[138:141], v[210:213], v[54:57]
	v_mfma_f32_16x16x32_bf16 v[56:59], v[174:177], v[210:213], v[58:61]
	v_mfma_f32_16x16x32_bf16 v[102:105], v[170:173], v[190:193], v[102:105]
	v_mfma_f32_16x16x32_bf16 v[32:35], v[178:181], v[190:193], v[32:35]
	s_barrier
	v_mfma_f32_16x16x32_bf16 v[36:39], v[170:173], v[198:201], v[36:39]
	v_mfma_f32_16x16x32_bf16 v[40:43], v[178:181], v[198:201], v[40:43]
	v_mfma_f32_16x16x32_bf16 v[44:47], v[170:173], v[206:209], v[44:47]
	v_mfma_f32_16x16x32_bf16 v[52:55], v[170:173], v[220:223], v[52:55]
	v_mfma_f32_16x16x32_bf16 v[56:59], v[178:181], v[220:223], v[56:59]
	v_mfma_f32_16x16x32_bf16 v[48:51], v[178:181], v[206:209], v[48:51]
	s_setprio 0
	s_add_i32 s18, s35, s75
	s_add_i32 s35, s18, 0x2000
	v_lshl_add_u64 v[60:61], s[84:85], 0, v[134:135]
	s_mov_b32 m0, s18
	s_add_u32 s42, s84, 0x18000
	ds_read_b128 v[182:185], v157 offset:49152
	ds_read_b128 v[190:193], v157 offset:50176
	ds_read_b128 v[194:197], v157 offset:51200
	ds_read_b128 v[198:201], v157 offset:52224
	ds_read_b128 v[202:205], v157 offset:53248
	ds_read_b128 v[206:209], v157 offset:54272
	ds_read_b128 v[210:213], v157 offset:55296
	ds_read_b128 v[220:223], v157 offset:56320
	global_load_lds_dwordx4 v[60:61], off
	v_lshl_add_u64 v[60:61], s[84:85], 0, v[130:131]
	s_mov_b32 m0, s35
	s_addc_u32 s43, s85, 0
	s_add_i32 s19, s44, s75
	global_load_lds_dwordx4 v[60:61], off
	v_lshl_add_u64 v[60:61], s[42:43], 0, v[134:135]
	s_mov_b32 m0, s19
	s_add_i32 s84, s19, 0x2000
	global_load_lds_dwordx4 v[60:61], off
	v_lshl_add_u64 v[60:61], s[42:43], 0, v[130:131]
	s_mov_b32 m0, s84
	s_nop 0
	global_load_lds_dwordx4 v[60:61], off
	v_lshl_add_u64 v[60:61], s[82:83], 0, v[136:137]
	s_mov_b32 m0, s93
	s_nop 0
	global_load_lds_dwordx4 v[60:61], off
	v_lshl_add_u64 v[60:61], s[82:83], 0, v[132:133]
	s_mov_b32 m0, s94
	s_nop 0
	global_load_lds_dwordx4 v[60:61], off
	s_waitcnt vmcnt(8)
	s_waitcnt lgkmcnt(0)
	s_barrier
	s_setprio 1
	s_waitcnt lgkmcnt(0)
	v_mfma_f32_16x16x32_bf16 v[4:7], v[24:27], v[210:213], v[4:7]
	v_mfma_f32_16x16x32_bf16 v[8:11], v[122:125], v[210:213], v[8:11]
	v_mfma_f32_16x16x32_bf16 v[142:145], v[24:27], v[182:185], v[142:145]
	v_mfma_f32_16x16x32_bf16 v[146:149], v[122:125], v[182:185], v[146:149]
	v_mfma_f32_16x16x32_bf16 v[150:153], v[24:27], v[194:197], v[150:153]
	v_mfma_f32_16x16x32_bf16 v[158:161], v[122:125], v[194:197], v[158:161]
	v_mfma_f32_16x16x32_bf16 v[162:165], v[24:27], v[202:205], v[162:165]
	v_mfma_f32_16x16x32_bf16 v[166:169], v[122:125], v[202:205], v[166:169]
	v_mfma_f32_16x16x32_bf16 v[4:7], v[28:31], v[220:223], v[4:7]
	v_mfma_f32_16x16x32_bf16 v[8:11], v[126:129], v[220:223], v[8:11]
	v_mfma_f32_16x16x32_bf16 v[142:145], v[28:31], v[190:193], v[142:145]
	v_mfma_f32_16x16x32_bf16 v[146:149], v[126:129], v[190:193], v[146:149]
	v_mfma_f32_16x16x32_bf16 v[150:153], v[28:31], v[198:201], v[150:153]
	v_mfma_f32_16x16x32_bf16 v[158:161], v[126:129], v[198:201], v[158:161]
	v_mfma_f32_16x16x32_bf16 v[162:165], v[28:31], v[206:209], v[162:165]
	v_mfma_f32_16x16x32_bf16 v[166:169], v[126:129], v[206:209], v[166:169]
	v_mfma_f32_16x16x32_bf16 v[12:15], v[138:141], v[182:185], v[12:15]
	v_mfma_f32_16x16x32_bf16 v[24:27], v[174:177], v[182:185], v[62:65]
	v_mfma_f32_16x16x32_bf16 v[28:31], v[138:141], v[194:197], v[106:109]
	v_mfma_f32_16x16x32_bf16 v[60:63], v[174:177], v[194:197], v[110:113]
	v_mfma_f32_16x16x32_bf16 v[106:109], v[138:141], v[202:205], v[114:117]
	v_mfma_f32_16x16x32_bf16 v[110:113], v[174:177], v[202:205], v[118:121]
	v_mfma_f32_16x16x32_bf16 v[16:19], v[138:141], v[210:213], v[16:19]
	v_mfma_f32_16x16x32_bf16 v[20:23], v[174:177], v[210:213], v[20:23]
	v_mfma_f32_16x16x32_bf16 v[12:15], v[170:173], v[190:193], v[12:15]
	v_mfma_f32_16x16x32_bf16 v[24:27], v[178:181], v[190:193], v[24:27]
	s_barrier
	v_mfma_f32_16x16x32_bf16 v[28:31], v[170:173], v[198:201], v[28:31]
	v_mfma_f32_16x16x32_bf16 v[60:63], v[178:181], v[198:201], v[60:63]
	v_mfma_f32_16x16x32_bf16 v[106:109], v[170:173], v[206:209], v[106:109]
	v_mfma_f32_16x16x32_bf16 v[110:113], v[178:181], v[206:209], v[110:113]
	v_mfma_f32_16x16x32_bf16 v[16:19], v[170:173], v[220:223], v[16:19]
	v_mfma_f32_16x16x32_bf16 v[20:23], v[178:181], v[220:223], v[20:23]
	s_setprio 0
	s_add_u32 s44, s78, 0x200
	s_addc_u32 s45, s79, 0
	s_add_u32 s46, s76, 0x200
	s_addc_u32 s47, s77, 0
	s_add_u32 s78, s78, 0x280
	s_addc_u32 s79, s79, 0
	s_add_u32 s76, s76, 0x280
	s_addc_u32 s77, s77, 0
	s_mov_b64 s[42:43], s[78:79]
	ds_read_b128 v[114:117], v0
	ds_read_b128 v[118:121], v0 offset:1024
	ds_read_b128 v[122:125], v0 offset:2048
	ds_read_b128 v[126:129], v0 offset:3072
	ds_read_b128 v[138:141], v1
	ds_read_b128 v[170:173], v1 offset:1024
	ds_read_b128 v[174:177], v1 offset:2048
	ds_read_b128 v[178:181], v1 offset:3072
	s_add_u32 s80, s80, 0x18000
	s_addc_u32 s81, s81, 0
	s_mov_b32 m0, s88
	v_lshl_add_u64 v[64:65], s[80:81], 0, v[136:137]
	ds_read_b128 v[182:185], v157
	ds_read_b128 v[190:193], v157 offset:1024
	ds_read_b128 v[194:197], v157 offset:2048
	ds_read_b128 v[198:201], v157 offset:3072
	ds_read_b128 v[202:205], v157 offset:4096
	ds_read_b128 v[206:209], v157 offset:5120
	ds_read_b128 v[210:213], v157 offset:6144
	ds_read_b128 v[220:223], v157 offset:7168
	global_load_lds_dwordx4 v[64:65], off
	v_lshl_add_u64 v[64:65], s[80:81], 0, v[132:133]
	s_mov_b32 m0, vcc_lo
	s_nop 0
	global_load_lds_dwordx4 v[64:65], off
	s_waitcnt vmcnt(8)
	s_waitcnt lgkmcnt(0)
	s_barrier
	s_setprio 1
	s_waitcnt lgkmcnt(0)
	v_mfma_f32_16x16x32_bf16 v[64:67], v[114:117], v[182:185], v[66:69]
	v_mfma_f32_16x16x32_bf16 v[68:71], v[122:125], v[182:185], v[70:73]
	v_mfma_f32_16x16x32_bf16 v[72:75], v[114:117], v[194:197], v[74:77]
	v_mfma_f32_16x16x32_bf16 v[76:79], v[122:125], v[194:197], v[78:81]
	v_mfma_f32_16x16x32_bf16 v[80:83], v[114:117], v[202:205], v[82:85]
	v_mfma_f32_16x16x32_bf16 v[84:87], v[122:125], v[202:205], v[86:89]
	v_mfma_f32_16x16x32_bf16 v[88:91], v[114:117], v[210:213], v[90:93]
	v_mfma_f32_16x16x32_bf16 v[92:95], v[122:125], v[210:213], v[98:101]
	v_mfma_f32_16x16x32_bf16 v[64:67], v[118:121], v[190:193], v[64:67]
	v_mfma_f32_16x16x32_bf16 v[68:71], v[126:129], v[190:193], v[68:71]
	v_mfma_f32_16x16x32_bf16 v[72:75], v[118:121], v[198:201], v[72:75]
	v_mfma_f32_16x16x32_bf16 v[76:79], v[126:129], v[198:201], v[76:79]
	v_mfma_f32_16x16x32_bf16 v[80:83], v[118:121], v[206:209], v[80:83]
	v_mfma_f32_16x16x32_bf16 v[84:87], v[126:129], v[206:209], v[84:87]
	v_mfma_f32_16x16x32_bf16 v[88:91], v[118:121], v[220:223], v[88:91]
	v_mfma_f32_16x16x32_bf16 v[92:95], v[126:129], v[220:223], v[92:95]
	v_mfma_f32_16x16x32_bf16 v[98:101], v[138:141], v[182:185], v[102:105]
	v_mfma_f32_16x16x32_bf16 v[32:35], v[174:177], v[182:185], v[32:35]
	v_mfma_f32_16x16x32_bf16 v[36:39], v[138:141], v[194:197], v[36:39]
	v_mfma_f32_16x16x32_bf16 v[40:43], v[174:177], v[194:197], v[40:43]
	v_mfma_f32_16x16x32_bf16 v[44:47], v[138:141], v[202:205], v[44:47]
	v_mfma_f32_16x16x32_bf16 v[52:55], v[138:141], v[210:213], v[52:55]
	v_mfma_f32_16x16x32_bf16 v[56:59], v[174:177], v[210:213], v[56:59]
	v_mfma_f32_16x16x32_bf16 v[98:101], v[170:173], v[190:193], v[98:101]
	v_mfma_f32_16x16x32_bf16 v[32:35], v[178:181], v[190:193], v[32:35]
	v_mfma_f32_16x16x32_bf16 v[36:39], v[170:173], v[198:201], v[36:39]
	s_barrier
	v_mfma_f32_16x16x32_bf16 v[40:43], v[178:181], v[198:201], v[40:43]
	v_mfma_f32_16x16x32_bf16 v[44:47], v[170:173], v[206:209], v[44:47]
	v_mfma_f32_16x16x32_bf16 v[48:51], v[174:177], v[202:205], v[48:51]
	v_mfma_f32_16x16x32_bf16 v[52:55], v[170:173], v[220:223], v[52:55]
	v_mfma_f32_16x16x32_bf16 v[56:59], v[178:181], v[220:223], v[56:59]
	v_mfma_f32_16x16x32_bf16 v[48:51], v[178:181], v[206:209], v[48:51]
	s_setprio 0
	s_mov_b32 m0, vcc_hi
	v_lshl_add_u64 v[186:187], s[46:47], 0, v[134:135]
	ds_read_b128 v[102:105], v157 offset:16384
	ds_read_b128 v[182:185], v157 offset:17408
	ds_read_b128 v[190:193], v157 offset:18432
	ds_read_b128 v[194:197], v157 offset:19456
	ds_read_b128 v[198:201], v157 offset:20480
	ds_read_b128 v[202:205], v157 offset:21504
	ds_read_b128 v[206:209], v157 offset:22528
	ds_read_b128 v[210:213], v157 offset:23552
	global_load_lds_dwordx4 v[186:187], off
	v_lshl_add_u64 v[186:187], s[46:47], 0, v[130:131]
	s_add_u32 s46, s46, 0x18000
	s_mov_b32 m0, s70
	s_addc_u32 s47, s47, 0
	global_load_lds_dwordx4 v[186:187], off
	v_lshl_add_u64 v[186:187], s[46:47], 0, v[134:135]
	s_mov_b32 m0, s22
	s_nop 0
	global_load_lds_dwordx4 v[186:187], off
	v_lshl_add_u64 v[186:187], s[46:47], 0, v[130:131]
	s_mov_b32 m0, s23
	s_nop 0
	global_load_lds_dwordx4 v[186:187], off
	v_lshl_add_u64 v[186:187], s[44:45], 0, v[136:137]
	s_mov_b32 m0, s49
	s_nop 0
	global_load_lds_dwordx4 v[186:187], off
	v_lshl_add_u64 v[186:187], s[44:45], 0, v[132:133]
	s_mov_b32 m0, s89
	s_nop 0
	global_load_lds_dwordx4 v[186:187], off
	s_waitcnt vmcnt(8)
	s_waitcnt lgkmcnt(0)
	s_barrier
	s_setprio 1
	s_waitcnt lgkmcnt(0)
	v_mfma_f32_16x16x32_bf16 v[4:7], v[114:117], v[206:209], v[4:7]
	v_mfma_f32_16x16x32_bf16 v[8:11], v[122:125], v[206:209], v[8:11]
	v_mfma_f32_16x16x32_bf16 v[142:145], v[114:117], v[102:105], v[142:145]
	v_mfma_f32_16x16x32_bf16 v[146:149], v[122:125], v[102:105], v[146:149]
	v_mfma_f32_16x16x32_bf16 v[150:153], v[114:117], v[190:193], v[150:153]
	v_mfma_f32_16x16x32_bf16 v[158:161], v[122:125], v[190:193], v[158:161]
	v_mfma_f32_16x16x32_bf16 v[162:165], v[114:117], v[198:201], v[162:165]
	v_mfma_f32_16x16x32_bf16 v[166:169], v[122:125], v[198:201], v[166:169]
	v_mfma_f32_16x16x32_bf16 v[4:7], v[118:121], v[210:213], v[4:7]
	v_mfma_f32_16x16x32_bf16 v[8:11], v[126:129], v[210:213], v[8:11]
	v_mfma_f32_16x16x32_bf16 v[142:145], v[118:121], v[182:185], v[142:145]
	v_mfma_f32_16x16x32_bf16 v[146:149], v[126:129], v[182:185], v[146:149]
	v_mfma_f32_16x16x32_bf16 v[150:153], v[118:121], v[194:197], v[150:153]
	v_mfma_f32_16x16x32_bf16 v[158:161], v[126:129], v[194:197], v[158:161]
	v_mfma_f32_16x16x32_bf16 v[162:165], v[118:121], v[202:205], v[162:165]
	v_mfma_f32_16x16x32_bf16 v[166:169], v[126:129], v[202:205], v[166:169]
	v_mfma_f32_16x16x32_bf16 v[12:15], v[138:141], v[102:105], v[12:15]
	v_mfma_f32_16x16x32_bf16 v[24:27], v[174:177], v[102:105], v[24:27]
	v_mfma_f32_16x16x32_bf16 v[28:31], v[138:141], v[190:193], v[28:31]
	v_mfma_f32_16x16x32_bf16 v[60:63], v[174:177], v[190:193], v[60:63]
	v_mfma_f32_16x16x32_bf16 v[102:105], v[138:141], v[198:201], v[106:109]
	v_mfma_f32_16x16x32_bf16 v[106:109], v[174:177], v[198:201], v[110:113]
	v_mfma_f32_16x16x32_bf16 v[16:19], v[138:141], v[206:209], v[16:19]
	v_mfma_f32_16x16x32_bf16 v[20:23], v[174:177], v[206:209], v[20:23]
	v_mfma_f32_16x16x32_bf16 v[12:15], v[170:173], v[182:185], v[12:15]
	v_mfma_f32_16x16x32_bf16 v[24:27], v[178:181], v[182:185], v[24:27]
	s_barrier
	v_mfma_f32_16x16x32_bf16 v[28:31], v[170:173], v[194:197], v[28:31]
	v_mfma_f32_16x16x32_bf16 v[60:63], v[178:181], v[194:197], v[60:63]
	v_mfma_f32_16x16x32_bf16 v[102:105], v[170:173], v[202:205], v[102:105]
	v_mfma_f32_16x16x32_bf16 v[106:109], v[178:181], v[202:205], v[106:109]
	v_mfma_f32_16x16x32_bf16 v[16:19], v[170:173], v[210:213], v[16:19]
	v_mfma_f32_16x16x32_bf16 v[20:23], v[178:181], v[210:213], v[20:23]
	s_setprio 0
	ds_read_b128 v[110:113], v2
	ds_read_b128 v[114:117], v2 offset:1024
	ds_read_b128 v[118:121], v2 offset:2048
	ds_read_b128 v[122:125], v2 offset:3072
	ds_read_b128 v[126:129], v3
	ds_read_b128 v[138:141], v3 offset:1024
	ds_read_b128 v[170:173], v3 offset:2048
	ds_read_b128 v[174:177], v3 offset:3072
	s_add_u32 s44, s44, 0x18000
	s_addc_u32 s45, s45, 0
	s_mov_b32 m0, s90
	v_lshl_add_u64 v[186:187], s[44:45], 0, v[136:137]
	ds_read_b128 v[178:181], v157 offset:32768
	ds_read_b128 v[182:185], v157 offset:33792
	ds_read_b128 v[190:193], v157 offset:34816
	ds_read_b128 v[194:197], v157 offset:35840
	ds_read_b128 v[198:201], v157 offset:36864
	ds_read_b128 v[202:205], v157 offset:37888
	ds_read_b128 v[206:209], v157 offset:38912
	ds_read_b128 v[210:213], v157 offset:39936
	global_load_lds_dwordx4 v[186:187], off
	v_lshl_add_u64 v[186:187], s[44:45], 0, v[132:133]
	s_mov_b32 m0, s91
	s_nop 0
	global_load_lds_dwordx4 v[186:187], off
	s_waitcnt vmcnt(8)
	s_waitcnt lgkmcnt(0)
	s_barrier
	s_setprio 1
	s_waitcnt lgkmcnt(0)
	v_mfma_f32_16x16x32_bf16 v[64:67], v[110:113], v[178:181], v[64:67]
	v_mfma_f32_16x16x32_bf16 v[68:71], v[118:121], v[178:181], v[68:71]
	v_mfma_f32_16x16x32_bf16 v[72:75], v[110:113], v[190:193], v[72:75]
	v_mfma_f32_16x16x32_bf16 v[76:79], v[118:121], v[190:193], v[76:79]
	v_mfma_f32_16x16x32_bf16 v[80:83], v[110:113], v[198:201], v[80:83]
	v_mfma_f32_16x16x32_bf16 v[84:87], v[118:121], v[198:201], v[84:87]
	v_mfma_f32_16x16x32_bf16 v[88:91], v[110:113], v[206:209], v[88:91]
	v_mfma_f32_16x16x32_bf16 v[92:95], v[118:121], v[206:209], v[92:95]
	v_mfma_f32_16x16x32_bf16 v[64:67], v[114:117], v[182:185], v[64:67]
	v_mfma_f32_16x16x32_bf16 v[68:71], v[122:125], v[182:185], v[68:71]
	v_mfma_f32_16x16x32_bf16 v[72:75], v[114:117], v[194:197], v[72:75]
	v_mfma_f32_16x16x32_bf16 v[76:79], v[122:125], v[194:197], v[76:79]
	v_mfma_f32_16x16x32_bf16 v[80:83], v[114:117], v[202:205], v[80:83]
	v_mfma_f32_16x16x32_bf16 v[84:87], v[122:125], v[202:205], v[84:87]
	v_mfma_f32_16x16x32_bf16 v[88:91], v[114:117], v[210:213], v[88:91]
	v_mfma_f32_16x16x32_bf16 v[92:95], v[122:125], v[210:213], v[92:95]
	v_mfma_f32_16x16x32_bf16 v[98:101], v[126:129], v[178:181], v[98:101]
	v_mfma_f32_16x16x32_bf16 v[32:35], v[170:173], v[178:181], v[32:35]
	v_mfma_f32_16x16x32_bf16 v[36:39], v[126:129], v[190:193], v[36:39]
	v_mfma_f32_16x16x32_bf16 v[40:43], v[170:173], v[190:193], v[40:43]
	v_mfma_f32_16x16x32_bf16 v[44:47], v[126:129], v[198:201], v[44:47]
	v_mfma_f32_16x16x32_bf16 v[52:55], v[126:129], v[206:209], v[52:55]
	v_mfma_f32_16x16x32_bf16 v[56:59], v[170:173], v[206:209], v[56:59]
	v_mfma_f32_16x16x32_bf16 v[98:101], v[138:141], v[182:185], v[98:101]
	v_mfma_f32_16x16x32_bf16 v[32:35], v[174:177], v[182:185], v[32:35]
	v_mfma_f32_16x16x32_bf16 v[36:39], v[138:141], v[194:197], v[36:39]
	s_barrier
	v_mfma_f32_16x16x32_bf16 v[40:43], v[174:177], v[194:197], v[40:43]
	v_mfma_f32_16x16x32_bf16 v[44:47], v[138:141], v[202:205], v[44:47]
	v_mfma_f32_16x16x32_bf16 v[48:51], v[170:173], v[198:201], v[48:51]
	v_mfma_f32_16x16x32_bf16 v[52:55], v[138:141], v[210:213], v[52:55]
	v_mfma_f32_16x16x32_bf16 v[56:59], v[174:177], v[210:213], v[56:59]
	v_mfma_f32_16x16x32_bf16 v[48:51], v[174:177], v[202:205], v[48:51]
	s_setprio 0
	s_mov_b32 m0, s18
	v_lshl_add_u64 v[186:187], s[76:77], 0, v[134:135]
	s_add_u32 s44, s76, 0x18000
	ds_read_b128 v[178:181], v157 offset:49152
	ds_read_b128 v[182:185], v157 offset:50176
	ds_read_b128 v[190:193], v157 offset:51200
	ds_read_b128 v[194:197], v157 offset:52224
	ds_read_b128 v[198:201], v157 offset:53248
	ds_read_b128 v[202:205], v157 offset:54272
	ds_read_b128 v[206:209], v157 offset:55296
	ds_read_b128 v[210:213], v157 offset:56320
	global_load_lds_dwordx4 v[186:187], off
	v_lshl_add_u64 v[186:187], s[76:77], 0, v[130:131]
	s_mov_b32 m0, s35
	s_addc_u32 s45, s77, 0
	global_load_lds_dwordx4 v[186:187], off
	v_lshl_add_u64 v[186:187], s[44:45], 0, v[134:135]
	s_mov_b32 m0, s19
	s_nop 0
	global_load_lds_dwordx4 v[186:187], off
	v_lshl_add_u64 v[186:187], s[44:45], 0, v[130:131]
	s_mov_b32 m0, s84
	s_nop 0
	global_load_lds_dwordx4 v[186:187], off
	v_lshl_add_u64 v[186:187], s[42:43], 0, v[136:137]
	s_mov_b32 m0, s93
	s_nop 0
	global_load_lds_dwordx4 v[186:187], off
	v_lshl_add_u64 v[186:187], s[42:43], 0, v[132:133]
	s_mov_b32 m0, s94
	s_nop 0
	global_load_lds_dwordx4 v[186:187], off
	s_waitcnt vmcnt(8)
	s_waitcnt lgkmcnt(0)
	s_barrier
	s_setprio 1
	s_waitcnt lgkmcnt(0)
	v_mfma_f32_16x16x32_bf16 v[4:7], v[110:113], v[206:209], v[4:7]
	v_mfma_f32_16x16x32_bf16 v[8:11], v[118:121], v[206:209], v[8:11]
	v_mfma_f32_16x16x32_bf16 v[142:145], v[110:113], v[178:181], v[142:145]
	v_mfma_f32_16x16x32_bf16 v[146:149], v[118:121], v[178:181], v[146:149]
	v_mfma_f32_16x16x32_bf16 v[150:153], v[110:113], v[190:193], v[150:153]
	v_mfma_f32_16x16x32_bf16 v[158:161], v[118:121], v[190:193], v[158:161]
	v_mfma_f32_16x16x32_bf16 v[162:165], v[110:113], v[198:201], v[162:165]
	v_mfma_f32_16x16x32_bf16 v[166:169], v[118:121], v[198:201], v[166:169]
	v_mfma_f32_16x16x32_bf16 v[4:7], v[114:117], v[210:213], v[4:7]
	v_mfma_f32_16x16x32_bf16 v[8:11], v[122:125], v[210:213], v[8:11]
	v_mfma_f32_16x16x32_bf16 v[142:145], v[114:117], v[182:185], v[142:145]
	v_mfma_f32_16x16x32_bf16 v[146:149], v[122:125], v[182:185], v[146:149]
	v_mfma_f32_16x16x32_bf16 v[150:153], v[114:117], v[194:197], v[150:153]
	v_mfma_f32_16x16x32_bf16 v[158:161], v[122:125], v[194:197], v[158:161]
	v_mfma_f32_16x16x32_bf16 v[162:165], v[114:117], v[202:205], v[162:165]
	v_mfma_f32_16x16x32_bf16 v[166:169], v[122:125], v[202:205], v[166:169]
	v_mfma_f32_16x16x32_bf16 v[12:15], v[126:129], v[178:181], v[12:15]
	v_mfma_f32_16x16x32_bf16 v[24:27], v[170:173], v[178:181], v[24:27]
	v_mfma_f32_16x16x32_bf16 v[28:31], v[126:129], v[190:193], v[28:31]
	v_mfma_f32_16x16x32_bf16 v[60:63], v[170:173], v[190:193], v[60:63]
	v_mfma_f32_16x16x32_bf16 v[102:105], v[126:129], v[198:201], v[102:105]
	v_mfma_f32_16x16x32_bf16 v[106:109], v[170:173], v[198:201], v[106:109]
	v_mfma_f32_16x16x32_bf16 v[16:19], v[126:129], v[206:209], v[16:19]
	v_mfma_f32_16x16x32_bf16 v[20:23], v[170:173], v[206:209], v[20:23]
	v_mfma_f32_16x16x32_bf16 v[12:15], v[138:141], v[182:185], v[12:15]
	v_mfma_f32_16x16x32_bf16 v[24:27], v[174:177], v[182:185], v[24:27]
	s_barrier
	v_mfma_f32_16x16x32_bf16 v[28:31], v[138:141], v[194:197], v[28:31]
	v_mfma_f32_16x16x32_bf16 v[60:63], v[174:177], v[194:197], v[60:63]
	v_mfma_f32_16x16x32_bf16 v[102:105], v[138:141], v[202:205], v[102:105]
	v_mfma_f32_16x16x32_bf16 v[106:109], v[174:177], v[202:205], v[106:109]
	v_mfma_f32_16x16x32_bf16 v[16:19], v[138:141], v[210:213], v[16:19]
	v_mfma_f32_16x16x32_bf16 v[20:23], v[174:177], v[210:213], v[20:23]
	s_setprio 0
	s_add_u32 s76, s38, 0x80
	s_addc_u32 s77, s39, 0
	s_add_u32 s42, s68, 0x80
	s_addc_u32 s43, s69, 0
	ds_read_b128 v[110:113], v0
	ds_read_b128 v[114:117], v0 offset:1024
	ds_read_b128 v[118:121], v0 offset:2048
	ds_read_b128 v[122:125], v0 offset:3072
	ds_read_b128 v[126:129], v1
	ds_read_b128 v[138:141], v1 offset:1024
	ds_read_b128 v[170:173], v1 offset:2048
	ds_read_b128 v[174:177], v1 offset:3072
	s_add_u32 s44, s78, 0x18000
	s_addc_u32 s45, s79, 0
	s_mov_b32 m0, s88
	v_lshl_add_u64 v[0:1], s[44:45], 0, v[136:137]
	ds_read_b128 v[178:181], v157
	ds_read_b128 v[182:185], v157 offset:1024
	ds_read_b128 v[190:193], v157 offset:2048
	ds_read_b128 v[194:197], v157 offset:3072
	ds_read_b128 v[198:201], v157 offset:4096
	ds_read_b128 v[202:205], v157 offset:5120
	ds_read_b128 v[206:209], v157 offset:6144
	ds_read_b128 v[210:213], v157 offset:7168
	global_load_lds_dwordx4 v[0:1], off
	v_lshl_add_u64 v[0:1], s[44:45], 0, v[132:133]
	s_mov_b32 m0, vcc_lo
	s_nop 0
	global_load_lds_dwordx4 v[0:1], off
	s_waitcnt vmcnt(8)
	s_waitcnt lgkmcnt(0)
	s_barrier
	s_setprio 1
	s_waitcnt lgkmcnt(0)
	v_mfma_f32_16x16x32_bf16 v[88:91], v[110:113], v[206:209], v[88:91]
	v_mfma_f32_16x16x32_bf16 v[64:67], v[110:113], v[178:181], v[64:67]
	v_mfma_f32_16x16x32_bf16 v[68:71], v[118:121], v[178:181], v[68:71]
	v_mfma_f32_16x16x32_bf16 v[72:75], v[110:113], v[190:193], v[72:75]
	v_mfma_f32_16x16x32_bf16 v[76:79], v[118:121], v[190:193], v[76:79]
	v_mfma_f32_16x16x32_bf16 v[80:83], v[110:113], v[198:201], v[80:83]
	v_mfma_f32_16x16x32_bf16 v[84:87], v[118:121], v[198:201], v[84:87]
	v_mfma_f32_16x16x32_bf16 v[220:223], v[114:117], v[210:213], v[88:91]
	v_mfma_f32_16x16x32_bf16 v[88:91], v[118:121], v[206:209], v[92:95]
	v_mfma_f32_16x16x32_bf16 v[64:67], v[114:117], v[182:185], v[64:67]
	v_mfma_f32_16x16x32_bf16 v[68:71], v[122:125], v[182:185], v[68:71]
	v_mfma_f32_16x16x32_bf16 v[72:75], v[114:117], v[194:197], v[72:75]
	v_mfma_f32_16x16x32_bf16 v[76:79], v[122:125], v[194:197], v[76:79]
	v_mfma_f32_16x16x32_bf16 v[80:83], v[114:117], v[202:205], v[80:83]
	v_mfma_f32_16x16x32_bf16 v[84:87], v[122:125], v[202:205], v[84:87]
	v_mfma_f32_16x16x32_bf16 v[92:95], v[122:125], v[210:213], v[88:91]
	v_mfma_f32_16x16x32_bf16 v[48:51], v[170:173], v[198:201], v[48:51]
	v_mfma_f32_16x16x32_bf16 v[88:91], v[126:129], v[178:181], v[98:101]
	v_mfma_f32_16x16x32_bf16 v[32:35], v[170:173], v[178:181], v[32:35]
	v_mfma_f32_16x16x32_bf16 v[36:39], v[126:129], v[190:193], v[36:39]
	v_mfma_f32_16x16x32_bf16 v[40:43], v[170:173], v[190:193], v[40:43]
	v_mfma_f32_16x16x32_bf16 v[44:47], v[126:129], v[198:201], v[44:47]
	v_mfma_f32_16x16x32_bf16 v[178:181], v[174:177], v[202:205], v[48:51]
	v_mfma_f32_16x16x32_bf16 v[48:51], v[126:129], v[206:209], v[52:55]
	v_mfma_f32_16x16x32_bf16 v[32:35], v[174:177], v[182:185], v[32:35]
	v_mfma_f32_16x16x32_bf16 v[36:39], v[138:141], v[194:197], v[36:39]
	s_barrier
	v_mfma_f32_16x16x32_bf16 v[40:43], v[174:177], v[194:197], v[40:43]
	v_mfma_f32_16x16x32_bf16 v[44:47], v[138:141], v[202:205], v[44:47]
	v_mfma_f32_16x16x32_bf16 v[52:55], v[138:141], v[210:213], v[48:51]
	v_mfma_f32_16x16x32_bf16 v[48:51], v[170:173], v[206:209], v[56:59]
	v_mfma_f32_16x16x32_bf16 v[224:227], v[138:141], v[182:185], v[88:91]
	v_mfma_f32_16x16x32_bf16 v[182:185], v[174:177], v[210:213], v[48:51]
	s_setprio 0
	s_mov_b32 m0, vcc_hi
	v_lshl_add_u64 v[0:1], s[68:69], 0, v[134:135]
	s_add_u32 s44, s68, 0x18000
	s_nop 0
	ds_read_b128 v[48:51], v157 offset:16384
	ds_read_b128 v[56:59], v157 offset:17408
	ds_read_b128 v[88:91], v157 offset:18432
	ds_read_b128 v[98:101], v157 offset:19456
	ds_read_b128 v[190:193], v157 offset:20480
	ds_read_b128 v[194:197], v157 offset:21504
	ds_read_b128 v[198:201], v157 offset:22528
	ds_read_b128 v[202:205], v157 offset:23552
	global_load_lds_dwordx4 v[0:1], off
	v_lshl_add_u64 v[0:1], s[68:69], 0, v[130:131]
	s_mov_b32 m0, s70
	s_addc_u32 s45, s69, 0
	global_load_lds_dwordx4 v[0:1], off
	v_lshl_add_u64 v[0:1], s[44:45], 0, v[134:135]
	s_mov_b32 m0, s22
	s_nop 0
	global_load_lds_dwordx4 v[0:1], off
	v_lshl_add_u64 v[0:1], s[44:45], 0, v[130:131]
	s_mov_b32 m0, s23
	s_nop 0
	global_load_lds_dwordx4 v[0:1], off
	v_lshl_add_u64 v[0:1], s[38:39], 0, v[136:137]
	s_mov_b32 m0, s49
	s_nop 0
	global_load_lds_dwordx4 v[0:1], off
	v_lshl_add_u64 v[0:1], s[38:39], 0, v[132:133]
	s_mov_b32 m0, s89
	s_nop 0
	global_load_lds_dwordx4 v[0:1], off
	s_waitcnt vmcnt(8)
	s_waitcnt lgkmcnt(0)
	s_barrier
	s_setprio 1
	s_waitcnt lgkmcnt(0)
	v_mfma_f32_16x16x32_bf16 v[4:7], v[110:113], v[198:201], v[4:7]
	v_mfma_f32_16x16x32_bf16 v[142:145], v[110:113], v[48:51], v[142:145]
	v_mfma_f32_16x16x32_bf16 v[146:149], v[118:121], v[48:51], v[146:149]
	v_mfma_f32_16x16x32_bf16 v[150:153], v[110:113], v[88:91], v[150:153]
	v_mfma_f32_16x16x32_bf16 v[158:161], v[118:121], v[88:91], v[158:161]
	v_mfma_f32_16x16x32_bf16 v[162:165], v[110:113], v[190:193], v[162:165]
	v_mfma_f32_16x16x32_bf16 v[166:169], v[118:121], v[190:193], v[166:169]
	v_mfma_f32_16x16x32_bf16 v[4:7], v[114:117], v[202:205], v[4:7]
	v_mfma_f32_16x16x32_bf16 v[8:11], v[118:121], v[198:201], v[8:11]
	v_mfma_f32_16x16x32_bf16 v[142:145], v[114:117], v[56:59], v[142:145]
	v_mfma_f32_16x16x32_bf16 v[146:149], v[122:125], v[56:59], v[146:149]
	v_mfma_f32_16x16x32_bf16 v[150:153], v[114:117], v[98:101], v[150:153]
	v_mfma_f32_16x16x32_bf16 v[158:161], v[122:125], v[98:101], v[158:161]
	v_mfma_f32_16x16x32_bf16 v[162:165], v[114:117], v[194:197], v[162:165]
	v_mfma_f32_16x16x32_bf16 v[166:169], v[122:125], v[194:197], v[166:169]
	v_mfma_f32_16x16x32_bf16 v[206:209], v[122:125], v[202:205], v[8:11]
	v_mfma_f32_16x16x32_bf16 v[8:11], v[126:129], v[48:51], v[12:15]
	v_mfma_f32_16x16x32_bf16 v[12:15], v[138:141], v[56:59], v[8:11]
	v_mfma_f32_16x16x32_bf16 v[8:11], v[170:173], v[48:51], v[24:27]
	v_mfma_f32_16x16x32_bf16 v[210:213], v[174:177], v[56:59], v[8:11]
	v_mfma_f32_16x16x32_bf16 v[8:11], v[126:129], v[88:91], v[28:31]
	v_mfma_f32_16x16x32_bf16 v[28:31], v[138:141], v[98:101], v[8:11]
	v_mfma_f32_16x16x32_bf16 v[8:11], v[170:173], v[88:91], v[60:63]
	v_mfma_f32_16x16x32_bf16 v[228:231], v[174:177], v[98:101], v[8:11]
	v_mfma_f32_16x16x32_bf16 v[8:11], v[126:129], v[190:193], v[102:105]
	v_mfma_f32_16x16x32_bf16 v[232:235], v[138:141], v[194:197], v[8:11]
	s_barrier
	v_mfma_f32_16x16x32_bf16 v[8:11], v[170:173], v[190:193], v[106:109]
	v_mfma_f32_16x16x32_bf16 v[190:193], v[174:177], v[194:197], v[8:11]
	v_mfma_f32_16x16x32_bf16 v[8:11], v[126:129], v[198:201], v[16:19]
	v_mfma_f32_16x16x32_bf16 v[138:141], v[138:141], v[202:205], v[8:11]
	v_mfma_f32_16x16x32_bf16 v[8:11], v[170:173], v[198:201], v[20:23]
	v_mfma_f32_16x16x32_bf16 v[170:173], v[174:177], v[202:205], v[8:11]
	s_setprio 0
	s_nop 4
	ds_read_b128 v[8:11], v2
	ds_read_b128 v[20:23], v2 offset:1024
	ds_read_b128 v[174:177], v2 offset:2048
	ds_read_b128 v[194:197], v2 offset:3072
	ds_read_b128 v[198:201], v3
	ds_read_b128 v[202:205], v3 offset:1024
	ds_read_b128 v[236:239], v3 offset:2048
	ds_read_b128 v[240:243], v3 offset:3072
	s_add_u32 s22, s38, 0x18000
	s_addc_u32 s23, s39, 0
	s_mov_b32 m0, s90
	v_lshl_add_u64 v[56:57], s[22:23], 0, v[136:137]
	ds_read_b128 v[0:3], v157 offset:32768
	ds_read_b128 v[16:19], v157 offset:33792
	ds_read_b128 v[24:27], v157 offset:34816
	ds_read_b128 v[60:63], v157 offset:35840
	ds_read_b128 v[244:247], v157 offset:36864
	ds_read_b128 v[248:251], v157 offset:37888
	ds_read_b128 v[186:189], v157 offset:38912
	ds_read_b128 v[48:51], v157 offset:39936
	global_load_lds_dwordx4 v[56:57], off
	v_lshl_add_u64 v[56:57], s[22:23], 0, v[132:133]
	s_mov_b32 m0, s91
	s_nop 0
	global_load_lds_dwordx4 v[56:57], off
	s_waitcnt vmcnt(8)
	s_waitcnt lgkmcnt(0)
	s_barrier
	s_setprio 1
	s_waitcnt lgkmcnt(0)
	v_mfma_f32_16x16x32_bf16 v[56:59], v[8:11], v[0:3], v[64:67]
	v_mfma_f32_16x16x32_bf16 v[122:125], v[20:23], v[16:19], v[56:59]
	v_mfma_f32_16x16x32_bf16 v[56:59], v[174:177], v[0:3], v[68:71]
	v_mfma_f32_16x16x32_bf16 v[114:117], v[194:197], v[16:19], v[56:59]
	v_mfma_f32_16x16x32_bf16 v[56:59], v[8:11], v[24:27], v[72:75]
	v_mfma_f32_16x16x32_bf16 v[106:109], v[20:23], v[60:63], v[56:59]
	v_mfma_f32_16x16x32_bf16 v[56:59], v[174:177], v[24:27], v[76:79]
	v_mfma_f32_16x16x32_bf16 v[98:101], v[194:197], v[60:63], v[56:59]
	v_mfma_f32_16x16x32_bf16 v[56:59], v[8:11], v[244:247], v[80:83]
	v_mfma_f32_16x16x32_bf16 v[88:91], v[20:23], v[248:251], v[56:59]
	v_mfma_f32_16x16x32_bf16 v[56:59], v[174:177], v[244:247], v[84:87]
	v_mfma_f32_16x16x32_bf16 v[80:83], v[194:197], v[248:251], v[56:59]
	v_mfma_f32_16x16x32_bf16 v[56:59], v[8:11], v[186:189], v[220:223]
	v_mfma_f32_16x16x32_bf16 v[64:67], v[174:177], v[186:189], v[92:95]
	v_mfma_f32_16x16x32_bf16 v[56:59], v[20:23], v[48:51], v[56:59]
	v_mfma_f32_16x16x32_bf16 v[220:223], v[194:197], v[48:51], v[64:67]
	v_mfma_f32_16x16x32_bf16 v[64:67], v[198:201], v[0:3], v[224:227]
	v_mfma_f32_16x16x32_bf16 v[0:3], v[236:239], v[0:3], v[32:35]
	v_mfma_f32_16x16x32_bf16 v[118:121], v[240:243], v[16:19], v[0:3]
	v_mfma_f32_16x16x32_bf16 v[0:3], v[198:201], v[24:27], v[36:39]
	v_mfma_f32_16x16x32_bf16 v[110:113], v[202:205], v[60:63], v[0:3]
	v_mfma_f32_16x16x32_bf16 v[0:3], v[236:239], v[24:27], v[40:43]
	v_mfma_f32_16x16x32_bf16 v[102:105], v[240:243], v[60:63], v[0:3]
	v_mfma_f32_16x16x32_bf16 v[0:3], v[198:201], v[244:247], v[44:47]
	v_mfma_f32_16x16x32_bf16 v[92:95], v[202:205], v[248:251], v[0:3]
	v_mfma_f32_16x16x32_bf16 v[0:3], v[236:239], v[244:247], v[178:181]
	s_barrier
	v_mfma_f32_16x16x32_bf16 v[84:87], v[240:243], v[248:251], v[0:3]
	v_mfma_f32_16x16x32_bf16 v[0:3], v[198:201], v[186:189], v[52:55]
	v_mfma_f32_16x16x32_bf16 v[60:63], v[202:205], v[48:51], v[0:3]
	v_mfma_f32_16x16x32_bf16 v[0:3], v[236:239], v[186:189], v[182:185]
	v_mfma_f32_16x16x32_bf16 v[126:129], v[202:205], v[16:19], v[64:67]
	v_mfma_f32_16x16x32_bf16 v[52:55], v[240:243], v[48:51], v[0:3]
	s_setprio 0
	s_mov_b32 m0, s18
	s_nop 2
	v_lshl_add_u64 v[0:1], s[42:43], 0, v[134:135]
	s_add_u32 s22, s42, 0x18000
	ds_read_b128 v[36:39], v157 offset:49152
	ds_read_b128 v[44:47], v157 offset:50176
	ds_read_b128 v[48:51], v157 offset:51200
	ds_read_b128 v[178:181], v157 offset:52224
	ds_read_b128 v[182:185], v157 offset:53248
	ds_read_b128 v[186:189], v157 offset:54272
	ds_read_b128 v[224:227], v157 offset:55296
	ds_read_b128 v[244:247], v157 offset:56320
	global_load_lds_dwordx4 v[0:1], off
	v_lshl_add_u64 v[0:1], s[42:43], 0, v[130:131]
	s_mov_b32 m0, s35
	s_addc_u32 s23, s43, 0
	global_load_lds_dwordx4 v[0:1], off
	v_lshl_add_u64 v[0:1], s[22:23], 0, v[134:135]
	s_mov_b32 m0, s19
	s_nop 0
	global_load_lds_dwordx4 v[0:1], off
	v_lshl_add_u64 v[0:1], s[22:23], 0, v[130:131]
	s_mov_b32 m0, s84
	s_nop 0
	global_load_lds_dwordx4 v[0:1], off
	v_lshl_add_u64 v[0:1], s[76:77], 0, v[136:137]
	s_mov_b32 m0, s93
	s_nop 0
	global_load_lds_dwordx4 v[0:1], off
	v_lshl_add_u64 v[0:1], s[76:77], 0, v[132:133]
	s_mov_b32 m0, s94
	s_nop 0
	global_load_lds_dwordx4 v[0:1], off
	s_waitcnt vmcnt(8)
	s_waitcnt lgkmcnt(0)
	s_barrier
	s_setprio 1
	s_waitcnt lgkmcnt(0)
	v_mfma_f32_16x16x32_bf16 v[0:3], v[8:11], v[36:39], v[142:145]
	v_mfma_f32_16x16x32_bf16 v[72:75], v[20:23], v[44:47], v[0:3]
	v_mfma_f32_16x16x32_bf16 v[0:3], v[174:177], v[36:39], v[146:149]
	v_mfma_f32_16x16x32_bf16 v[64:67], v[194:197], v[44:47], v[0:3]
	v_mfma_f32_16x16x32_bf16 v[0:3], v[8:11], v[48:51], v[150:153]
	v_mfma_f32_16x16x32_bf16 v[40:43], v[20:23], v[178:181], v[0:3]
	v_mfma_f32_16x16x32_bf16 v[0:3], v[174:177], v[48:51], v[158:161]
	v_mfma_f32_16x16x32_bf16 v[32:35], v[194:197], v[178:181], v[0:3]
	v_mfma_f32_16x16x32_bf16 v[0:3], v[8:11], v[182:185], v[162:165]
	v_mfma_f32_16x16x32_bf16 v[24:27], v[20:23], v[186:189], v[0:3]
	v_mfma_f32_16x16x32_bf16 v[0:3], v[174:177], v[182:185], v[166:169]
	v_mfma_f32_16x16x32_bf16 v[16:19], v[194:197], v[186:189], v[0:3]
	v_mfma_f32_16x16x32_bf16 v[0:3], v[8:11], v[224:227], v[4:7]
	v_mfma_f32_16x16x32_bf16 v[8:11], v[20:23], v[244:247], v[0:3]
	v_mfma_f32_16x16x32_bf16 v[0:3], v[174:177], v[224:227], v[206:209]
	v_mfma_f32_16x16x32_bf16 v[0:3], v[194:197], v[244:247], v[0:3]
	v_mfma_f32_16x16x32_bf16 v[4:7], v[198:201], v[36:39], v[12:15]
	v_mfma_f32_16x16x32_bf16 v[76:79], v[202:205], v[44:47], v[4:7]
	v_mfma_f32_16x16x32_bf16 v[4:7], v[236:239], v[36:39], v[210:213]
	v_mfma_f32_16x16x32_bf16 v[68:71], v[240:243], v[44:47], v[4:7]
	v_mfma_f32_16x16x32_bf16 v[4:7], v[198:201], v[48:51], v[28:31]
	v_mfma_f32_16x16x32_bf16 v[44:47], v[202:205], v[178:181], v[4:7]
	v_mfma_f32_16x16x32_bf16 v[4:7], v[236:239], v[48:51], v[228:231]
	v_mfma_f32_16x16x32_bf16 v[36:39], v[240:243], v[178:181], v[4:7]
	v_mfma_f32_16x16x32_bf16 v[4:7], v[198:201], v[182:185], v[232:235]
	v_mfma_f32_16x16x32_bf16 v[28:31], v[202:205], v[186:189], v[4:7]
	s_barrier
	v_mfma_f32_16x16x32_bf16 v[4:7], v[236:239], v[182:185], v[190:193]
	v_mfma_f32_16x16x32_bf16 v[20:23], v[240:243], v[186:189], v[4:7]
	v_mfma_f32_16x16x32_bf16 v[4:7], v[198:201], v[224:227], v[138:141]
	v_mfma_f32_16x16x32_bf16 v[12:15], v[202:205], v[244:247], v[4:7]
	v_mfma_f32_16x16x32_bf16 v[4:7], v[236:239], v[224:227], v[170:173]
	v_mfma_f32_16x16x32_bf16 v[4:7], v[240:243], v[244:247], v[4:7]
	s_setprio 0
	s_andn2_b64 vcc, exec, s[62:63]
	s_cbranch_vccnz .LBB0_385
	s_barrier

.LBB0_409:
	s_ashr_i32 s61, s60, 31
	s_lshl_b64 s[18:19], s[60:61], 17
	s_add_u32 s62, s47, s18
	s_addc_u32 s63, s71, s19
	s_and_b64 s[18:19], s[6:7], exec
	s_cselect_b32 s39, s63, s79
	s_cselect_b32 s38, s62, s78
	s_ashr_i32 s59, s58, 31
	s_lshl_b64 s[18:19], s[58:59], 17
	s_add_u32 s64, s14, s18
	s_addc_u32 s65, s16, s19
	s_and_b64 s[18:19], s[6:7], exec
	s_cselect_b32 s69, s65, s77
	s_cselect_b32 s68, s64, s76
	s_add_u32 s18, s78, 0x80
	s_addc_u32 s19, s79, 0
	s_add_u32 s42, s78, 0x100
	s_addc_u32 s43, s79, 0
	s_add_u32 s44, s76, 0x100
	s_addc_u32 s45, s77, 0
	s_add_u32 s78, s78, 0x180
	s_addc_u32 s79, s79, 0
	s_add_u32 s80, s76, 0x180
	s_addc_u32 s81, s77, 0
	s_add_i32 s49, 0, 0x10000
	s_add_i32 s20, 0, 0x14000
	s_mov_b64 s[76:77], s[78:79]
	v_add_u32_e32 v96, s49, v139
	v_add_u32_e32 v138, s20, v139
	ds_read_b128 v[0:3], v96
	ds_read_b128 v[4:7], v96 offset:1024
	ds_read_b128 v[8:11], v96 offset:2048
	ds_read_b128 v[12:15], v96 offset:3072
	ds_read_b128 v[16:19], v138
	ds_read_b128 v[20:23], v138 offset:1024
	ds_read_b128 v[24:27], v138 offset:2048
	ds_read_b128 v[28:31], v138 offset:3072
	s_add_u32 s18, s18, 0x10000
	s_addc_u32 s19, s19, 0
	s_add_i32 s59, s67, 0xc000
	v_lshl_add_u64 v[64:65], s[18:19], 0, v[130:131]
	s_mov_b32 m0, s59
	ds_read_b128 v[32:35], v141
	ds_read_b128 v[36:39], v141 offset:1024
	ds_read_b128 v[40:43], v141 offset:2048
	ds_read_b128 v[44:47], v141 offset:3072
	ds_read_b128 v[48:51], v141 offset:4096
	ds_read_b128 v[52:55], v141 offset:5120
	ds_read_b128 v[56:59], v141 offset:6144
	ds_read_b128 v[60:63], v141 offset:7168
	global_load_lds_dwordx4 v[64:65], off
	v_lshl_add_u64 v[64:65], s[18:19], 0, v[134:135]
	s_add_i32 s18, s67, 0xe000
	s_mov_b32 m0, s18
	s_nop 0
	global_load_lds_dwordx4 v[64:65], off
	s_waitcnt vmcnt(8)
	s_waitcnt lgkmcnt(0)
	s_barrier
	s_setprio 1
	s_waitcnt lgkmcnt(0)
	v_mfma_f32_16x16x32_bf16 v[64:67], v[0:3], v[32:35], 0
	v_mfma_f32_16x16x32_bf16 v[68:71], v[8:11], v[32:35], 0
	v_mfma_f32_16x16x32_bf16 v[72:75], v[0:3], v[40:43], 0
	v_mfma_f32_16x16x32_bf16 v[76:79], v[8:11], v[40:43], 0
	v_mfma_f32_16x16x32_bf16 v[80:83], v[0:3], v[48:51], 0
	v_mfma_f32_16x16x32_bf16 v[84:87], v[8:11], v[48:51], 0
	v_mfma_f32_16x16x32_bf16 v[88:91], v[0:3], v[56:59], 0
	v_mfma_f32_16x16x32_bf16 v[92:95], v[8:11], v[56:59], 0
	v_mfma_f32_16x16x32_bf16 v[64:67], v[4:7], v[36:39], v[64:67]
	v_mfma_f32_16x16x32_bf16 v[68:71], v[12:15], v[36:39], v[68:71]
	v_mfma_f32_16x16x32_bf16 v[72:75], v[4:7], v[44:47], v[72:75]
	v_mfma_f32_16x16x32_bf16 v[76:79], v[12:15], v[44:47], v[76:79]
	v_mfma_f32_16x16x32_bf16 v[80:83], v[4:7], v[52:55], v[80:83]
	v_mfma_f32_16x16x32_bf16 v[84:87], v[12:15], v[52:55], v[84:87]
	v_mfma_f32_16x16x32_bf16 v[88:91], v[4:7], v[60:63], v[88:91]
	v_mfma_f32_16x16x32_bf16 v[92:95], v[12:15], v[60:63], v[92:95]
	v_mfma_f32_16x16x32_bf16 v[98:101], v[16:19], v[32:35], 0
	v_mfma_f32_16x16x32_bf16 v[32:35], v[24:27], v[32:35], 0
	v_mfma_f32_16x16x32_bf16 v[98:101], v[20:23], v[36:39], v[98:101]
	v_mfma_f32_16x16x32_bf16 v[32:35], v[28:31], v[36:39], v[32:35]
	v_mfma_f32_16x16x32_bf16 v[36:39], v[16:19], v[40:43], 0
	v_mfma_f32_16x16x32_bf16 v[40:43], v[24:27], v[40:43], 0
	v_mfma_f32_16x16x32_bf16 v[36:39], v[20:23], v[44:47], v[36:39]
	v_mfma_f32_16x16x32_bf16 v[40:43], v[28:31], v[44:47], v[40:43]
	v_mfma_f32_16x16x32_bf16 v[44:47], v[16:19], v[48:51], 0
	v_mfma_f32_16x16x32_bf16 v[48:51], v[24:27], v[48:51], 0
	s_barrier
	v_mfma_f32_16x16x32_bf16 v[44:47], v[20:23], v[52:55], v[44:47]
	v_mfma_f32_16x16x32_bf16 v[48:51], v[28:31], v[52:55], v[48:51]
	v_mfma_f32_16x16x32_bf16 v[52:55], v[16:19], v[56:59], 0
	v_mfma_f32_16x16x32_bf16 v[56:59], v[24:27], v[56:59], 0
	v_mfma_f32_16x16x32_bf16 v[52:55], v[20:23], v[60:63], v[52:55]
	v_mfma_f32_16x16x32_bf16 v[56:59], v[28:31], v[60:63], v[56:59]
	s_setprio 0
	s_add_i32 s49, s49, s46
	v_lshl_add_u64 v[142:143], s[44:45], 0, v[132:133]
	s_mov_b32 m0, s49
	s_add_i32 s19, s49, 0x2000
	ds_read_b128 v[60:63], v141 offset:16384
	ds_read_b128 v[102:105], v141 offset:17408
	ds_read_b128 v[106:109], v141 offset:18432
	ds_read_b128 v[110:113], v141 offset:19456
	ds_read_b128 v[114:117], v141 offset:20480
	ds_read_b128 v[118:121], v141 offset:21504
	ds_read_b128 v[122:125], v141 offset:22528
	ds_read_b128 v[126:129], v141 offset:23552
	global_load_lds_dwordx4 v[142:143], off
	v_lshl_add_u64 v[142:143], s[44:45], 0, v[136:137]
	s_add_u32 s44, s44, 0x10000
	s_mov_b32 m0, s19
	s_addc_u32 s45, s45, 0
	s_add_i32 s20, s20, s46
	global_load_lds_dwordx4 v[142:143], off
	v_lshl_add_u64 v[142:143], s[44:45], 0, v[132:133]
	s_mov_b32 m0, s20
	s_add_i32 s33, s20, 0x2000
	global_load_lds_dwordx4 v[142:143], off
	v_lshl_add_u64 v[142:143], s[44:45], 0, v[136:137]
	s_mov_b32 m0, s33
	s_nop 0
	global_load_lds_dwordx4 v[142:143], off
	v_lshl_add_u64 v[142:143], s[42:43], 0, v[130:131]
	s_mov_b32 m0, s67
	s_nop 0
	global_load_lds_dwordx4 v[142:143], off
	v_lshl_add_u64 v[142:143], s[42:43], 0, v[134:135]
	s_mov_b32 m0, s72
	s_nop 0
	global_load_lds_dwordx4 v[142:143], off
	s_waitcnt vmcnt(8)
	s_waitcnt lgkmcnt(0)
	s_barrier
	s_setprio 1
	s_waitcnt lgkmcnt(0)
	v_mfma_f32_16x16x32_bf16 v[142:145], v[0:3], v[60:63], 0
	v_mfma_f32_16x16x32_bf16 v[150:153], v[0:3], v[106:109], 0
	v_mfma_f32_16x16x32_bf16 v[158:161], v[0:3], v[114:117], 0
	v_mfma_f32_16x16x32_bf16 v[0:3], v[0:3], v[122:125], 0
	v_mfma_f32_16x16x32_bf16 v[142:145], v[4:7], v[102:105], v[142:145]
	v_mfma_f32_16x16x32_bf16 v[150:153], v[4:7], v[110:113], v[150:153]
	v_mfma_f32_16x16x32_bf16 v[158:161], v[4:7], v[118:121], v[158:161]
	v_mfma_f32_16x16x32_bf16 v[0:3], v[4:7], v[126:129], v[0:3]
	v_mfma_f32_16x16x32_bf16 v[4:7], v[8:11], v[122:125], 0
	v_mfma_f32_16x16x32_bf16 v[146:149], v[8:11], v[60:63], 0
	v_mfma_f32_16x16x32_bf16 v[154:157], v[8:11], v[106:109], 0
	v_mfma_f32_16x16x32_bf16 v[162:165], v[8:11], v[114:117], 0
	v_mfma_f32_16x16x32_bf16 v[4:7], v[12:15], v[126:129], v[4:7]
	v_mfma_f32_16x16x32_bf16 v[146:149], v[12:15], v[102:105], v[146:149]
	v_mfma_f32_16x16x32_bf16 v[154:157], v[12:15], v[110:113], v[154:157]
	v_mfma_f32_16x16x32_bf16 v[162:165], v[12:15], v[118:121], v[162:165]
	v_mfma_f32_16x16x32_bf16 v[8:11], v[16:19], v[60:63], 0
	v_mfma_f32_16x16x32_bf16 v[12:15], v[24:27], v[60:63], 0
	v_mfma_f32_16x16x32_bf16 v[8:11], v[20:23], v[102:105], v[8:11]
	v_mfma_f32_16x16x32_bf16 v[12:15], v[28:31], v[102:105], v[12:15]
	v_mfma_f32_16x16x32_bf16 v[60:63], v[16:19], v[106:109], 0
	v_mfma_f32_16x16x32_bf16 v[102:105], v[24:27], v[106:109], 0
	v_mfma_f32_16x16x32_bf16 v[106:109], v[16:19], v[114:117], 0
	v_mfma_f32_16x16x32_bf16 v[16:19], v[16:19], v[122:125], 0
	v_mfma_f32_16x16x32_bf16 v[60:63], v[20:23], v[110:113], v[60:63]
	v_mfma_f32_16x16x32_bf16 v[102:105], v[28:31], v[110:113], v[102:105]
	s_barrier
	v_mfma_f32_16x16x32_bf16 v[106:109], v[20:23], v[118:121], v[106:109]
	v_mfma_f32_16x16x32_bf16 v[110:113], v[24:27], v[114:117], 0
	v_mfma_f32_16x16x32_bf16 v[16:19], v[20:23], v[126:129], v[16:19]
	v_mfma_f32_16x16x32_bf16 v[20:23], v[24:27], v[122:125], 0
	v_mfma_f32_16x16x32_bf16 v[110:113], v[28:31], v[118:121], v[110:113]
	v_mfma_f32_16x16x32_bf16 v[20:23], v[28:31], v[126:129], v[20:23]
	s_setprio 0
	s_add_i32 s61, 0, 0x18000
	s_add_i32 s44, 0, 0x1c000
	v_add_u32_e32 v140, s61, v139
	v_add_u32_e32 v236, s44, v139
	ds_read_b128 v[24:27], v140
	ds_read_b128 v[28:31], v140 offset:1024
	ds_read_b128 v[114:117], v140 offset:2048
	ds_read_b128 v[118:121], v140 offset:3072
	ds_read_b128 v[122:125], v236
	ds_read_b128 v[126:129], v236 offset:1024
	ds_read_b128 v[166:169], v236 offset:2048
	ds_read_b128 v[170:173], v236 offset:3072
	s_add_u32 s42, s42, 0x10000
	s_addc_u32 s43, s43, 0
	s_mov_b32 m0, s73
	v_lshl_add_u64 v[206:207], s[42:43], 0, v[130:131]
	ds_read_b128 v[174:177], v141 offset:32768
	ds_read_b128 v[178:181], v141 offset:33792
	ds_read_b128 v[182:185], v141 offset:34816
	ds_read_b128 v[186:189], v141 offset:35840
	ds_read_b128 v[190:193], v141 offset:36864
	ds_read_b128 v[194:197], v141 offset:37888
	ds_read_b128 v[198:201], v141 offset:38912
	ds_read_b128 v[202:205], v141 offset:39936
	global_load_lds_dwordx4 v[206:207], off
	v_lshl_add_u64 v[206:207], s[42:43], 0, v[134:135]
	s_mov_b32 m0, s74
	s_nop 0
	global_load_lds_dwordx4 v[206:207], off
	s_waitcnt vmcnt(8)
	s_waitcnt lgkmcnt(0)
	s_barrier
	s_setprio 1
	s_waitcnt lgkmcnt(0)
	v_mfma_f32_16x16x32_bf16 v[64:67], v[24:27], v[174:177], v[64:67]
	v_mfma_f32_16x16x32_bf16 v[68:71], v[114:117], v[174:177], v[68:71]
	v_mfma_f32_16x16x32_bf16 v[72:75], v[24:27], v[182:185], v[72:75]
	v_mfma_f32_16x16x32_bf16 v[76:79], v[114:117], v[182:185], v[76:79]
	v_mfma_f32_16x16x32_bf16 v[80:83], v[24:27], v[190:193], v[80:83]
	v_mfma_f32_16x16x32_bf16 v[84:87], v[114:117], v[190:193], v[84:87]
	v_mfma_f32_16x16x32_bf16 v[88:91], v[24:27], v[198:201], v[88:91]
	v_mfma_f32_16x16x32_bf16 v[92:95], v[114:117], v[198:201], v[92:95]
	v_mfma_f32_16x16x32_bf16 v[64:67], v[28:31], v[178:181], v[64:67]
	v_mfma_f32_16x16x32_bf16 v[68:71], v[118:121], v[178:181], v[68:71]
	v_mfma_f32_16x16x32_bf16 v[72:75], v[28:31], v[186:189], v[72:75]
	v_mfma_f32_16x16x32_bf16 v[76:79], v[118:121], v[186:189], v[76:79]
	v_mfma_f32_16x16x32_bf16 v[80:83], v[28:31], v[194:197], v[80:83]
	v_mfma_f32_16x16x32_bf16 v[84:87], v[118:121], v[194:197], v[84:87]
	v_mfma_f32_16x16x32_bf16 v[88:91], v[28:31], v[202:205], v[88:91]
	v_mfma_f32_16x16x32_bf16 v[92:95], v[118:121], v[202:205], v[92:95]
	v_mfma_f32_16x16x32_bf16 v[98:101], v[122:125], v[174:177], v[98:101]
	v_mfma_f32_16x16x32_bf16 v[32:35], v[166:169], v[174:177], v[32:35]
	v_mfma_f32_16x16x32_bf16 v[36:39], v[122:125], v[182:185], v[36:39]
	v_mfma_f32_16x16x32_bf16 v[40:43], v[166:169], v[182:185], v[40:43]
	v_mfma_f32_16x16x32_bf16 v[44:47], v[122:125], v[190:193], v[44:47]
	v_mfma_f32_16x16x32_bf16 v[48:51], v[166:169], v[190:193], v[48:51]
	v_mfma_f32_16x16x32_bf16 v[52:55], v[122:125], v[198:201], v[52:55]
	v_mfma_f32_16x16x32_bf16 v[56:59], v[166:169], v[198:201], v[56:59]
	v_mfma_f32_16x16x32_bf16 v[98:101], v[126:129], v[178:181], v[98:101]
	v_mfma_f32_16x16x32_bf16 v[32:35], v[170:173], v[178:181], v[32:35]
	s_barrier
	v_mfma_f32_16x16x32_bf16 v[36:39], v[126:129], v[186:189], v[36:39]
	v_mfma_f32_16x16x32_bf16 v[40:43], v[170:173], v[186:189], v[40:43]
	v_mfma_f32_16x16x32_bf16 v[44:47], v[126:129], v[194:197], v[44:47]
	v_mfma_f32_16x16x32_bf16 v[48:51], v[170:173], v[194:197], v[48:51]
	v_mfma_f32_16x16x32_bf16 v[52:55], v[126:129], v[202:205], v[52:55]
	v_mfma_f32_16x16x32_bf16 v[56:59], v[170:173], v[202:205], v[56:59]
	s_setprio 0
	s_add_i32 s61, s61, s46
	s_add_i32 s35, s61, 0x2000
	v_lshl_add_u64 v[206:207], s[80:81], 0, v[132:133]
	s_mov_b32 m0, s61
	s_add_u32 s42, s80, 0x10000
	ds_read_b128 v[174:177], v141 offset:49152
	ds_read_b128 v[178:181], v141 offset:50176
	ds_read_b128 v[182:185], v141 offset:51200
	ds_read_b128 v[186:189], v141 offset:52224
	ds_read_b128 v[190:193], v141 offset:53248
	ds_read_b128 v[194:197], v141 offset:54272
	ds_read_b128 v[198:201], v141 offset:55296
	ds_read_b128 v[202:205], v141 offset:56320
	global_load_lds_dwordx4 v[206:207], off
	v_lshl_add_u64 v[206:207], s[80:81], 0, v[136:137]
	s_mov_b32 m0, s35
	s_addc_u32 s43, s81, 0
	s_add_i32 s44, s44, s46
	global_load_lds_dwordx4 v[206:207], off
	v_lshl_add_u64 v[206:207], s[42:43], 0, v[132:133]
	s_mov_b32 m0, s44
	s_add_i32 s45, s44, 0x2000
	global_load_lds_dwordx4 v[206:207], off
	v_lshl_add_u64 v[206:207], s[42:43], 0, v[136:137]
	s_mov_b32 m0, s45
	s_nop 0
	global_load_lds_dwordx4 v[206:207], off
	v_lshl_add_u64 v[206:207], s[76:77], 0, v[130:131]
	s_mov_b32 m0, s85
	s_nop 0
	global_load_lds_dwordx4 v[206:207], off
	v_lshl_add_u64 v[206:207], s[76:77], 0, v[134:135]
	s_mov_b32 m0, s86
	s_nop 0
	global_load_lds_dwordx4 v[206:207], off
	s_waitcnt vmcnt(8)
	s_waitcnt lgkmcnt(0)
	s_barrier
	s_setprio 1
	s_waitcnt lgkmcnt(0)
	v_mfma_f32_16x16x32_bf16 v[0:3], v[24:27], v[198:201], v[0:3]
	v_mfma_f32_16x16x32_bf16 v[4:7], v[114:117], v[198:201], v[4:7]
	v_mfma_f32_16x16x32_bf16 v[142:145], v[24:27], v[174:177], v[142:145]
	v_mfma_f32_16x16x32_bf16 v[146:149], v[114:117], v[174:177], v[146:149]
	v_mfma_f32_16x16x32_bf16 v[150:153], v[24:27], v[182:185], v[150:153]
	v_mfma_f32_16x16x32_bf16 v[154:157], v[114:117], v[182:185], v[154:157]
	v_mfma_f32_16x16x32_bf16 v[158:161], v[24:27], v[190:193], v[158:161]
	v_mfma_f32_16x16x32_bf16 v[162:165], v[114:117], v[190:193], v[162:165]
	v_mfma_f32_16x16x32_bf16 v[0:3], v[28:31], v[202:205], v[0:3]
	v_mfma_f32_16x16x32_bf16 v[4:7], v[118:121], v[202:205], v[4:7]
	v_mfma_f32_16x16x32_bf16 v[142:145], v[28:31], v[178:181], v[142:145]
	v_mfma_f32_16x16x32_bf16 v[146:149], v[118:121], v[178:181], v[146:149]
	v_mfma_f32_16x16x32_bf16 v[150:153], v[28:31], v[186:189], v[150:153]
	v_mfma_f32_16x16x32_bf16 v[154:157], v[118:121], v[186:189], v[154:157]
	v_mfma_f32_16x16x32_bf16 v[158:161], v[28:31], v[194:197], v[158:161]
	v_mfma_f32_16x16x32_bf16 v[162:165], v[118:121], v[194:197], v[162:165]
	v_mfma_f32_16x16x32_bf16 v[8:11], v[122:125], v[174:177], v[8:11]
	v_mfma_f32_16x16x32_bf16 v[12:15], v[166:169], v[174:177], v[12:15]
	v_mfma_f32_16x16x32_bf16 v[24:27], v[122:125], v[182:185], v[60:63]
	v_mfma_f32_16x16x32_bf16 v[28:31], v[166:169], v[182:185], v[102:105]
	v_mfma_f32_16x16x32_bf16 v[60:63], v[122:125], v[190:193], v[106:109]
	v_mfma_f32_16x16x32_bf16 v[102:105], v[166:169], v[190:193], v[110:113]
	v_mfma_f32_16x16x32_bf16 v[16:19], v[122:125], v[198:201], v[16:19]
	v_mfma_f32_16x16x32_bf16 v[20:23], v[166:169], v[198:201], v[20:23]
	v_mfma_f32_16x16x32_bf16 v[8:11], v[126:129], v[178:181], v[8:11]
	v_mfma_f32_16x16x32_bf16 v[12:15], v[170:173], v[178:181], v[12:15]
	s_barrier
	v_mfma_f32_16x16x32_bf16 v[24:27], v[126:129], v[186:189], v[24:27]
	v_mfma_f32_16x16x32_bf16 v[28:31], v[170:173], v[186:189], v[28:31]
	v_mfma_f32_16x16x32_bf16 v[60:63], v[126:129], v[194:197], v[60:63]
	v_mfma_f32_16x16x32_bf16 v[102:105], v[170:173], v[194:197], v[102:105]
	v_mfma_f32_16x16x32_bf16 v[16:19], v[126:129], v[202:205], v[16:19]
	v_mfma_f32_16x16x32_bf16 v[20:23], v[170:173], v[202:205], v[20:23]
	s_setprio 0
	s_add_u32 s76, s38, 0x80
	s_addc_u32 s77, s39, 0
	s_add_u32 s42, s68, 0x80
	s_addc_u32 s43, s69, 0
	ds_read_b128 v[106:109], v96
	ds_read_b128 v[110:113], v96 offset:1024
	ds_read_b128 v[114:117], v96 offset:2048
	ds_read_b128 v[118:121], v96 offset:3072
	ds_read_b128 v[122:125], v138
	ds_read_b128 v[126:129], v138 offset:1024
	ds_read_b128 v[166:169], v138 offset:2048
	ds_read_b128 v[170:173], v138 offset:3072
	s_add_u32 s78, s78, 0x10000
	s_addc_u32 s79, s79, 0
	s_mov_b32 m0, s59
	v_lshl_add_u64 v[206:207], s[78:79], 0, v[130:131]
	ds_read_b128 v[174:177], v141
	ds_read_b128 v[178:181], v141 offset:1024
	ds_read_b128 v[182:185], v141 offset:2048
	ds_read_b128 v[186:189], v141 offset:3072
	ds_read_b128 v[190:193], v141 offset:4096
	ds_read_b128 v[194:197], v141 offset:5120
	ds_read_b128 v[198:201], v141 offset:6144
	ds_read_b128 v[202:205], v141 offset:7168
	global_load_lds_dwordx4 v[206:207], off
	v_lshl_add_u64 v[206:207], s[78:79], 0, v[134:135]
	s_mov_b32 m0, s18
	s_nop 0
	global_load_lds_dwordx4 v[206:207], off
	s_waitcnt vmcnt(8)
	s_waitcnt lgkmcnt(0)
	s_barrier
	s_setprio 1
	s_waitcnt lgkmcnt(0)
	v_mfma_f32_16x16x32_bf16 v[88:91], v[106:109], v[198:201], v[88:91]
	v_mfma_f32_16x16x32_bf16 v[64:67], v[106:109], v[174:177], v[64:67]
	v_mfma_f32_16x16x32_bf16 v[68:71], v[114:117], v[174:177], v[68:71]
	v_mfma_f32_16x16x32_bf16 v[72:75], v[106:109], v[182:185], v[72:75]
	v_mfma_f32_16x16x32_bf16 v[76:79], v[114:117], v[182:185], v[76:79]
	v_mfma_f32_16x16x32_bf16 v[80:83], v[106:109], v[190:193], v[80:83]
	v_mfma_f32_16x16x32_bf16 v[84:87], v[114:117], v[190:193], v[84:87]
	v_mfma_f32_16x16x32_bf16 v[206:209], v[110:113], v[202:205], v[88:91]
	v_mfma_f32_16x16x32_bf16 v[88:91], v[114:117], v[198:201], v[92:95]
	v_mfma_f32_16x16x32_bf16 v[64:67], v[110:113], v[178:181], v[64:67]
	v_mfma_f32_16x16x32_bf16 v[68:71], v[118:121], v[178:181], v[68:71]
	v_mfma_f32_16x16x32_bf16 v[72:75], v[110:113], v[186:189], v[72:75]
	v_mfma_f32_16x16x32_bf16 v[76:79], v[118:121], v[186:189], v[76:79]
	v_mfma_f32_16x16x32_bf16 v[80:83], v[110:113], v[194:197], v[80:83]
	v_mfma_f32_16x16x32_bf16 v[84:87], v[118:121], v[194:197], v[84:87]
	v_mfma_f32_16x16x32_bf16 v[92:95], v[118:121], v[202:205], v[88:91]
	v_mfma_f32_16x16x32_bf16 v[44:47], v[122:125], v[190:193], v[44:47]
	v_mfma_f32_16x16x32_bf16 v[88:91], v[122:125], v[174:177], v[98:101]
	v_mfma_f32_16x16x32_bf16 v[32:35], v[166:169], v[174:177], v[32:35]
	v_mfma_f32_16x16x32_bf16 v[174:177], v[126:129], v[194:197], v[44:47]
	v_mfma_f32_16x16x32_bf16 v[44:47], v[166:169], v[190:193], v[48:51]
	v_mfma_f32_16x16x32_bf16 v[36:39], v[122:125], v[182:185], v[36:39]
	v_mfma_f32_16x16x32_bf16 v[40:43], v[166:169], v[182:185], v[40:43]
	v_mfma_f32_16x16x32_bf16 v[48:51], v[170:173], v[194:197], v[44:47]
	v_mfma_f32_16x16x32_bf16 v[44:47], v[122:125], v[198:201], v[52:55]
	v_mfma_f32_16x16x32_bf16 v[210:213], v[126:129], v[178:181], v[88:91]
	s_barrier
	v_mfma_f32_16x16x32_bf16 v[32:35], v[170:173], v[178:181], v[32:35]
	v_mfma_f32_16x16x32_bf16 v[36:39], v[126:129], v[186:189], v[36:39]
	v_mfma_f32_16x16x32_bf16 v[40:43], v[170:173], v[186:189], v[40:43]
	v_mfma_f32_16x16x32_bf16 v[178:181], v[126:129], v[202:205], v[44:47]
	v_mfma_f32_16x16x32_bf16 v[44:47], v[166:169], v[198:201], v[56:59]
	v_mfma_f32_16x16x32_bf16 v[182:185], v[170:173], v[202:205], v[44:47]
	s_setprio 0
	s_mov_b32 m0, s49
	v_lshl_add_u64 v[198:199], s[68:69], 0, v[132:133]
	s_add_u32 s18, s68, 0x10000
	s_nop 1
	ds_read_b128 v[44:47], v141 offset:16384
	ds_read_b128 v[52:55], v141 offset:17408
	ds_read_b128 v[56:59], v141 offset:18432
	ds_read_b128 v[88:91], v141 offset:19456
	ds_read_b128 v[98:101], v141 offset:20480
	ds_read_b128 v[186:189], v141 offset:21504
	ds_read_b128 v[190:193], v141 offset:22528
	ds_read_b128 v[194:197], v141 offset:23552
	global_load_lds_dwordx4 v[198:199], off
	v_lshl_add_u64 v[198:199], s[68:69], 0, v[136:137]
	s_mov_b32 m0, s19
	s_addc_u32 s19, s69, 0
	global_load_lds_dwordx4 v[198:199], off
	v_lshl_add_u64 v[198:199], s[18:19], 0, v[132:133]
	s_mov_b32 m0, s20
	s_nop 0
	global_load_lds_dwordx4 v[198:199], off
	v_lshl_add_u64 v[198:199], s[18:19], 0, v[136:137]
	s_mov_b32 m0, s33
	s_nop 0
	global_load_lds_dwordx4 v[198:199], off
	v_lshl_add_u64 v[198:199], s[38:39], 0, v[130:131]
	s_mov_b32 m0, s67
	s_nop 0
	global_load_lds_dwordx4 v[198:199], off
	v_lshl_add_u64 v[198:199], s[38:39], 0, v[134:135]
	s_mov_b32 m0, s72
	s_nop 0
	global_load_lds_dwordx4 v[198:199], off
	s_waitcnt vmcnt(8)
	s_waitcnt lgkmcnt(0)
	s_barrier
	s_setprio 1
	s_waitcnt lgkmcnt(0)
	v_mfma_f32_16x16x32_bf16 v[0:3], v[106:109], v[190:193], v[0:3]
	v_mfma_f32_16x16x32_bf16 v[4:7], v[114:117], v[190:193], v[4:7]
	v_mfma_f32_16x16x32_bf16 v[142:145], v[106:109], v[44:47], v[142:145]
	v_mfma_f32_16x16x32_bf16 v[146:149], v[114:117], v[44:47], v[146:149]
	v_mfma_f32_16x16x32_bf16 v[150:153], v[106:109], v[56:59], v[150:153]
	v_mfma_f32_16x16x32_bf16 v[154:157], v[114:117], v[56:59], v[154:157]
	v_mfma_f32_16x16x32_bf16 v[158:161], v[106:109], v[98:101], v[158:161]
	v_mfma_f32_16x16x32_bf16 v[162:165], v[114:117], v[98:101], v[162:165]
	v_mfma_f32_16x16x32_bf16 v[0:3], v[110:113], v[194:197], v[0:3]
	v_mfma_f32_16x16x32_bf16 v[4:7], v[118:121], v[194:197], v[4:7]
	v_mfma_f32_16x16x32_bf16 v[142:145], v[110:113], v[52:55], v[142:145]
	v_mfma_f32_16x16x32_bf16 v[146:149], v[118:121], v[52:55], v[146:149]
	v_mfma_f32_16x16x32_bf16 v[150:153], v[110:113], v[88:91], v[150:153]
	v_mfma_f32_16x16x32_bf16 v[154:157], v[118:121], v[88:91], v[154:157]
	v_mfma_f32_16x16x32_bf16 v[158:161], v[110:113], v[186:189], v[158:161]
	v_mfma_f32_16x16x32_bf16 v[162:165], v[118:121], v[186:189], v[162:165]
	v_mfma_f32_16x16x32_bf16 v[28:31], v[166:169], v[56:59], v[28:31]
	v_mfma_f32_16x16x32_bf16 v[8:11], v[122:125], v[44:47], v[8:11]
	v_mfma_f32_16x16x32_bf16 v[12:15], v[166:169], v[44:47], v[12:15]
	v_mfma_f32_16x16x32_bf16 v[24:27], v[122:125], v[56:59], v[24:27]
	v_mfma_f32_16x16x32_bf16 v[198:201], v[170:173], v[88:91], v[28:31]
	v_mfma_f32_16x16x32_bf16 v[28:31], v[122:125], v[98:101], v[60:63]
	v_mfma_f32_16x16x32_bf16 v[16:19], v[122:125], v[190:193], v[16:19]
	v_mfma_f32_16x16x32_bf16 v[8:11], v[126:129], v[52:55], v[8:11]
	v_mfma_f32_16x16x32_bf16 v[12:15], v[170:173], v[52:55], v[12:15]
	v_mfma_f32_16x16x32_bf16 v[24:27], v[126:129], v[88:91], v[24:27]
	s_barrier
	v_mfma_f32_16x16x32_bf16 v[202:205], v[126:129], v[186:189], v[28:31]
	v_mfma_f32_16x16x32_bf16 v[28:31], v[166:169], v[98:101], v[102:105]
	v_mfma_f32_16x16x32_bf16 v[16:19], v[126:129], v[194:197], v[16:19]
	v_mfma_f32_16x16x32_bf16 v[20:23], v[166:169], v[190:193], v[20:23]
	v_mfma_f32_16x16x32_bf16 v[186:189], v[170:173], v[186:189], v[28:31]
	v_mfma_f32_16x16x32_bf16 v[166:169], v[170:173], v[194:197], v[20:23]
	s_setprio 0
	ds_read_b128 v[170:173], v140
	ds_read_b128 v[190:193], v140 offset:1024
	ds_read_b128 v[194:197], v140 offset:2048
	ds_read_b128 v[220:223], v140 offset:3072
	ds_read_b128 v[224:227], v236
	ds_read_b128 v[228:231], v236 offset:1024
	ds_read_b128 v[232:235], v236 offset:2048
	ds_read_b128 v[236:239], v236 offset:3072
	s_add_u32 s18, s38, 0x10000
	s_addc_u32 s19, s39, 0
	s_mov_b32 m0, s73
	v_lshl_add_u64 v[44:45], s[18:19], 0, v[130:131]
	ds_read_b128 v[20:23], v141 offset:32768
	ds_read_b128 v[28:31], v141 offset:33792
	ds_read_b128 v[52:55], v141 offset:34816
	ds_read_b128 v[102:105], v141 offset:35840
	ds_read_b128 v[110:113], v141 offset:36864
	ds_read_b128 v[118:121], v141 offset:37888
	ds_read_b128 v[240:243], v141 offset:38912
	ds_read_b128 v[244:247], v141 offset:39936
	global_load_lds_dwordx4 v[44:45], off
	v_lshl_add_u64 v[44:45], s[18:19], 0, v[134:135]
	s_mov_b32 m0, s74
	s_nop 0
	global_load_lds_dwordx4 v[44:45], off
	s_waitcnt vmcnt(8)
	s_waitcnt lgkmcnt(0)
	s_barrier
	s_setprio 1
	s_waitcnt lgkmcnt(0)
	v_mfma_f32_16x16x32_bf16 v[44:47], v[170:173], v[20:23], v[64:67]
	v_mfma_f32_16x16x32_bf16 v[126:129], v[190:193], v[28:31], v[44:47]
	v_mfma_f32_16x16x32_bf16 v[44:47], v[194:197], v[20:23], v[68:71]
	v_mfma_f32_16x16x32_bf16 v[122:125], v[220:223], v[28:31], v[44:47]
	v_mfma_f32_16x16x32_bf16 v[44:47], v[170:173], v[52:55], v[72:75]
	v_mfma_f32_16x16x32_bf16 v[114:117], v[190:193], v[102:105], v[44:47]
	v_mfma_f32_16x16x32_bf16 v[44:47], v[194:197], v[52:55], v[76:79]
	v_mfma_f32_16x16x32_bf16 v[106:109], v[220:223], v[102:105], v[44:47]
	v_mfma_f32_16x16x32_bf16 v[44:47], v[170:173], v[110:113], v[80:83]
	v_mfma_f32_16x16x32_bf16 v[98:101], v[190:193], v[118:121], v[44:47]
	v_mfma_f32_16x16x32_bf16 v[44:47], v[194:197], v[110:113], v[84:87]
	v_mfma_f32_16x16x32_bf16 v[88:91], v[220:223], v[118:121], v[44:47]
	v_mfma_f32_16x16x32_bf16 v[44:47], v[170:173], v[240:243], v[206:209]
	v_mfma_f32_16x16x32_bf16 v[80:83], v[190:193], v[244:247], v[44:47]
	v_mfma_f32_16x16x32_bf16 v[44:47], v[194:197], v[240:243], v[92:95]
	v_mfma_f32_16x16x32_bf16 v[72:75], v[220:223], v[244:247], v[44:47]
	v_mfma_f32_16x16x32_bf16 v[44:47], v[224:227], v[20:23], v[210:213]
	v_mfma_f32_16x16x32_bf16 v[20:23], v[232:235], v[20:23], v[32:35]
	v_mfma_f32_16x16x32_bf16 v[60:63], v[228:231], v[28:31], v[44:47]
	v_mfma_f32_16x16x32_bf16 v[44:47], v[236:239], v[28:31], v[20:23]
	v_mfma_f32_16x16x32_bf16 v[20:23], v[224:227], v[52:55], v[36:39]
	v_mfma_f32_16x16x32_bf16 v[56:59], v[228:231], v[102:105], v[20:23]
	v_mfma_f32_16x16x32_bf16 v[20:23], v[232:235], v[52:55], v[40:43]
	v_mfma_f32_16x16x32_bf16 v[36:39], v[236:239], v[102:105], v[20:23]
	v_mfma_f32_16x16x32_bf16 v[20:23], v[224:227], v[110:113], v[174:177]
	v_mfma_f32_16x16x32_bf16 v[52:55], v[228:231], v[118:121], v[20:23]
	s_barrier
	v_mfma_f32_16x16x32_bf16 v[20:23], v[232:235], v[110:113], v[48:51]
	v_mfma_f32_16x16x32_bf16 v[28:31], v[236:239], v[118:121], v[20:23]
	v_mfma_f32_16x16x32_bf16 v[20:23], v[224:227], v[240:243], v[178:181]
	v_mfma_f32_16x16x32_bf16 v[48:51], v[228:231], v[244:247], v[20:23]
	v_mfma_f32_16x16x32_bf16 v[20:23], v[232:235], v[240:243], v[182:185]
	v_mfma_f32_16x16x32_bf16 v[20:23], v[236:239], v[244:247], v[20:23]
	s_setprio 0
	s_mov_b32 m0, s61
	v_lshl_add_u64 v[40:41], s[42:43], 0, v[132:133]
	s_add_u32 s18, s42, 0x10000
	ds_read_b128 v[32:35], v141 offset:49152
	ds_read_b128 v[174:177], v141 offset:50176
	ds_read_b128 v[178:181], v141 offset:51200
	ds_read_b128 v[182:185], v141 offset:52224
	ds_read_b128 v[206:209], v141 offset:53248
	ds_read_b128 v[210:213], v141 offset:54272
	ds_read_b128 v[240:243], v141 offset:55296
	ds_read_b128 v[244:247], v141 offset:56320
	global_load_lds_dwordx4 v[40:41], off
	v_lshl_add_u64 v[40:41], s[42:43], 0, v[136:137]
	s_mov_b32 m0, s35
	s_addc_u32 s19, s43, 0
	global_load_lds_dwordx4 v[40:41], off
	v_lshl_add_u64 v[40:41], s[18:19], 0, v[132:133]
	s_mov_b32 m0, s44
	s_nop 0
	global_load_lds_dwordx4 v[40:41], off
	v_lshl_add_u64 v[40:41], s[18:19], 0, v[136:137]
	s_mov_b32 m0, s45
	s_nop 0
	global_load_lds_dwordx4 v[40:41], off
	v_lshl_add_u64 v[40:41], s[76:77], 0, v[130:131]
	s_mov_b32 m0, s85
	s_nop 0
	global_load_lds_dwordx4 v[40:41], off
	v_lshl_add_u64 v[40:41], s[76:77], 0, v[134:135]
	s_mov_b32 m0, s86
	s_nop 0
	global_load_lds_dwordx4 v[40:41], off
	s_waitcnt vmcnt(8)
	s_waitcnt lgkmcnt(0)
	s_barrier
	s_setprio 1
	s_waitcnt lgkmcnt(0)
	v_mfma_f32_16x16x32_bf16 v[40:43], v[170:173], v[32:35], v[142:145]
	v_mfma_f32_16x16x32_bf16 v[118:121], v[190:193], v[174:177], v[40:43]
	v_mfma_f32_16x16x32_bf16 v[40:43], v[194:197], v[32:35], v[146:149]
	v_mfma_f32_16x16x32_bf16 v[110:113], v[220:223], v[174:177], v[40:43]
	v_mfma_f32_16x16x32_bf16 v[40:43], v[170:173], v[178:181], v[150:153]
	v_mfma_f32_16x16x32_bf16 v[102:105], v[190:193], v[182:185], v[40:43]
	v_mfma_f32_16x16x32_bf16 v[40:43], v[194:197], v[178:181], v[154:157]
	v_mfma_f32_16x16x32_bf16 v[92:95], v[220:223], v[182:185], v[40:43]
	v_mfma_f32_16x16x32_bf16 v[40:43], v[170:173], v[206:209], v[158:161]
	v_mfma_f32_16x16x32_bf16 v[0:3], v[170:173], v[240:243], v[0:3]
	v_mfma_f32_16x16x32_bf16 v[84:87], v[190:193], v[210:213], v[40:43]
	v_mfma_f32_16x16x32_bf16 v[40:43], v[194:197], v[206:209], v[162:165]
	v_mfma_f32_16x16x32_bf16 v[68:71], v[190:193], v[244:247], v[0:3]
	v_mfma_f32_16x16x32_bf16 v[0:3], v[194:197], v[240:243], v[4:7]
	v_mfma_f32_16x16x32_bf16 v[76:79], v[220:223], v[210:213], v[40:43]
	v_mfma_f32_16x16x32_bf16 v[64:67], v[220:223], v[244:247], v[0:3]
	v_mfma_f32_16x16x32_bf16 v[0:3], v[224:227], v[32:35], v[8:11]
	v_mfma_f32_16x16x32_bf16 v[40:43], v[228:231], v[174:177], v[0:3]
	v_mfma_f32_16x16x32_bf16 v[0:3], v[232:235], v[32:35], v[12:15]
	v_mfma_f32_16x16x32_bf16 v[12:15], v[236:239], v[174:177], v[0:3]
	v_mfma_f32_16x16x32_bf16 v[0:3], v[224:227], v[178:181], v[24:27]
	v_mfma_f32_16x16x32_bf16 v[32:35], v[228:231], v[182:185], v[0:3]
	v_mfma_f32_16x16x32_bf16 v[0:3], v[232:235], v[178:181], v[198:201]
	v_mfma_f32_16x16x32_bf16 v[8:11], v[236:239], v[182:185], v[0:3]
	v_mfma_f32_16x16x32_bf16 v[0:3], v[224:227], v[206:209], v[202:205]
	v_mfma_f32_16x16x32_bf16 v[24:27], v[228:231], v[210:213], v[0:3]
	s_barrier
	v_mfma_f32_16x16x32_bf16 v[0:3], v[232:235], v[206:209], v[186:189]
	v_mfma_f32_16x16x32_bf16 v[4:7], v[236:239], v[210:213], v[0:3]
	v_mfma_f32_16x16x32_bf16 v[0:3], v[224:227], v[240:243], v[16:19]
	v_mfma_f32_16x16x32_bf16 v[16:19], v[228:231], v[244:247], v[0:3]
	v_mfma_f32_16x16x32_bf16 v[0:3], v[232:235], v[240:243], v[166:169]
	v_mfma_f32_16x16x32_bf16 v[0:3], v[236:239], v[244:247], v[0:3]
	s_setprio 0
	s_andn2_b64 vcc, exec, s[10:11]
	s_cbranch_vccnz .LBB0_411
	s_barrier

.LBB0_433:
	s_add_u32 s18, s10, 0x80
	s_addc_u32 s19, s11, 0
	s_add_u32 s10, s10, 0x100
	s_addc_u32 s11, s11, 0
	s_cmp_eq_u32 s92, 12
	s_cselect_b32 s42, s87, s10
	s_cselect_b32 s43, s9, s11
	s_cselect_b32 s45, s85, s94
	s_cselect_b32 s44, vcc_lo, vcc_hi
	s_add_u32 s38, s42, 0x80
	s_addc_u32 s39, s43, 0
	s_add_u32 s68, s44, 0x80
	s_addc_u32 s69, s45, 0
	s_add_i32 s35, 0, 0x10000
	s_add_i32 s49, 0, 0x14000
	v_add_u32_e32 v96, s35, v199
	v_add_u32_e32 v166, s49, v199
	ds_read_b128 v[138:141], v96
	ds_read_b128 v[142:145], v96 offset:1024
	ds_read_b128 v[146:149], v96 offset:2048
	ds_read_b128 v[150:153], v96 offset:3072
	s_waitcnt lgkmcnt(0)
	ds_read_b128 v[154:157], v166
	ds_read_b128 v[158:161], v166 offset:1024
	ds_read_b128 v[162:165], v166 offset:2048
	ds_read_b128 v[166:169], v166 offset:3072
	s_add_u32 s18, s18, 0x40000
	s_addc_u32 s19, s19, 0
	v_lshl_add_u64 v[186:187], s[18:19], 0, v[130:131]
	s_add_i32 m0, s73, 0xc000
	ds_read_b128 v[170:173], v200
	ds_read_b128 v[174:177], v200 offset:1024
	ds_read_b128 v[178:181], v200 offset:2048
	ds_read_b128 v[182:185], v200 offset:3072
	ds_read_b128 v[190:193], v200 offset:4096
	ds_read_b128 v[194:197], v200 offset:5120
	ds_read_b128 v[202:205], v200 offset:6144
	ds_read_b128 v[206:209], v200 offset:7168
	global_load_lds_dwordx4 v[186:187], off
	v_lshl_add_u64 v[186:187], s[18:19], 0, v[134:135]
	s_add_i32 m0, s73, 0xe000
	s_nop 0
	global_load_lds_dwordx4 v[186:187], off
	s_waitcnt vmcnt(8)
	s_waitcnt lgkmcnt(0)
	s_barrier
	s_setprio 1
	s_waitcnt lgkmcnt(0)
	v_mfma_f32_16x16x32_bf16 v[126:129], v[138:141], v[170:173], v[126:129]
	v_mfma_f32_16x16x32_bf16 v[122:125], v[146:149], v[170:173], v[122:125]
	v_mfma_f32_16x16x32_bf16 v[118:121], v[138:141], v[178:181], v[118:121]
	v_mfma_f32_16x16x32_bf16 v[110:113], v[146:149], v[178:181], v[110:113]
	v_mfma_f32_16x16x32_bf16 v[102:105], v[138:141], v[190:193], v[102:105]
	v_mfma_f32_16x16x32_bf16 v[92:95], v[146:149], v[190:193], v[92:95]
	v_mfma_f32_16x16x32_bf16 v[84:87], v[138:141], v[202:205], v[84:87]
	v_mfma_f32_16x16x32_bf16 v[76:79], v[146:149], v[202:205], v[76:79]
	v_mfma_f32_16x16x32_bf16 v[126:129], v[142:145], v[174:177], v[126:129]
	v_mfma_f32_16x16x32_bf16 v[122:125], v[150:153], v[174:177], v[122:125]
	v_mfma_f32_16x16x32_bf16 v[118:121], v[142:145], v[182:185], v[118:121]
	v_mfma_f32_16x16x32_bf16 v[110:113], v[150:153], v[182:185], v[110:113]
	v_mfma_f32_16x16x32_bf16 v[102:105], v[142:145], v[194:197], v[102:105]
	v_mfma_f32_16x16x32_bf16 v[92:95], v[150:153], v[194:197], v[92:95]
	v_mfma_f32_16x16x32_bf16 v[84:87], v[142:145], v[206:209], v[84:87]
	v_mfma_f32_16x16x32_bf16 v[76:79], v[150:153], v[206:209], v[76:79]
	v_mfma_f32_16x16x32_bf16 v[114:117], v[154:157], v[170:173], v[114:117]
	v_mfma_f32_16x16x32_bf16 v[106:109], v[162:165], v[170:173], v[106:109]
	v_mfma_f32_16x16x32_bf16 v[98:101], v[154:157], v[178:181], v[98:101]
	v_mfma_f32_16x16x32_bf16 v[88:91], v[162:165], v[178:181], v[88:91]
	v_mfma_f32_16x16x32_bf16 v[80:83], v[154:157], v[190:193], v[80:83]
	v_mfma_f32_16x16x32_bf16 v[72:75], v[162:165], v[190:193], v[72:75]
	v_mfma_f32_16x16x32_bf16 v[68:71], v[154:157], v[202:205], v[68:71]
	v_mfma_f32_16x16x32_bf16 v[64:67], v[162:165], v[202:205], v[64:67]
	v_mfma_f32_16x16x32_bf16 v[114:117], v[158:161], v[174:177], v[114:117]
	v_mfma_f32_16x16x32_bf16 v[106:109], v[166:169], v[174:177], v[106:109]
	s_barrier
	v_mfma_f32_16x16x32_bf16 v[98:101], v[158:161], v[182:185], v[98:101]
	v_mfma_f32_16x16x32_bf16 v[88:91], v[166:169], v[182:185], v[88:91]
	v_mfma_f32_16x16x32_bf16 v[80:83], v[158:161], v[194:197], v[80:83]
	v_mfma_f32_16x16x32_bf16 v[72:75], v[166:169], v[194:197], v[72:75]
	v_mfma_f32_16x16x32_bf16 v[68:71], v[158:161], v[206:209], v[68:71]
	v_mfma_f32_16x16x32_bf16 v[64:67], v[166:169], v[206:209], v[64:67]
	s_setprio 0
	s_add_i32 s18, s35, s72
	v_lshl_add_u64 v[186:187], s[44:45], 0, v[132:133]
	s_mov_b32 m0, s18
	ds_read_b128 v[170:173], v200 offset:16384
	ds_read_b128 v[174:177], v200 offset:17408
	ds_read_b128 v[178:181], v200 offset:18432
	ds_read_b128 v[182:185], v200 offset:19456
	ds_read_b128 v[190:193], v200 offset:20480
	ds_read_b128 v[194:197], v200 offset:21504
	ds_read_b128 v[202:205], v200 offset:22528
	ds_read_b128 v[206:209], v200 offset:23552
	global_load_lds_dwordx4 v[186:187], off
	s_add_i32 m0, s18, 0x2000
	s_add_u32 s18, s44, 0x40000
	v_lshl_add_u64 v[186:187], s[44:45], 0, v[136:137]
	s_addc_u32 s19, s45, 0
	s_add_i32 s35, s49, s72
	global_load_lds_dwordx4 v[186:187], off
	v_lshl_add_u64 v[186:187], s[18:19], 0, v[132:133]
	s_mov_b32 m0, s35
	s_nop 0
	global_load_lds_dwordx4 v[186:187], off
	v_lshl_add_u64 v[186:187], s[18:19], 0, v[136:137]
	s_add_i32 m0, s35, 0x2000
	s_nop 0
	global_load_lds_dwordx4 v[186:187], off
	v_lshl_add_u64 v[186:187], s[42:43], 0, v[130:131]
	s_mov_b32 m0, s73
	s_nop 0
	global_load_lds_dwordx4 v[186:187], off
	v_lshl_add_u64 v[186:187], s[42:43], 0, v[134:135]
	s_mov_b32 m0, s74
	s_nop 0
	global_load_lds_dwordx4 v[186:187], off
	s_waitcnt vmcnt(8)
	s_waitcnt lgkmcnt(0)
	s_barrier
	s_setprio 1
	s_waitcnt lgkmcnt(0)
	v_mfma_f32_16x16x32_bf16 v[60:63], v[138:141], v[170:173], v[60:63]
	v_mfma_f32_16x16x32_bf16 v[56:59], v[146:149], v[170:173], v[56:59]
	v_mfma_f32_16x16x32_bf16 v[52:55], v[138:141], v[178:181], v[52:55]
	v_mfma_f32_16x16x32_bf16 v[44:47], v[146:149], v[178:181], v[44:47]
	v_mfma_f32_16x16x32_bf16 v[36:39], v[138:141], v[190:193], v[36:39]
	v_mfma_f32_16x16x32_bf16 v[28:31], v[146:149], v[190:193], v[28:31]
	v_mfma_f32_16x16x32_bf16 v[20:23], v[138:141], v[202:205], v[20:23]
	v_mfma_f32_16x16x32_bf16 v[12:15], v[146:149], v[202:205], v[12:15]
	v_mfma_f32_16x16x32_bf16 v[60:63], v[142:145], v[174:177], v[60:63]
	v_mfma_f32_16x16x32_bf16 v[56:59], v[150:153], v[174:177], v[56:59]
	v_mfma_f32_16x16x32_bf16 v[52:55], v[142:145], v[182:185], v[52:55]
	v_mfma_f32_16x16x32_bf16 v[44:47], v[150:153], v[182:185], v[44:47]
	v_mfma_f32_16x16x32_bf16 v[36:39], v[142:145], v[194:197], v[36:39]
	v_mfma_f32_16x16x32_bf16 v[28:31], v[150:153], v[194:197], v[28:31]
	v_mfma_f32_16x16x32_bf16 v[20:23], v[142:145], v[206:209], v[20:23]
	v_mfma_f32_16x16x32_bf16 v[12:15], v[150:153], v[206:209], v[12:15]
	v_mfma_f32_16x16x32_bf16 v[48:51], v[154:157], v[170:173], v[48:51]
	v_mfma_f32_16x16x32_bf16 v[40:43], v[162:165], v[170:173], v[40:43]
	v_mfma_f32_16x16x32_bf16 v[32:35], v[154:157], v[178:181], v[32:35]
	v_mfma_f32_16x16x32_bf16 v[24:27], v[162:165], v[178:181], v[24:27]
	v_mfma_f32_16x16x32_bf16 v[16:19], v[154:157], v[190:193], v[16:19]
	v_mfma_f32_16x16x32_bf16 v[8:11], v[162:165], v[190:193], v[8:11]
	v_mfma_f32_16x16x32_bf16 v[4:7], v[154:157], v[202:205], v[4:7]
	v_mfma_f32_16x16x32_bf16 v[0:3], v[162:165], v[202:205], v[0:3]
	v_mfma_f32_16x16x32_bf16 v[48:51], v[158:161], v[174:177], v[48:51]
	v_mfma_f32_16x16x32_bf16 v[40:43], v[166:169], v[174:177], v[40:43]
	s_barrier
	v_mfma_f32_16x16x32_bf16 v[32:35], v[158:161], v[182:185], v[32:35]
	v_mfma_f32_16x16x32_bf16 v[24:27], v[166:169], v[182:185], v[24:27]
	v_mfma_f32_16x16x32_bf16 v[16:19], v[158:161], v[194:197], v[16:19]
	v_mfma_f32_16x16x32_bf16 v[8:11], v[166:169], v[194:197], v[8:11]
	v_mfma_f32_16x16x32_bf16 v[4:7], v[158:161], v[206:209], v[4:7]
	v_mfma_f32_16x16x32_bf16 v[0:3], v[166:169], v[206:209], v[0:3]
	s_setprio 0
	s_add_i32 s35, 0, 0x18000
	v_add_u32_e32 v96, s35, v199
	s_add_i32 s44, 0, 0x1c000
	ds_read_b128 v[138:141], v96
	ds_read_b128 v[142:145], v96 offset:1024
	ds_read_b128 v[146:149], v96 offset:2048
	ds_read_b128 v[150:153], v96 offset:3072
	v_add_u32_e32 v96, s44, v199
	ds_read_b128 v[154:157], v96
	ds_read_b128 v[158:161], v96 offset:1024
	ds_read_b128 v[162:165], v96 offset:2048
	ds_read_b128 v[166:169], v96 offset:3072
	s_add_u32 s18, s42, 0x40000
	s_addc_u32 s19, s43, 0
	s_mov_b32 m0, s75
	v_lshl_add_u64 v[186:187], s[18:19], 0, v[130:131]
	ds_read_b128 v[170:173], v200 offset:32768
	ds_read_b128 v[174:177], v200 offset:33792
	ds_read_b128 v[178:181], v200 offset:34816
	ds_read_b128 v[182:185], v200 offset:35840
	ds_read_b128 v[190:193], v200 offset:36864
	ds_read_b128 v[194:197], v200 offset:37888
	ds_read_b128 v[202:205], v200 offset:38912
	ds_read_b128 v[206:209], v200 offset:39936
	global_load_lds_dwordx4 v[186:187], off
	v_lshl_add_u64 v[186:187], s[18:19], 0, v[134:135]
	s_mov_b32 m0, s83
	s_nop 0
	global_load_lds_dwordx4 v[186:187], off
	s_waitcnt vmcnt(8)
	s_waitcnt lgkmcnt(0)
	s_barrier
	s_setprio 1
	s_waitcnt lgkmcnt(0)
	v_mfma_f32_16x16x32_bf16 v[126:129], v[138:141], v[170:173], v[126:129]
	v_mfma_f32_16x16x32_bf16 v[122:125], v[146:149], v[170:173], v[122:125]
	v_mfma_f32_16x16x32_bf16 v[118:121], v[138:141], v[178:181], v[118:121]
	v_mfma_f32_16x16x32_bf16 v[110:113], v[146:149], v[178:181], v[110:113]
	v_mfma_f32_16x16x32_bf16 v[102:105], v[138:141], v[190:193], v[102:105]
	v_mfma_f32_16x16x32_bf16 v[92:95], v[146:149], v[190:193], v[92:95]
	v_mfma_f32_16x16x32_bf16 v[84:87], v[138:141], v[202:205], v[84:87]
	v_mfma_f32_16x16x32_bf16 v[76:79], v[146:149], v[202:205], v[76:79]
	v_mfma_f32_16x16x32_bf16 v[126:129], v[142:145], v[174:177], v[126:129]
	v_mfma_f32_16x16x32_bf16 v[122:125], v[150:153], v[174:177], v[122:125]
	v_mfma_f32_16x16x32_bf16 v[118:121], v[142:145], v[182:185], v[118:121]
	v_mfma_f32_16x16x32_bf16 v[110:113], v[150:153], v[182:185], v[110:113]
	v_mfma_f32_16x16x32_bf16 v[102:105], v[142:145], v[194:197], v[102:105]
	v_mfma_f32_16x16x32_bf16 v[92:95], v[150:153], v[194:197], v[92:95]
	v_mfma_f32_16x16x32_bf16 v[84:87], v[142:145], v[206:209], v[84:87]
	v_mfma_f32_16x16x32_bf16 v[76:79], v[150:153], v[206:209], v[76:79]
	v_mfma_f32_16x16x32_bf16 v[114:117], v[154:157], v[170:173], v[114:117]
	v_mfma_f32_16x16x32_bf16 v[106:109], v[162:165], v[170:173], v[106:109]
	v_mfma_f32_16x16x32_bf16 v[98:101], v[154:157], v[178:181], v[98:101]
	v_mfma_f32_16x16x32_bf16 v[88:91], v[162:165], v[178:181], v[88:91]
	v_mfma_f32_16x16x32_bf16 v[80:83], v[154:157], v[190:193], v[80:83]
	v_mfma_f32_16x16x32_bf16 v[72:75], v[162:165], v[190:193], v[72:75]
	v_mfma_f32_16x16x32_bf16 v[68:71], v[154:157], v[202:205], v[68:71]
	v_mfma_f32_16x16x32_bf16 v[64:67], v[162:165], v[202:205], v[64:67]
	v_mfma_f32_16x16x32_bf16 v[114:117], v[158:161], v[174:177], v[114:117]
	v_mfma_f32_16x16x32_bf16 v[106:109], v[166:169], v[174:177], v[106:109]
	s_barrier
	v_mfma_f32_16x16x32_bf16 v[98:101], v[158:161], v[182:185], v[98:101]
	v_mfma_f32_16x16x32_bf16 v[88:91], v[166:169], v[182:185], v[88:91]
	v_mfma_f32_16x16x32_bf16 v[80:83], v[158:161], v[194:197], v[80:83]
	v_mfma_f32_16x16x32_bf16 v[72:75], v[166:169], v[194:197], v[72:75]
	v_mfma_f32_16x16x32_bf16 v[68:71], v[158:161], v[206:209], v[68:71]
	v_mfma_f32_16x16x32_bf16 v[64:67], v[166:169], v[206:209], v[64:67]
	s_setprio 0
	s_add_i32 s18, s35, s72
	v_lshl_add_u64 v[186:187], s[68:69], 0, v[132:133]
	s_mov_b32 m0, s18
	ds_read_b128 v[170:173], v200 offset:49152
	ds_read_b128 v[174:177], v200 offset:50176
	ds_read_b128 v[178:181], v200 offset:51200
	ds_read_b128 v[182:185], v200 offset:52224
	ds_read_b128 v[190:193], v200 offset:53248
	ds_read_b128 v[194:197], v200 offset:54272
	ds_read_b128 v[202:205], v200 offset:55296
	ds_read_b128 v[206:209], v200 offset:56320
	global_load_lds_dwordx4 v[186:187], off
	s_add_i32 m0, s18, 0x2000
	s_add_u32 s18, s68, 0x40000
	v_lshl_add_u64 v[186:187], s[68:69], 0, v[136:137]
	s_addc_u32 s19, s69, 0
	s_add_i32 s35, s44, s72
	global_load_lds_dwordx4 v[186:187], off
	v_lshl_add_u64 v[186:187], s[18:19], 0, v[132:133]
	s_mov_b32 m0, s35
	s_nop 0
	global_load_lds_dwordx4 v[186:187], off
	v_lshl_add_u64 v[186:187], s[18:19], 0, v[136:137]
	s_add_i32 m0, s35, 0x2000
	s_nop 0
	global_load_lds_dwordx4 v[186:187], off
	v_lshl_add_u64 v[186:187], s[38:39], 0, v[130:131]
	s_mov_b32 m0, s29
	s_nop 0
	global_load_lds_dwordx4 v[186:187], off
	v_lshl_add_u64 v[186:187], s[38:39], 0, v[134:135]
	s_mov_b32 m0, s16
	s_nop 0
	global_load_lds_dwordx4 v[186:187], off
	s_waitcnt vmcnt(8)
	s_waitcnt lgkmcnt(0)
	s_barrier
	s_setprio 1
	s_waitcnt lgkmcnt(0)
	v_mfma_f32_16x16x32_bf16 v[60:63], v[138:141], v[170:173], v[60:63]
	v_mfma_f32_16x16x32_bf16 v[56:59], v[146:149], v[170:173], v[56:59]
	v_mfma_f32_16x16x32_bf16 v[52:55], v[138:141], v[178:181], v[52:55]
	v_mfma_f32_16x16x32_bf16 v[44:47], v[146:149], v[178:181], v[44:47]
	v_mfma_f32_16x16x32_bf16 v[36:39], v[138:141], v[190:193], v[36:39]
	v_mfma_f32_16x16x32_bf16 v[28:31], v[146:149], v[190:193], v[28:31]
	v_mfma_f32_16x16x32_bf16 v[20:23], v[138:141], v[202:205], v[20:23]
	v_mfma_f32_16x16x32_bf16 v[12:15], v[146:149], v[202:205], v[12:15]
	v_mfma_f32_16x16x32_bf16 v[60:63], v[142:145], v[174:177], v[60:63]
	v_mfma_f32_16x16x32_bf16 v[56:59], v[150:153], v[174:177], v[56:59]
	v_mfma_f32_16x16x32_bf16 v[52:55], v[142:145], v[182:185], v[52:55]
	v_mfma_f32_16x16x32_bf16 v[44:47], v[150:153], v[182:185], v[44:47]
	v_mfma_f32_16x16x32_bf16 v[36:39], v[142:145], v[194:197], v[36:39]
	v_mfma_f32_16x16x32_bf16 v[28:31], v[150:153], v[194:197], v[28:31]
	v_mfma_f32_16x16x32_bf16 v[20:23], v[142:145], v[206:209], v[20:23]
	v_mfma_f32_16x16x32_bf16 v[12:15], v[150:153], v[206:209], v[12:15]
	v_mfma_f32_16x16x32_bf16 v[48:51], v[154:157], v[170:173], v[48:51]
	v_mfma_f32_16x16x32_bf16 v[40:43], v[162:165], v[170:173], v[40:43]
	v_mfma_f32_16x16x32_bf16 v[32:35], v[154:157], v[178:181], v[32:35]
	v_mfma_f32_16x16x32_bf16 v[24:27], v[162:165], v[178:181], v[24:27]
	v_mfma_f32_16x16x32_bf16 v[16:19], v[154:157], v[190:193], v[16:19]
	v_mfma_f32_16x16x32_bf16 v[8:11], v[162:165], v[190:193], v[8:11]
	v_mfma_f32_16x16x32_bf16 v[4:7], v[154:157], v[202:205], v[4:7]
	v_mfma_f32_16x16x32_bf16 v[0:3], v[162:165], v[202:205], v[0:3]
	v_mfma_f32_16x16x32_bf16 v[48:51], v[158:161], v[174:177], v[48:51]
	v_mfma_f32_16x16x32_bf16 v[40:43], v[166:169], v[174:177], v[40:43]
	s_barrier
	v_mfma_f32_16x16x32_bf16 v[32:35], v[158:161], v[182:185], v[32:35]
	v_mfma_f32_16x16x32_bf16 v[24:27], v[166:169], v[182:185], v[24:27]
	v_mfma_f32_16x16x32_bf16 v[16:19], v[158:161], v[194:197], v[16:19]
	v_mfma_f32_16x16x32_bf16 v[8:11], v[166:169], v[194:197], v[8:11]
	v_mfma_f32_16x16x32_bf16 v[4:7], v[158:161], v[206:209], v[4:7]
	v_mfma_f32_16x16x32_bf16 v[0:3], v[166:169], v[206:209], v[0:3]
	s_setprio 0
	s_add_i32 s92, s92, 2
	s_add_u32 vcc_hi, vcc_hi, 0x100
	s_addc_u32 s94, s94, 0
	s_cmp_gt_u32 s92, 13
	s_cbranch_scc0 .LBB0_433
	s_and_b64 vcc, exec, s[76:77]
	s_cbranch_vccz .LBB0_436
	s_barrier

.LBB0_703:
	s_cmp_eq_u32 s85, 40
	s_cselect_b32 s42, s8, s81
	s_cselect_b32 s43, s9, s82
	s_cselect_b32 s45, s59, s84
	s_cselect_b32 s44, s58, s83
	s_add_u32 s38, s42, 0x80
	s_addc_u32 s39, s43, 0
	s_add_u32 s62, s44, 0x80
	s_addc_u32 s63, s45, 0
	s_add_i32 s35, 0, 0x10000
	s_mov_b64 s[18:19], s[60:61]
	v_add_u32_e32 v140, s35, v142
	s_add_i32 s49, 0, 0x14000
	ds_read_b128 v[136:139], v140
	ds_read_b128 v[144:147], v140 offset:1024
	ds_read_b128 v[148:151], v140 offset:2048
	ds_read_b128 v[152:155], v140 offset:3072
	v_add_u32_e32 v140, s49, v142
	ds_read_b128 v[156:159], v140
	ds_read_b128 v[160:163], v140 offset:1024
	ds_read_b128 v[164:167], v140 offset:2048
	ds_read_b128 v[168:171], v140 offset:3072
	s_add_u32 s18, s18, 0xb0000
	s_addc_u32 s19, s19, 0
	v_lshl_add_u64 v[140:141], s[18:19], 0, v[130:131]
	s_add_i32 m0, s66, 0xc000
	ds_read_b128 v[172:175], v143
	ds_read_b128 v[176:179], v143 offset:1024
	ds_read_b128 v[180:183], v143 offset:2048
	ds_read_b128 v[190:193], v143 offset:3072
	ds_read_b128 v[194:197], v143 offset:4096
	ds_read_b128 v[198:201], v143 offset:5120
	ds_read_b128 v[202:205], v143 offset:6144
	ds_read_b128 v[206:209], v143 offset:7168
	global_load_lds_dwordx4 v[140:141], off
	v_lshl_add_u64 v[140:141], s[18:19], 0, v[132:133]
	s_add_i32 m0, s66, 0xe000
	s_nop 0
	global_load_lds_dwordx4 v[140:141], off
	s_waitcnt vmcnt(8)
	s_waitcnt lgkmcnt(0)
	s_barrier
	s_setprio 1
	s_waitcnt lgkmcnt(0)
	v_mfma_f32_16x16x32_bf16 v[126:129], v[136:139], v[172:175], v[126:129]
	v_mfma_f32_16x16x32_bf16 v[122:125], v[148:151], v[172:175], v[122:125]
	v_mfma_f32_16x16x32_bf16 v[110:113], v[136:139], v[180:183], v[110:113]
	v_mfma_f32_16x16x32_bf16 v[106:109], v[148:151], v[180:183], v[106:109]
	v_mfma_f32_16x16x32_bf16 v[92:95], v[136:139], v[194:197], v[92:95]
	v_mfma_f32_16x16x32_bf16 v[88:91], v[148:151], v[194:197], v[88:91]
	v_mfma_f32_16x16x32_bf16 v[76:79], v[136:139], v[202:205], v[76:79]
	v_mfma_f32_16x16x32_bf16 v[72:75], v[148:151], v[202:205], v[72:75]
	v_mfma_f32_16x16x32_bf16 v[126:129], v[144:147], v[176:179], v[126:129]
	v_mfma_f32_16x16x32_bf16 v[122:125], v[152:155], v[176:179], v[122:125]
	v_mfma_f32_16x16x32_bf16 v[110:113], v[144:147], v[190:193], v[110:113]
	v_mfma_f32_16x16x32_bf16 v[106:109], v[152:155], v[190:193], v[106:109]
	v_mfma_f32_16x16x32_bf16 v[92:95], v[144:147], v[198:201], v[92:95]
	v_mfma_f32_16x16x32_bf16 v[88:91], v[152:155], v[198:201], v[88:91]
	v_mfma_f32_16x16x32_bf16 v[76:79], v[144:147], v[206:209], v[76:79]
	v_mfma_f32_16x16x32_bf16 v[72:75], v[152:155], v[206:209], v[72:75]
	v_mfma_f32_16x16x32_bf16 v[118:121], v[156:159], v[172:175], v[118:121]
	v_mfma_f32_16x16x32_bf16 v[114:117], v[164:167], v[172:175], v[114:117]
	v_mfma_f32_16x16x32_bf16 v[102:105], v[156:159], v[180:183], v[102:105]
	v_mfma_f32_16x16x32_bf16 v[98:101], v[164:167], v[180:183], v[98:101]
	v_mfma_f32_16x16x32_bf16 v[84:87], v[156:159], v[194:197], v[84:87]
	v_mfma_f32_16x16x32_bf16 v[80:83], v[164:167], v[194:197], v[80:83]
	v_mfma_f32_16x16x32_bf16 v[68:71], v[156:159], v[202:205], v[68:71]
	v_mfma_f32_16x16x32_bf16 v[64:67], v[164:167], v[202:205], v[64:67]
	v_mfma_f32_16x16x32_bf16 v[118:121], v[160:163], v[176:179], v[118:121]
	v_mfma_f32_16x16x32_bf16 v[114:117], v[168:171], v[176:179], v[114:117]
	s_barrier
	v_mfma_f32_16x16x32_bf16 v[102:105], v[160:163], v[190:193], v[102:105]
	v_mfma_f32_16x16x32_bf16 v[98:101], v[168:171], v[190:193], v[98:101]
	v_mfma_f32_16x16x32_bf16 v[84:87], v[160:163], v[198:201], v[84:87]
	v_mfma_f32_16x16x32_bf16 v[80:83], v[168:171], v[198:201], v[80:83]
	v_mfma_f32_16x16x32_bf16 v[68:71], v[160:163], v[206:209], v[68:71]
	v_mfma_f32_16x16x32_bf16 v[64:67], v[168:171], v[206:209], v[64:67]
	s_setprio 0
	s_add_i32 s18, s35, s14
	v_lshl_add_u64 v[140:141], s[44:45], 0, v[96:97]
	s_mov_b32 m0, s18
	ds_read_b128 v[172:175], v143 offset:16384
	ds_read_b128 v[176:179], v143 offset:17408
	ds_read_b128 v[180:183], v143 offset:18432
	ds_read_b128 v[190:193], v143 offset:19456
	ds_read_b128 v[194:197], v143 offset:20480
	ds_read_b128 v[198:201], v143 offset:21504
	ds_read_b128 v[202:205], v143 offset:22528
	ds_read_b128 v[206:209], v143 offset:23552
	global_load_lds_dwordx4 v[140:141], off
	s_add_i32 m0, s18, 0x2000
	s_add_u32 s18, s44, 0xb0000
	v_lshl_add_u64 v[140:141], s[44:45], 0, v[134:135]
	s_addc_u32 s19, s45, 0
	s_add_i32 s35, s49, s14
	global_load_lds_dwordx4 v[140:141], off
	v_lshl_add_u64 v[140:141], s[18:19], 0, v[96:97]
	s_mov_b32 m0, s35
	s_nop 0
	global_load_lds_dwordx4 v[140:141], off
	v_lshl_add_u64 v[140:141], s[18:19], 0, v[134:135]
	s_add_i32 m0, s35, 0x2000
	s_nop 0
	global_load_lds_dwordx4 v[140:141], off
	v_lshl_add_u64 v[140:141], s[42:43], 0, v[130:131]
	s_mov_b32 m0, s66
	s_nop 0
	global_load_lds_dwordx4 v[140:141], off
	v_lshl_add_u64 v[140:141], s[42:43], 0, v[132:133]
	s_mov_b32 m0, s67
	s_nop 0
	global_load_lds_dwordx4 v[140:141], off
	s_waitcnt vmcnt(8)
	s_waitcnt lgkmcnt(0)
	s_barrier
	s_setprio 1
	s_waitcnt lgkmcnt(0)
	v_mfma_f32_16x16x32_bf16 v[60:63], v[136:139], v[172:175], v[60:63]
	v_mfma_f32_16x16x32_bf16 v[56:59], v[148:151], v[172:175], v[56:59]
	v_mfma_f32_16x16x32_bf16 v[44:47], v[136:139], v[180:183], v[44:47]
	v_mfma_f32_16x16x32_bf16 v[40:43], v[148:151], v[180:183], v[40:43]
	v_mfma_f32_16x16x32_bf16 v[28:31], v[136:139], v[194:197], v[28:31]
	v_mfma_f32_16x16x32_bf16 v[24:27], v[148:151], v[194:197], v[24:27]
	v_mfma_f32_16x16x32_bf16 v[12:15], v[136:139], v[202:205], v[12:15]
	v_mfma_f32_16x16x32_bf16 v[8:11], v[148:151], v[202:205], v[8:11]
	v_mfma_f32_16x16x32_bf16 v[60:63], v[144:147], v[176:179], v[60:63]
	v_mfma_f32_16x16x32_bf16 v[56:59], v[152:155], v[176:179], v[56:59]
	v_mfma_f32_16x16x32_bf16 v[44:47], v[144:147], v[190:193], v[44:47]
	v_mfma_f32_16x16x32_bf16 v[40:43], v[152:155], v[190:193], v[40:43]
	v_mfma_f32_16x16x32_bf16 v[28:31], v[144:147], v[198:201], v[28:31]
	v_mfma_f32_16x16x32_bf16 v[24:27], v[152:155], v[198:201], v[24:27]
	v_mfma_f32_16x16x32_bf16 v[12:15], v[144:147], v[206:209], v[12:15]
	v_mfma_f32_16x16x32_bf16 v[8:11], v[152:155], v[206:209], v[8:11]
	v_mfma_f32_16x16x32_bf16 v[52:55], v[156:159], v[172:175], v[52:55]
	v_mfma_f32_16x16x32_bf16 v[48:51], v[164:167], v[172:175], v[48:51]
	v_mfma_f32_16x16x32_bf16 v[36:39], v[156:159], v[180:183], v[36:39]
	v_mfma_f32_16x16x32_bf16 v[32:35], v[164:167], v[180:183], v[32:35]
	v_mfma_f32_16x16x32_bf16 v[20:23], v[156:159], v[194:197], v[20:23]
	v_mfma_f32_16x16x32_bf16 v[16:19], v[164:167], v[194:197], v[16:19]
	v_mfma_f32_16x16x32_bf16 v[4:7], v[156:159], v[202:205], v[4:7]
	v_mfma_f32_16x16x32_bf16 v[0:3], v[164:167], v[202:205], v[0:3]
	v_mfma_f32_16x16x32_bf16 v[52:55], v[160:163], v[176:179], v[52:55]
	v_mfma_f32_16x16x32_bf16 v[48:51], v[168:171], v[176:179], v[48:51]
	s_barrier
	v_mfma_f32_16x16x32_bf16 v[36:39], v[160:163], v[190:193], v[36:39]
	v_mfma_f32_16x16x32_bf16 v[32:35], v[168:171], v[190:193], v[32:35]
	v_mfma_f32_16x16x32_bf16 v[20:23], v[160:163], v[198:201], v[20:23]
	v_mfma_f32_16x16x32_bf16 v[16:19], v[168:171], v[198:201], v[16:19]
	v_mfma_f32_16x16x32_bf16 v[4:7], v[160:163], v[206:209], v[4:7]
	v_mfma_f32_16x16x32_bf16 v[0:3], v[168:171], v[206:209], v[0:3]
	s_setprio 0
	s_add_i32 s35, 0, 0x18000
	v_add_u32_e32 v140, s35, v142
	s_add_i32 s44, 0, 0x1c000
	ds_read_b128 v[136:139], v140
	ds_read_b128 v[144:147], v140 offset:1024
	ds_read_b128 v[148:151], v140 offset:2048
	ds_read_b128 v[152:155], v140 offset:3072
	v_add_u32_e32 v140, s44, v142
	ds_read_b128 v[156:159], v140
	ds_read_b128 v[160:163], v140 offset:1024
	ds_read_b128 v[164:167], v140 offset:2048
	ds_read_b128 v[168:171], v140 offset:3072
	s_add_u32 s18, s42, 0xb0000
	s_addc_u32 s19, s43, 0
	s_mov_b32 m0, s68
	v_lshl_add_u64 v[140:141], s[18:19], 0, v[130:131]
	ds_read_b128 v[172:175], v143 offset:32768
	ds_read_b128 v[176:179], v143 offset:33792
	ds_read_b128 v[180:183], v143 offset:34816
	ds_read_b128 v[190:193], v143 offset:35840
	ds_read_b128 v[194:197], v143 offset:36864
	ds_read_b128 v[198:201], v143 offset:37888
	ds_read_b128 v[202:205], v143 offset:38912
	ds_read_b128 v[206:209], v143 offset:39936
	global_load_lds_dwordx4 v[140:141], off
	v_lshl_add_u64 v[140:141], s[18:19], 0, v[132:133]
	s_mov_b32 m0, s69
	s_nop 0
	global_load_lds_dwordx4 v[140:141], off
	s_waitcnt vmcnt(8)
	s_waitcnt lgkmcnt(0)
	s_barrier
	s_setprio 1
	s_waitcnt lgkmcnt(0)
	v_mfma_f32_16x16x32_bf16 v[126:129], v[136:139], v[172:175], v[126:129]
	v_mfma_f32_16x16x32_bf16 v[122:125], v[148:151], v[172:175], v[122:125]
	v_mfma_f32_16x16x32_bf16 v[110:113], v[136:139], v[180:183], v[110:113]
	v_mfma_f32_16x16x32_bf16 v[106:109], v[148:151], v[180:183], v[106:109]
	v_mfma_f32_16x16x32_bf16 v[92:95], v[136:139], v[194:197], v[92:95]
	v_mfma_f32_16x16x32_bf16 v[88:91], v[148:151], v[194:197], v[88:91]
	v_mfma_f32_16x16x32_bf16 v[76:79], v[136:139], v[202:205], v[76:79]
	v_mfma_f32_16x16x32_bf16 v[72:75], v[148:151], v[202:205], v[72:75]
	v_mfma_f32_16x16x32_bf16 v[126:129], v[144:147], v[176:179], v[126:129]
	v_mfma_f32_16x16x32_bf16 v[122:125], v[152:155], v[176:179], v[122:125]
	v_mfma_f32_16x16x32_bf16 v[110:113], v[144:147], v[190:193], v[110:113]
	v_mfma_f32_16x16x32_bf16 v[106:109], v[152:155], v[190:193], v[106:109]
	v_mfma_f32_16x16x32_bf16 v[92:95], v[144:147], v[198:201], v[92:95]
	v_mfma_f32_16x16x32_bf16 v[88:91], v[152:155], v[198:201], v[88:91]
	v_mfma_f32_16x16x32_bf16 v[76:79], v[144:147], v[206:209], v[76:79]
	v_mfma_f32_16x16x32_bf16 v[72:75], v[152:155], v[206:209], v[72:75]
	v_mfma_f32_16x16x32_bf16 v[118:121], v[156:159], v[172:175], v[118:121]
	v_mfma_f32_16x16x32_bf16 v[114:117], v[164:167], v[172:175], v[114:117]
	v_mfma_f32_16x16x32_bf16 v[102:105], v[156:159], v[180:183], v[102:105]
	v_mfma_f32_16x16x32_bf16 v[98:101], v[164:167], v[180:183], v[98:101]
	v_mfma_f32_16x16x32_bf16 v[84:87], v[156:159], v[194:197], v[84:87]
	v_mfma_f32_16x16x32_bf16 v[80:83], v[164:167], v[194:197], v[80:83]
	v_mfma_f32_16x16x32_bf16 v[68:71], v[156:159], v[202:205], v[68:71]
	v_mfma_f32_16x16x32_bf16 v[64:67], v[164:167], v[202:205], v[64:67]
	v_mfma_f32_16x16x32_bf16 v[118:121], v[160:163], v[176:179], v[118:121]
	v_mfma_f32_16x16x32_bf16 v[114:117], v[168:171], v[176:179], v[114:117]
	s_barrier
	v_mfma_f32_16x16x32_bf16 v[102:105], v[160:163], v[190:193], v[102:105]
	v_mfma_f32_16x16x32_bf16 v[98:101], v[168:171], v[190:193], v[98:101]
	v_mfma_f32_16x16x32_bf16 v[84:87], v[160:163], v[198:201], v[84:87]
	v_mfma_f32_16x16x32_bf16 v[80:83], v[168:171], v[198:201], v[80:83]
	v_mfma_f32_16x16x32_bf16 v[68:71], v[160:163], v[206:209], v[68:71]
	v_mfma_f32_16x16x32_bf16 v[64:67], v[168:171], v[206:209], v[64:67]
	s_setprio 0
	s_add_i32 s18, s35, s14
	v_lshl_add_u64 v[140:141], s[62:63], 0, v[96:97]
	s_mov_b32 m0, s18
	ds_read_b128 v[172:175], v143 offset:49152
	ds_read_b128 v[176:179], v143 offset:50176
	ds_read_b128 v[180:183], v143 offset:51200
	ds_read_b128 v[190:193], v143 offset:52224
	ds_read_b128 v[194:197], v143 offset:53248
	ds_read_b128 v[198:201], v143 offset:54272
	ds_read_b128 v[202:205], v143 offset:55296
	ds_read_b128 v[206:209], v143 offset:56320
	global_load_lds_dwordx4 v[140:141], off
	s_add_i32 m0, s18, 0x2000
	s_add_u32 s18, s62, 0xb0000
	v_lshl_add_u64 v[140:141], s[62:63], 0, v[134:135]
	s_addc_u32 s19, s63, 0
	s_add_i32 s35, s44, s14
	global_load_lds_dwordx4 v[140:141], off
	v_lshl_add_u64 v[140:141], s[18:19], 0, v[96:97]
	s_mov_b32 m0, s35
	s_nop 0
	global_load_lds_dwordx4 v[140:141], off
	v_lshl_add_u64 v[140:141], s[18:19], 0, v[134:135]
	s_add_i32 m0, s35, 0x2000
	s_nop 0
	global_load_lds_dwordx4 v[140:141], off
	v_lshl_add_u64 v[140:141], s[38:39], 0, v[130:131]
	s_mov_b32 m0, s74
	s_nop 0
	global_load_lds_dwordx4 v[140:141], off
	v_lshl_add_u64 v[140:141], s[38:39], 0, v[132:133]
	s_mov_b32 m0, s75
	s_nop 0
	global_load_lds_dwordx4 v[140:141], off
	s_waitcnt vmcnt(8)
	s_waitcnt lgkmcnt(0)
	s_barrier
	s_setprio 1
	s_waitcnt lgkmcnt(0)
	v_mfma_f32_16x16x32_bf16 v[60:63], v[136:139], v[172:175], v[60:63]
	v_mfma_f32_16x16x32_bf16 v[56:59], v[148:151], v[172:175], v[56:59]
	v_mfma_f32_16x16x32_bf16 v[44:47], v[136:139], v[180:183], v[44:47]
	v_mfma_f32_16x16x32_bf16 v[40:43], v[148:151], v[180:183], v[40:43]
	v_mfma_f32_16x16x32_bf16 v[28:31], v[136:139], v[194:197], v[28:31]
	v_mfma_f32_16x16x32_bf16 v[24:27], v[148:151], v[194:197], v[24:27]
	v_mfma_f32_16x16x32_bf16 v[12:15], v[136:139], v[202:205], v[12:15]
	v_mfma_f32_16x16x32_bf16 v[8:11], v[148:151], v[202:205], v[8:11]
	v_mfma_f32_16x16x32_bf16 v[60:63], v[144:147], v[176:179], v[60:63]
	v_mfma_f32_16x16x32_bf16 v[56:59], v[152:155], v[176:179], v[56:59]
	v_mfma_f32_16x16x32_bf16 v[44:47], v[144:147], v[190:193], v[44:47]
	v_mfma_f32_16x16x32_bf16 v[40:43], v[152:155], v[190:193], v[40:43]
	v_mfma_f32_16x16x32_bf16 v[28:31], v[144:147], v[198:201], v[28:31]
	v_mfma_f32_16x16x32_bf16 v[24:27], v[152:155], v[198:201], v[24:27]
	v_mfma_f32_16x16x32_bf16 v[12:15], v[144:147], v[206:209], v[12:15]
	v_mfma_f32_16x16x32_bf16 v[8:11], v[152:155], v[206:209], v[8:11]
	v_mfma_f32_16x16x32_bf16 v[52:55], v[156:159], v[172:175], v[52:55]
	v_mfma_f32_16x16x32_bf16 v[48:51], v[164:167], v[172:175], v[48:51]
	v_mfma_f32_16x16x32_bf16 v[36:39], v[156:159], v[180:183], v[36:39]
	v_mfma_f32_16x16x32_bf16 v[32:35], v[164:167], v[180:183], v[32:35]
	v_mfma_f32_16x16x32_bf16 v[20:23], v[156:159], v[194:197], v[20:23]
	v_mfma_f32_16x16x32_bf16 v[16:19], v[164:167], v[194:197], v[16:19]
	v_mfma_f32_16x16x32_bf16 v[4:7], v[156:159], v[202:205], v[4:7]
	v_mfma_f32_16x16x32_bf16 v[0:3], v[164:167], v[202:205], v[0:3]
	v_mfma_f32_16x16x32_bf16 v[52:55], v[160:163], v[176:179], v[52:55]
	v_mfma_f32_16x16x32_bf16 v[48:51], v[168:171], v[176:179], v[48:51]
	s_barrier
	v_mfma_f32_16x16x32_bf16 v[36:39], v[160:163], v[190:193], v[36:39]
	v_mfma_f32_16x16x32_bf16 v[32:35], v[168:171], v[190:193], v[32:35]
	v_mfma_f32_16x16x32_bf16 v[20:23], v[160:163], v[198:201], v[20:23]
	v_mfma_f32_16x16x32_bf16 v[16:19], v[168:171], v[198:201], v[16:19]
	v_mfma_f32_16x16x32_bf16 v[4:7], v[160:163], v[206:209], v[4:7]
	v_mfma_f32_16x16x32_bf16 v[0:3], v[168:171], v[206:209], v[0:3]
	s_setprio 0
	s_add_i32 s85, s85, 2
	s_add_u32 s81, s81, 0x100
	s_addc_u32 s82, s82, 0
	s_add_u32 s83, s83, 0x100
	s_addc_u32 s84, s84, 0
	s_add_u32 s60, s60, 0x100
	s_addc_u32 s61, s61, 0
	s_cmp_gt_u32 s85, 41
	s_cbranch_scc0 .LBB0_703
	s_and_b64 vcc, exec, s[30:31]
	s_cbranch_vccz .LBB0_706
	s_barrier

.LBB0_740:
	s_add_u32 s18, s66, 0x80
	s_addc_u32 s19, s67, 0
	s_add_u32 s66, s66, 0x100
	s_addc_u32 s67, s67, 0
	s_cmp_eq_u32 s85, 12
	s_cselect_b32 s42, s81, s66
	s_cselect_b32 s43, s59, s67
	s_cselect_b32 s45, s31, s84
	s_cselect_b32 s44, s82, s83
	s_add_u32 s38, s42, 0x80
	s_addc_u32 s39, s43, 0
	s_add_u32 s68, s44, 0x80
	s_addc_u32 s69, s45, 0
	s_add_i32 s35, 0, 0x10000
	s_add_i32 s49, 0, 0x14000
	v_add_u32_e32 v96, s35, v151
	v_add_u32_e32 v150, s49, v151
	ds_read_b128 v[138:141], v96
	ds_read_b128 v[142:145], v96 offset:1024
	ds_read_b128 v[146:149], v96 offset:2048
	ds_read_b128 v[156:159], v96 offset:3072
	ds_read_b128 v[160:163], v150
	ds_read_b128 v[164:167], v150 offset:1024
	ds_read_b128 v[168:171], v150 offset:2048
	ds_read_b128 v[172:175], v150 offset:3072
	s_add_u32 s18, s18, 0x40000
	s_addc_u32 s19, s19, 0
	v_lshl_add_u64 v[152:153], s[18:19], 0, v[136:137]
	s_add_i32 m0, s65, 0xc000
	ds_read_b128 v[176:179], v155
	ds_read_b128 v[180:183], v155 offset:1024
	ds_read_b128 v[190:193], v155 offset:2048
	ds_read_b128 v[194:197], v155 offset:3072
	ds_read_b128 v[198:201], v155 offset:4096
	ds_read_b128 v[202:205], v155 offset:5120
	ds_read_b128 v[206:209], v155 offset:6144
	ds_read_b128 v[210:213], v155 offset:7168
	global_load_lds_dwordx4 v[152:153], off
	v_lshl_add_u64 v[152:153], s[18:19], 0, v[132:133]
	s_add_i32 m0, s65, 0xe000
	s_nop 0
	global_load_lds_dwordx4 v[152:153], off
	s_waitcnt vmcnt(8)
	s_waitcnt lgkmcnt(0)
	s_barrier
	s_setprio 1
	s_waitcnt lgkmcnt(0)
	v_mfma_f32_16x16x32_bf16 v[126:129], v[138:141], v[176:179], v[126:129]
	v_mfma_f32_16x16x32_bf16 v[118:121], v[146:149], v[176:179], v[118:121]
	v_mfma_f32_16x16x32_bf16 v[110:113], v[138:141], v[190:193], v[110:113]
	v_mfma_f32_16x16x32_bf16 v[102:105], v[146:149], v[190:193], v[102:105]
	v_mfma_f32_16x16x32_bf16 v[92:95], v[138:141], v[198:201], v[92:95]
	v_mfma_f32_16x16x32_bf16 v[84:87], v[146:149], v[198:201], v[84:87]
	v_mfma_f32_16x16x32_bf16 v[76:79], v[138:141], v[206:209], v[76:79]
	v_mfma_f32_16x16x32_bf16 v[68:71], v[146:149], v[206:209], v[68:71]
	v_mfma_f32_16x16x32_bf16 v[126:129], v[142:145], v[180:183], v[126:129]
	v_mfma_f32_16x16x32_bf16 v[118:121], v[156:159], v[180:183], v[118:121]
	v_mfma_f32_16x16x32_bf16 v[110:113], v[142:145], v[194:197], v[110:113]
	v_mfma_f32_16x16x32_bf16 v[102:105], v[156:159], v[194:197], v[102:105]
	v_mfma_f32_16x16x32_bf16 v[92:95], v[142:145], v[202:205], v[92:95]
	v_mfma_f32_16x16x32_bf16 v[84:87], v[156:159], v[202:205], v[84:87]
	v_mfma_f32_16x16x32_bf16 v[76:79], v[142:145], v[210:213], v[76:79]
	v_mfma_f32_16x16x32_bf16 v[68:71], v[156:159], v[210:213], v[68:71]
	v_mfma_f32_16x16x32_bf16 v[122:125], v[160:163], v[176:179], v[122:125]
	v_mfma_f32_16x16x32_bf16 v[114:117], v[168:171], v[176:179], v[114:117]
	v_mfma_f32_16x16x32_bf16 v[106:109], v[160:163], v[190:193], v[106:109]
	v_mfma_f32_16x16x32_bf16 v[98:101], v[168:171], v[190:193], v[98:101]
	v_mfma_f32_16x16x32_bf16 v[88:91], v[160:163], v[198:201], v[88:91]
	v_mfma_f32_16x16x32_bf16 v[80:83], v[168:171], v[198:201], v[80:83]
	v_mfma_f32_16x16x32_bf16 v[72:75], v[160:163], v[206:209], v[72:75]
	v_mfma_f32_16x16x32_bf16 v[64:67], v[168:171], v[206:209], v[64:67]
	v_mfma_f32_16x16x32_bf16 v[122:125], v[164:167], v[180:183], v[122:125]
	v_mfma_f32_16x16x32_bf16 v[114:117], v[172:175], v[180:183], v[114:117]
	s_barrier
	v_mfma_f32_16x16x32_bf16 v[106:109], v[164:167], v[194:197], v[106:109]
	v_mfma_f32_16x16x32_bf16 v[98:101], v[172:175], v[194:197], v[98:101]
	v_mfma_f32_16x16x32_bf16 v[88:91], v[164:167], v[202:205], v[88:91]
	v_mfma_f32_16x16x32_bf16 v[80:83], v[172:175], v[202:205], v[80:83]
	v_mfma_f32_16x16x32_bf16 v[72:75], v[164:167], v[210:213], v[72:75]
	v_mfma_f32_16x16x32_bf16 v[64:67], v[172:175], v[210:213], v[64:67]
	s_setprio 0
	s_add_i32 s18, s35, s47
	v_lshl_add_u64 v[152:153], s[44:45], 0, v[134:135]
	s_mov_b32 m0, s18
	ds_read_b128 v[176:179], v155 offset:16384
	ds_read_b128 v[180:183], v155 offset:17408
	ds_read_b128 v[190:193], v155 offset:18432
	ds_read_b128 v[194:197], v155 offset:19456
	ds_read_b128 v[198:201], v155 offset:20480
	ds_read_b128 v[202:205], v155 offset:21504
	ds_read_b128 v[206:209], v155 offset:22528
	ds_read_b128 v[210:213], v155 offset:23552
	global_load_lds_dwordx4 v[152:153], off
	s_add_i32 m0, s18, 0x2000
	s_add_u32 s18, s44, 0x40000
	v_lshl_add_u64 v[152:153], s[44:45], 0, v[130:131]
	s_addc_u32 s19, s45, 0
	s_add_i32 s35, s49, s47
	global_load_lds_dwordx4 v[152:153], off
	v_lshl_add_u64 v[152:153], s[18:19], 0, v[134:135]
	s_mov_b32 m0, s35
	s_nop 0
	global_load_lds_dwordx4 v[152:153], off
	v_lshl_add_u64 v[152:153], s[18:19], 0, v[130:131]
	s_add_i32 m0, s35, 0x2000
	s_nop 0
	global_load_lds_dwordx4 v[152:153], off
	v_lshl_add_u64 v[152:153], s[42:43], 0, v[136:137]
	s_mov_b32 m0, s65
	s_nop 0
	global_load_lds_dwordx4 v[152:153], off
	v_lshl_add_u64 v[152:153], s[42:43], 0, v[132:133]
	s_mov_b32 m0, s72
	s_nop 0
	global_load_lds_dwordx4 v[152:153], off
	s_waitcnt vmcnt(8)
	s_waitcnt lgkmcnt(0)
	s_barrier
	s_setprio 1
	s_waitcnt lgkmcnt(0)
	v_mfma_f32_16x16x32_bf16 v[60:63], v[138:141], v[176:179], v[60:63]
	v_mfma_f32_16x16x32_bf16 v[52:55], v[146:149], v[176:179], v[52:55]
	v_mfma_f32_16x16x32_bf16 v[44:47], v[138:141], v[190:193], v[44:47]
	v_mfma_f32_16x16x32_bf16 v[36:39], v[146:149], v[190:193], v[36:39]
	v_mfma_f32_16x16x32_bf16 v[28:31], v[138:141], v[198:201], v[28:31]
	v_mfma_f32_16x16x32_bf16 v[20:23], v[146:149], v[198:201], v[20:23]
	v_mfma_f32_16x16x32_bf16 v[12:15], v[138:141], v[206:209], v[12:15]
	v_mfma_f32_16x16x32_bf16 v[4:7], v[146:149], v[206:209], v[4:7]
	v_mfma_f32_16x16x32_bf16 v[60:63], v[142:145], v[180:183], v[60:63]
	v_mfma_f32_16x16x32_bf16 v[52:55], v[156:159], v[180:183], v[52:55]
	v_mfma_f32_16x16x32_bf16 v[44:47], v[142:145], v[194:197], v[44:47]
	v_mfma_f32_16x16x32_bf16 v[36:39], v[156:159], v[194:197], v[36:39]
	v_mfma_f32_16x16x32_bf16 v[28:31], v[142:145], v[202:205], v[28:31]
	v_mfma_f32_16x16x32_bf16 v[20:23], v[156:159], v[202:205], v[20:23]
	v_mfma_f32_16x16x32_bf16 v[12:15], v[142:145], v[210:213], v[12:15]
	v_mfma_f32_16x16x32_bf16 v[4:7], v[156:159], v[210:213], v[4:7]
	v_mfma_f32_16x16x32_bf16 v[56:59], v[160:163], v[176:179], v[56:59]
	v_mfma_f32_16x16x32_bf16 v[48:51], v[168:171], v[176:179], v[48:51]
	v_mfma_f32_16x16x32_bf16 v[40:43], v[160:163], v[190:193], v[40:43]
	v_mfma_f32_16x16x32_bf16 v[32:35], v[168:171], v[190:193], v[32:35]
	v_mfma_f32_16x16x32_bf16 v[24:27], v[160:163], v[198:201], v[24:27]
	v_mfma_f32_16x16x32_bf16 v[16:19], v[168:171], v[198:201], v[16:19]
	v_mfma_f32_16x16x32_bf16 v[8:11], v[160:163], v[206:209], v[8:11]
	v_mfma_f32_16x16x32_bf16 v[0:3], v[168:171], v[206:209], v[0:3]
	v_mfma_f32_16x16x32_bf16 v[56:59], v[164:167], v[180:183], v[56:59]
	v_mfma_f32_16x16x32_bf16 v[48:51], v[172:175], v[180:183], v[48:51]
	s_barrier
	v_mfma_f32_16x16x32_bf16 v[40:43], v[164:167], v[194:197], v[40:43]
	v_mfma_f32_16x16x32_bf16 v[32:35], v[172:175], v[194:197], v[32:35]
	v_mfma_f32_16x16x32_bf16 v[24:27], v[164:167], v[202:205], v[24:27]
	v_mfma_f32_16x16x32_bf16 v[16:19], v[172:175], v[202:205], v[16:19]
	v_mfma_f32_16x16x32_bf16 v[8:11], v[164:167], v[210:213], v[8:11]
	v_mfma_f32_16x16x32_bf16 v[0:3], v[172:175], v[210:213], v[0:3]
	s_setprio 0
	s_add_i32 s35, 0, 0x18000
	v_add_u32_e32 v96, s35, v151
	s_add_i32 s44, 0, 0x1c000
	ds_read_b128 v[138:141], v96
	ds_read_b128 v[142:145], v96 offset:1024
	ds_read_b128 v[146:149], v96 offset:2048
	ds_read_b128 v[156:159], v96 offset:3072
	v_add_u32_e32 v96, s44, v151
	ds_read_b128 v[160:163], v96
	ds_read_b128 v[164:167], v96 offset:1024
	ds_read_b128 v[168:171], v96 offset:2048
	ds_read_b128 v[172:175], v96 offset:3072
	s_add_u32 s18, s42, 0x40000
	s_addc_u32 s19, s43, 0
	s_mov_b32 m0, s73
	v_lshl_add_u64 v[152:153], s[18:19], 0, v[136:137]
	ds_read_b128 v[176:179], v155 offset:32768
	ds_read_b128 v[180:183], v155 offset:33792
	ds_read_b128 v[190:193], v155 offset:34816
	ds_read_b128 v[194:197], v155 offset:35840
	ds_read_b128 v[198:201], v155 offset:36864
	ds_read_b128 v[202:205], v155 offset:37888
	ds_read_b128 v[206:209], v155 offset:38912
	ds_read_b128 v[210:213], v155 offset:39936
	global_load_lds_dwordx4 v[152:153], off
	v_lshl_add_u64 v[152:153], s[18:19], 0, v[132:133]
	s_mov_b32 m0, s74
	s_nop 0
	global_load_lds_dwordx4 v[152:153], off
	s_waitcnt vmcnt(8)
	s_waitcnt lgkmcnt(0)
	s_barrier
	s_setprio 1
	s_waitcnt lgkmcnt(0)
	v_mfma_f32_16x16x32_bf16 v[126:129], v[138:141], v[176:179], v[126:129]
	v_mfma_f32_16x16x32_bf16 v[118:121], v[146:149], v[176:179], v[118:121]
	v_mfma_f32_16x16x32_bf16 v[110:113], v[138:141], v[190:193], v[110:113]
	v_mfma_f32_16x16x32_bf16 v[102:105], v[146:149], v[190:193], v[102:105]
	v_mfma_f32_16x16x32_bf16 v[92:95], v[138:141], v[198:201], v[92:95]
	v_mfma_f32_16x16x32_bf16 v[84:87], v[146:149], v[198:201], v[84:87]
	v_mfma_f32_16x16x32_bf16 v[76:79], v[138:141], v[206:209], v[76:79]
	v_mfma_f32_16x16x32_bf16 v[68:71], v[146:149], v[206:209], v[68:71]
	v_mfma_f32_16x16x32_bf16 v[126:129], v[142:145], v[180:183], v[126:129]
	v_mfma_f32_16x16x32_bf16 v[118:121], v[156:159], v[180:183], v[118:121]
	v_mfma_f32_16x16x32_bf16 v[110:113], v[142:145], v[194:197], v[110:113]
	v_mfma_f32_16x16x32_bf16 v[102:105], v[156:159], v[194:197], v[102:105]
	v_mfma_f32_16x16x32_bf16 v[92:95], v[142:145], v[202:205], v[92:95]
	v_mfma_f32_16x16x32_bf16 v[84:87], v[156:159], v[202:205], v[84:87]
	v_mfma_f32_16x16x32_bf16 v[76:79], v[142:145], v[210:213], v[76:79]
	v_mfma_f32_16x16x32_bf16 v[68:71], v[156:159], v[210:213], v[68:71]
	v_mfma_f32_16x16x32_bf16 v[122:125], v[160:163], v[176:179], v[122:125]
	v_mfma_f32_16x16x32_bf16 v[114:117], v[168:171], v[176:179], v[114:117]
	v_mfma_f32_16x16x32_bf16 v[106:109], v[160:163], v[190:193], v[106:109]
	v_mfma_f32_16x16x32_bf16 v[98:101], v[168:171], v[190:193], v[98:101]
	v_mfma_f32_16x16x32_bf16 v[88:91], v[160:163], v[198:201], v[88:91]
	v_mfma_f32_16x16x32_bf16 v[80:83], v[168:171], v[198:201], v[80:83]
	v_mfma_f32_16x16x32_bf16 v[72:75], v[160:163], v[206:209], v[72:75]
	v_mfma_f32_16x16x32_bf16 v[64:67], v[168:171], v[206:209], v[64:67]
	v_mfma_f32_16x16x32_bf16 v[122:125], v[164:167], v[180:183], v[122:125]
	v_mfma_f32_16x16x32_bf16 v[114:117], v[172:175], v[180:183], v[114:117]
	s_barrier
	v_mfma_f32_16x16x32_bf16 v[106:109], v[164:167], v[194:197], v[106:109]
	v_mfma_f32_16x16x32_bf16 v[98:101], v[172:175], v[194:197], v[98:101]
	v_mfma_f32_16x16x32_bf16 v[88:91], v[164:167], v[202:205], v[88:91]
	v_mfma_f32_16x16x32_bf16 v[80:83], v[172:175], v[202:205], v[80:83]
	v_mfma_f32_16x16x32_bf16 v[72:75], v[164:167], v[210:213], v[72:75]
	v_mfma_f32_16x16x32_bf16 v[64:67], v[172:175], v[210:213], v[64:67]
	s_setprio 0
	s_add_i32 s18, s35, s47
	v_lshl_add_u64 v[152:153], s[68:69], 0, v[134:135]
	s_mov_b32 m0, s18
	ds_read_b128 v[176:179], v155 offset:49152
	ds_read_b128 v[180:183], v155 offset:50176
	ds_read_b128 v[190:193], v155 offset:51200
	ds_read_b128 v[194:197], v155 offset:52224
	ds_read_b128 v[198:201], v155 offset:53248
	ds_read_b128 v[202:205], v155 offset:54272
	ds_read_b128 v[206:209], v155 offset:55296
	ds_read_b128 v[210:213], v155 offset:56320
	global_load_lds_dwordx4 v[152:153], off
	s_add_i32 m0, s18, 0x2000
	s_add_u32 s18, s68, 0x40000
	v_lshl_add_u64 v[152:153], s[68:69], 0, v[130:131]
	s_addc_u32 s19, s69, 0
	s_add_i32 s35, s44, s47
	global_load_lds_dwordx4 v[152:153], off
	v_lshl_add_u64 v[152:153], s[18:19], 0, v[134:135]
	s_mov_b32 m0, s35
	s_nop 0
	global_load_lds_dwordx4 v[152:153], off
	v_lshl_add_u64 v[152:153], s[18:19], 0, v[130:131]
	s_add_i32 m0, s35, 0x2000
	s_nop 0
	global_load_lds_dwordx4 v[152:153], off
	v_lshl_add_u64 v[152:153], s[38:39], 0, v[136:137]
	s_mov_b32 m0, s77
	s_nop 0
	global_load_lds_dwordx4 v[152:153], off
	v_lshl_add_u64 v[152:153], s[38:39], 0, v[132:133]
	s_mov_b32 m0, s78
	s_nop 0
	global_load_lds_dwordx4 v[152:153], off
	s_waitcnt vmcnt(8)
	s_cmp_lg_u32 s85, 12
	s_cbranch_scc1 .Lswi_ssq_skip
	global_load_dwordx4 v[220:223], v[252:253], off
	global_load_dwordx4 v[224:227], v[252:253], off offset:1024
	global_load_dwordx4 v[228:231], v[252:253], off offset:2048
	global_load_dwordx4 v[232:235], v[252:253], off offset:3072
	global_load_dwordx4 v[236:239], v[184:185], off
	global_load_dwordx4 v[240:243], v[184:185], off offset:1024
	global_load_dwordx4 v[244:247], v[184:185], off offset:2048
	global_load_dwordx4 v[248:251], v[184:185], off offset:3072
.Lswi_ssq_skip:
	s_waitcnt lgkmcnt(0)
	s_barrier
	s_setprio 1
	s_waitcnt lgkmcnt(0)
	v_mfma_f32_16x16x32_bf16 v[60:63], v[138:141], v[176:179], v[60:63]
	v_mfma_f32_16x16x32_bf16 v[52:55], v[146:149], v[176:179], v[52:55]
	v_mfma_f32_16x16x32_bf16 v[44:47], v[138:141], v[190:193], v[44:47]
	v_mfma_f32_16x16x32_bf16 v[36:39], v[146:149], v[190:193], v[36:39]
	v_mfma_f32_16x16x32_bf16 v[28:31], v[138:141], v[198:201], v[28:31]
	v_mfma_f32_16x16x32_bf16 v[20:23], v[146:149], v[198:201], v[20:23]
	v_mfma_f32_16x16x32_bf16 v[12:15], v[138:141], v[206:209], v[12:15]
	v_mfma_f32_16x16x32_bf16 v[4:7], v[146:149], v[206:209], v[4:7]
	v_mfma_f32_16x16x32_bf16 v[60:63], v[142:145], v[180:183], v[60:63]
	v_mfma_f32_16x16x32_bf16 v[52:55], v[156:159], v[180:183], v[52:55]
	v_mfma_f32_16x16x32_bf16 v[44:47], v[142:145], v[194:197], v[44:47]
	v_mfma_f32_16x16x32_bf16 v[36:39], v[156:159], v[194:197], v[36:39]
	v_mfma_f32_16x16x32_bf16 v[28:31], v[142:145], v[202:205], v[28:31]
	v_mfma_f32_16x16x32_bf16 v[20:23], v[156:159], v[202:205], v[20:23]
	v_mfma_f32_16x16x32_bf16 v[12:15], v[142:145], v[210:213], v[12:15]
	v_mfma_f32_16x16x32_bf16 v[4:7], v[156:159], v[210:213], v[4:7]
	v_mfma_f32_16x16x32_bf16 v[56:59], v[160:163], v[176:179], v[56:59]
	v_mfma_f32_16x16x32_bf16 v[48:51], v[168:171], v[176:179], v[48:51]
	v_mfma_f32_16x16x32_bf16 v[40:43], v[160:163], v[190:193], v[40:43]
	v_mfma_f32_16x16x32_bf16 v[32:35], v[168:171], v[190:193], v[32:35]
	v_mfma_f32_16x16x32_bf16 v[24:27], v[160:163], v[198:201], v[24:27]
	v_mfma_f32_16x16x32_bf16 v[16:19], v[168:171], v[198:201], v[16:19]
	v_mfma_f32_16x16x32_bf16 v[8:11], v[160:163], v[206:209], v[8:11]
	v_mfma_f32_16x16x32_bf16 v[0:3], v[168:171], v[206:209], v[0:3]
	v_mfma_f32_16x16x32_bf16 v[56:59], v[164:167], v[180:183], v[56:59]
	v_mfma_f32_16x16x32_bf16 v[48:51], v[172:175], v[180:183], v[48:51]
	s_barrier
	v_mfma_f32_16x16x32_bf16 v[40:43], v[164:167], v[194:197], v[40:43]
	v_mfma_f32_16x16x32_bf16 v[32:35], v[172:175], v[194:197], v[32:35]
	v_mfma_f32_16x16x32_bf16 v[24:27], v[164:167], v[202:205], v[24:27]
	v_mfma_f32_16x16x32_bf16 v[16:19], v[172:175], v[202:205], v[16:19]
	v_mfma_f32_16x16x32_bf16 v[8:11], v[164:167], v[210:213], v[8:11]
	v_mfma_f32_16x16x32_bf16 v[0:3], v[172:175], v[210:213], v[0:3]
	s_setprio 0
	s_add_i32 s85, s85, 2
	s_add_u32 s83, s83, 0x100
	s_addc_u32 s84, s84, 0
	s_cmp_gt_u32 s85, 13
	s_cbranch_scc0 .LBB0_740
	s_and_b64 vcc, exec, s[28:29]
	s_cbranch_vccz .LBB0_743
	s_barrier
